# epilogue de-serialisation: row loads of the WO/FD residual, PR0 and PR1 epilogues requested together (counted waits) instead of one vmcnt(0) round trip per row; on top of K-loop combo
# baseline (speedup 1.0000x reference)
; #define GAS __attribute__((address_space(1)))
; __device__ __forceinline__ u32x4 pack8(f32x4 v0, f32x4 v1) { u32x4 w; w.x = cvt_pk_bf16(v0[0], v0[1]); w.y = cvt_pk_bf16(v0[2], v0[3]); w.z = cvt_pk_bf16(v1[0], v1[1]); w.w = cvt_pk_bf16(v1[2], v1[3]); return w; }
; __device__ __forceinline__ void unpack8(u32x4 w, f32x4& v0, f32x4& v1) { v0 = (f32x4){bflo(w.x), bfhi(w.x), bflo(w.y), bfhi(w.y)}; v1 = (f32x4){bflo(w.z), bfhi(w.z), bflo(w.w), bfhi(w.w)}; }
; #define GAS __attribute__((address_space(1)))
;     __device__ __forceinline__ void operator()(const f32x4 (&acc)[2][2][4][2], const Unit& u, int wr, int wc, int fr, int fq) const {
;         const int row0 = u.pm * BM + wr * 64 + fr, col0 = u.pn * BM + wc * 32 + 8 * fq;
;         const bool samp = u.pm >= 32;
;         GAS unsigned* flag = (GAS unsigned*)(flags + 64 * (u.pn * 4 + (u.pm & 3)));
;         if (MODE == 1 && samp) {
;             unsigned spins = 0u;
;             while (__hip_atomic_load(flag, __ATOMIC_RELAXED, __HIP_MEMORY_SCOPE_AGENT) < 8u) { __builtin_amdgcn_s_sleep(2); if (++spins > (1u << 18)) break; }
;             __builtin_amdgcn_fence(__ATOMIC_ACQUIRE, "agent"); asm volatile("s_waitcnt vmcnt(0)" ::: "memory");
;         }
; #pragma unroll
;         for (int ai = 0; ai < 2; ++ai)
; #pragma unroll
;             for (int m = 0; m < 4; ++m) { const size_t r = (size_t)(row0 + ai * HALF + m * 16); const size_t off = r * 2048 + col0; const bf16_t* gp = P + r * NPJ + 2560 + MODE * 2048 + col0;
; #pragma unroll
;                 for (int bj = 0; bj < 2; ++bj) { f32x4 g0, g1; unpack8(*(const GAS u32x4*)(gp + bj * HALF), g0, g1);
;                     f32x4 v0 = g0 * acc[ai][bj][m][0], v1 = g1 * acc[ai][bj][m][1];
;                     if (MODE == 1) { f32x4 t0, t1; unpack8(*(const GAS u32x4*)(T1 + off + bj * HALF), t0, t1); v0 += t0; v1 += t1; }
;                     const u32x4 w = pack8(v0, v1);
;                     if (MODE == 0 && samp) asm volatile("global_store_dwordx4 %0, %1, off sc1\n\ts_nop 1" :: "v"(O + off + bj * HALF), "v"(w) : "memory");
;                     else *(GAS u32x4*)(O + off + bj * HALF) = w; } }
.LBB0_1070:
	s_lshl_b32 s15, s91, 8
	v_or_b32_e32 v144, s15, v150
	v_lshl_add_u32 v146, s90, 8, v1
	v_ashrrev_i32_e32 v145, 31, v144
	v_mov_b64_e32 v[148:149], s[8:9]
	s_movk_i32 s95, 0x3400
	v_mad_i64_i32 v[148:149], s[0:1], v146, s95, v[148:149]
	v_lshlrev_b64 v[144:145], 1, v[144:145]
	v_lshl_add_u64 v[148:149], v[148:149], 0, v[144:145]
	s_movk_i32 s0, 0x1000
	v_add_co_u32_e32 v152, vcc, s0, v148
	s_cmp_gt_i32 s90, 31
	s_nop 0
	v_addc_co_u32_e32 v153, vcc, 0, v149, vcc
	global_load_dwordx4 v[222:225], v[152:153], off offset:1024
	global_load_dwordx4 v[226:229], v[152:153], off offset:1280
	v_add_co_u32_e32 v188, vcc, 0x34000, v152
	s_nop 1
	v_addc_co_u32_e32 v189, vcc, 0, v153, vcc
	global_load_dwordx4 v[230:233], v[188:189], off offset:1024
	global_load_dwordx4 v[234:237], v[188:189], off offset:1280
	v_add_co_u32_e32 v188, vcc, 0x68000, v152
	s_nop 1
	v_addc_co_u32_e32 v189, vcc, 0, v153, vcc
	global_load_dwordx4 v[238:241], v[188:189], off offset:1024
	global_load_dwordx4 v[242:245], v[188:189], off offset:1280
	v_add_co_u32_e32 v188, vcc, 0x9c000, v152
	s_nop 1
	v_addc_co_u32_e32 v189, vcc, 0, v153, vcc
	global_load_dwordx4 v[180:183], v[188:189], off offset:1024
	global_load_dwordx4 v[184:187], v[188:189], off offset:1280
	v_ashrrev_i32_e32 v147, 31, v146
	s_cselect_b64 s[52:53], -1, 0
	s_cmp_lt_i32 s90, 32
	s_cselect_b64 s[54:55], -1, 0
	s_mov_b64 s[42:43], -1
	s_and_b64 vcc, exec, s[54:55]
	v_readlane_b32 s92, v254, 49
	s_mov_b64 s[2:3], 0x1400
	s_mov_b32 s93, 0x18000
	s_waitcnt vmcnt(7)
	s_nop 1
	v_mov_b32_e32 v152, v222
	v_mov_b32_e32 v153, v223
	v_mov_b32_e32 v154, v224
	v_mov_b32_e32 v155, v225
	v_lshlrev_b32_e32 v156, 16, v152
	v_and_b32_e32 v157, 0xffff0000, v152
	v_lshlrev_b32_e32 v152, 16, v153
	v_and_b32_e32 v153, 0xffff0000, v153
	v_lshlrev_b32_e32 v158, 16, v154
	v_and_b32_e32 v159, 0xffff0000, v154
	v_lshlrev_b32_e32 v154, 16, v155
	v_and_b32_e32 v155, 0xffff0000, v155
	v_pk_mul_f32 v[128:129], v[128:129], v[156:157]
	v_pk_mul_f32 v[130:131], v[130:131], v[152:153]
	v_pk_mul_f32 v[152:153], v[126:127], v[154:155]
	v_pk_mul_f32 v[126:127], v[124:125], v[158:159]
	v_cvt_pk_bf16_f32 v124, v128, v129
	v_lshlrev_b64 v[128:129], 12, v[146:147]
	v_lshl_add_u64 v[128:129], s[10:11], 0, v[128:129]
	v_cvt_pk_bf16_f32 v125, v130, v131
	v_cvt_pk_bf16_f32 v126, v126, v127
	v_cvt_pk_bf16_f32 v127, v152, v153
	v_lshl_add_u64 v[128:129], v[128:129], 0, v[144:145]
	s_cbranch_vccz .LBB0_1072
	global_store_dwordx4 v[128:129], v[124:127], off
	s_mov_b64 s[42:43], 0

; #define GAS __attribute__((address_space(1)))
; __device__ __forceinline__ u32x4 pack8(f32x4 v0, f32x4 v1) { u32x4 w; w.x = cvt_pk_bf16(v0[0], v0[1]); w.y = cvt_pk_bf16(v0[2], v0[3]); w.z = cvt_pk_bf16(v1[0], v1[1]); w.w = cvt_pk_bf16(v1[2], v1[3]); return w; }
; __device__ __forceinline__ void unpack8(u32x4 w, f32x4& v0, f32x4& v1) { v0 = (f32x4){bflo(w.x), bfhi(w.x), bflo(w.y), bfhi(w.y)}; v1 = (f32x4){bflo(w.z), bfhi(w.z), bflo(w.w), bfhi(w.w)}; }
; #define GAS __attribute__((address_space(1)))
;     __device__ __forceinline__ void operator()(const f32x4 (&acc)[2][2][4][2], const Unit& u, int wr, int wc, int fr, int fq) const {
;     ...
;             for (int m = 0; m < 4; ++m) { const size_t r = (size_t)(row0 + ai * HALF + m * 16); const size_t off = r * 2048 + col0; const bf16_t* gp = P + r * NPJ + 2560 + MODE * 2048 + col0;
; #pragma unroll
;                 for (int bj = 0; bj < 2; ++bj) { f32x4 g0, g1; unpack8(*(const GAS u32x4*)(gp + bj * HALF), g0, g1);
;                     f32x4 v0 = g0 * acc[ai][bj][m][0], v1 = g1 * acc[ai][bj][m][1];
;                     if (MODE == 1) { f32x4 t0, t1; unpack8(*(const GAS u32x4*)(T1 + off + bj * HALF), t0, t1); v0 += t0; v1 += t1; }
;                     const u32x4 w = pack8(v0, v1);
;                     if (MODE == 0 && samp) asm volatile("global_store_dwordx4 %0, %1, off sc1\n\ts_nop 1" :: "v"(O + off + bj * HALF), "v"(w) : "memory");
;                     else *(GAS u32x4*)(O + off + bj * HALF) = w; } }
.LBB0_1074:
	v_lshl_add_u64 v[124:125], v[148:149], 0, s[2:3]
	v_cndmask_b32_e64 v126, 0, 1, s[54:55]
	v_lshl_add_u64 v[124:125], v[128:129], 0, s[86:87]
	v_cmp_ne_u32_e64 s[42:43], 1, v126
	v_readlane_b32 s60, v251, 14
	s_andn2_b64 vcc, exec, s[54:55]
	s_mov_b64 s[54:55], -1
	v_readlane_b32 s61, v251, 15
	v_readlane_b32 s62, v251, 16
	v_readlane_b32 s63, v251, 17
	v_readlane_b32 s64, v251, 18
	v_readlane_b32 s65, v251, 19
	v_readlane_b32 s66, v251, 20
	v_readlane_b32 s67, v251, 21
	s_mov_b32 s94, 0x8000
	s_waitcnt vmcnt(7)
	s_nop 1
	v_mov_b32_e32 v152, v226
	v_mov_b32_e32 v153, v227
	v_mov_b32_e32 v154, v228
	v_mov_b32_e32 v155, v229
	v_lshlrev_b32_e32 v126, 16, v152
	v_and_b32_e32 v127, 0xffff0000, v152
	v_lshlrev_b32_e32 v128, 16, v153
	v_and_b32_e32 v129, 0xffff0000, v153
	v_lshlrev_b32_e32 v130, 16, v154
	v_and_b32_e32 v131, 0xffff0000, v154
	v_lshlrev_b32_e32 v148, 16, v155
	v_and_b32_e32 v149, 0xffff0000, v155
	v_pk_mul_f32 v[122:123], v[122:123], v[128:129]
	v_pk_mul_f32 v[120:121], v[120:121], v[126:127]
	v_pk_mul_f32 v[126:127], v[118:119], v[148:149]
	v_pk_mul_f32 v[118:119], v[116:117], v[130:131]
	v_cvt_pk_bf16_f32 v116, v120, v121
	v_cvt_pk_bf16_f32 v117, v122, v123
	v_cvt_pk_bf16_f32 v118, v118, v119
	v_cvt_pk_bf16_f32 v119, v126, v127
	s_cbranch_vccnz .LBB0_1076
	s_mov_b64 s[54:55], 0
	global_store_dwordx4 v[124:125], v[116:119], off

; #define GAS __attribute__((address_space(1)))
; __device__ __forceinline__ u32x4 pack8(f32x4 v0, f32x4 v1) { u32x4 w; w.x = cvt_pk_bf16(v0[0], v0[1]); w.y = cvt_pk_bf16(v0[2], v0[3]); w.z = cvt_pk_bf16(v1[0], v1[1]); w.w = cvt_pk_bf16(v1[2], v1[3]); return w; }
; __device__ __forceinline__ void unpack8(u32x4 w, f32x4& v0, f32x4& v1) { v0 = (f32x4){bflo(w.x), bfhi(w.x), bflo(w.y), bfhi(w.y)}; v1 = (f32x4){bflo(w.z), bfhi(w.z), bflo(w.w), bfhi(w.w)}; }
; #define GAS __attribute__((address_space(1)))
;     __device__ __forceinline__ void operator()(const f32x4 (&acc)[2][2][4][2], const Unit& u, int wr, int wc, int fr, int fq) const {
;     ...
;             for (int m = 0; m < 4; ++m) { const size_t r = (size_t)(row0 + ai * HALF + m * 16); const size_t off = r * 2048 + col0; const bf16_t* gp = P + r * NPJ + 2560 + MODE * 2048 + col0;
; #pragma unroll
;                 for (int bj = 0; bj < 2; ++bj) { f32x4 g0, g1; unpack8(*(const GAS u32x4*)(gp + bj * HALF), g0, g1);
;                     f32x4 v0 = g0 * acc[ai][bj][m][0], v1 = g1 * acc[ai][bj][m][1];
;                     if (MODE == 1) { f32x4 t0, t1; unpack8(*(const GAS u32x4*)(T1 + off + bj * HALF), t0, t1); v0 += t0; v1 += t1; }
;                     const u32x4 w = pack8(v0, v1);
;                     if (MODE == 0 && samp) asm volatile("global_store_dwordx4 %0, %1, off sc1\n\ts_nop 1" :: "v"(O + off + bj * HALF), "v"(w) : "memory");
;                     else *(GAS u32x4*)(O + off + bj * HALF) = w; } }
.LBB0_1078:
	v_or_b32_e32 v118, 16, v146
	v_mov_b64_e32 v[116:117], s[8:9]
	v_mad_i64_i32 v[116:117], s[0:1], v118, s95, v[116:117]
	v_lshl_add_u64 v[116:117], v[116:117], 0, v[144:145]
	v_add_co_u32_e32 v120, vcc, 0x1000, v116
	v_ashrrev_i32_e32 v119, 31, v118
	s_nop 0
	v_addc_co_u32_e32 v121, vcc, 0, v117, vcc
	v_lshlrev_b64 v[118:119], 12, v[118:119]
	v_lshl_add_u64 v[118:119], s[10:11], 0, v[118:119]
	v_lshl_add_u64 v[118:119], v[118:119], 0, v[144:145]
	s_and_b64 vcc, exec, s[42:43]
	s_mov_b64 s[54:55], -1
	s_waitcnt vmcnt(7)
	s_nop 1
	v_mov_b32_e32 v120, v230
	v_mov_b32_e32 v121, v231
	v_mov_b32_e32 v122, v232
	v_mov_b32_e32 v123, v233
	v_lshlrev_b32_e32 v124, 16, v120
	v_and_b32_e32 v125, 0xffff0000, v120
	v_lshlrev_b32_e32 v120, 16, v121
	v_and_b32_e32 v121, 0xffff0000, v121
	v_lshlrev_b32_e32 v126, 16, v122
	v_and_b32_e32 v127, 0xffff0000, v122
	v_lshlrev_b32_e32 v122, 16, v123
	v_and_b32_e32 v123, 0xffff0000, v123
	v_pk_mul_f32 v[114:115], v[114:115], v[120:121]
	v_pk_mul_f32 v[112:113], v[112:113], v[124:125]
	v_pk_mul_f32 v[120:121], v[110:111], v[122:123]
	v_pk_mul_f32 v[110:111], v[108:109], v[126:127]
	v_cvt_pk_bf16_f32 v108, v112, v113
	v_cvt_pk_bf16_f32 v109, v114, v115
	v_cvt_pk_bf16_f32 v110, v110, v111
	v_cvt_pk_bf16_f32 v111, v120, v121
	s_cbranch_vccnz .LBB0_1080
	s_mov_b64 s[54:55], 0
	global_store_dwordx4 v[118:119], v[108:111], off

; #define GAS __attribute__((address_space(1)))
; __device__ __forceinline__ u32x4 pack8(f32x4 v0, f32x4 v1) { u32x4 w; w.x = cvt_pk_bf16(v0[0], v0[1]); w.y = cvt_pk_bf16(v0[2], v0[3]); w.z = cvt_pk_bf16(v1[0], v1[1]); w.w = cvt_pk_bf16(v1[2], v1[3]); return w; }
; __device__ __forceinline__ void unpack8(u32x4 w, f32x4& v0, f32x4& v1) { v0 = (f32x4){bflo(w.x), bfhi(w.x), bflo(w.y), bfhi(w.y)}; v1 = (f32x4){bflo(w.z), bfhi(w.z), bflo(w.w), bfhi(w.w)}; }
; #define GAS __attribute__((address_space(1)))
;     __device__ __forceinline__ void operator()(const f32x4 (&acc)[2][2][4][2], const Unit& u, int wr, int wc, int fr, int fq) const {
;     ...
;             for (int m = 0; m < 4; ++m) { const size_t r = (size_t)(row0 + ai * HALF + m * 16); const size_t off = r * 2048 + col0; const bf16_t* gp = P + r * NPJ + 2560 + MODE * 2048 + col0;
; #pragma unroll
;                 for (int bj = 0; bj < 2; ++bj) { f32x4 g0, g1; unpack8(*(const GAS u32x4*)(gp + bj * HALF), g0, g1);
;                     f32x4 v0 = g0 * acc[ai][bj][m][0], v1 = g1 * acc[ai][bj][m][1];
;                     if (MODE == 1) { f32x4 t0, t1; unpack8(*(const GAS u32x4*)(T1 + off + bj * HALF), t0, t1); v0 += t0; v1 += t1; }
;                     const u32x4 w = pack8(v0, v1);
;                     if (MODE == 0 && samp) asm volatile("global_store_dwordx4 %0, %1, off sc1\n\ts_nop 1" :: "v"(O + off + bj * HALF), "v"(w) : "memory");
;                     else *(GAS u32x4*)(O + off + bj * HALF) = w; } }
.LBB0_1082:
	v_lshl_add_u64 v[108:109], v[116:117], 0, s[2:3]
	v_lshl_add_u64 v[108:109], v[118:119], 0, s[86:87]
	s_and_b64 vcc, exec, s[42:43]
	s_mov_b64 s[54:55], -1
	s_waitcnt vmcnt(7)
	s_nop 1
	v_mov_b32_e32 v110, v234
	v_mov_b32_e32 v111, v235
	v_mov_b32_e32 v112, v236
	v_mov_b32_e32 v113, v237
	v_lshlrev_b32_e32 v114, 16, v110
	v_and_b32_e32 v115, 0xffff0000, v110
	v_lshlrev_b32_e32 v110, 16, v111
	v_and_b32_e32 v111, 0xffff0000, v111
	v_lshlrev_b32_e32 v116, 16, v112
	v_and_b32_e32 v117, 0xffff0000, v112
	v_lshlrev_b32_e32 v112, 16, v113
	v_and_b32_e32 v113, 0xffff0000, v113
	v_pk_mul_f32 v[106:107], v[106:107], v[110:111]
	v_pk_mul_f32 v[104:105], v[104:105], v[114:115]
	v_pk_mul_f32 v[110:111], v[102:103], v[112:113]
	v_pk_mul_f32 v[102:103], v[100:101], v[116:117]
	v_cvt_pk_bf16_f32 v100, v104, v105
	v_cvt_pk_bf16_f32 v101, v106, v107
	v_cvt_pk_bf16_f32 v102, v102, v103
	v_cvt_pk_bf16_f32 v103, v110, v111
	s_cbranch_vccnz .LBB0_1084
	s_mov_b64 s[54:55], 0
	global_store_dwordx4 v[108:109], v[100:103], off

; #define GAS __attribute__((address_space(1)))
; __device__ __forceinline__ u32x4 pack8(f32x4 v0, f32x4 v1) { u32x4 w; w.x = cvt_pk_bf16(v0[0], v0[1]); w.y = cvt_pk_bf16(v0[2], v0[3]); w.z = cvt_pk_bf16(v1[0], v1[1]); w.w = cvt_pk_bf16(v1[2], v1[3]); return w; }
; __device__ __forceinline__ void unpack8(u32x4 w, f32x4& v0, f32x4& v1) { v0 = (f32x4){bflo(w.x), bfhi(w.x), bflo(w.y), bfhi(w.y)}; v1 = (f32x4){bflo(w.z), bfhi(w.z), bflo(w.w), bfhi(w.w)}; }
; #define GAS __attribute__((address_space(1)))
;     __device__ __forceinline__ void operator()(const f32x4 (&acc)[2][2][4][2], const Unit& u, int wr, int wc, int fr, int fq) const {
;     ...
;             for (int m = 0; m < 4; ++m) { const size_t r = (size_t)(row0 + ai * HALF + m * 16); const size_t off = r * 2048 + col0; const bf16_t* gp = P + r * NPJ + 2560 + MODE * 2048 + col0;
; #pragma unroll
;                 for (int bj = 0; bj < 2; ++bj) { f32x4 g0, g1; unpack8(*(const GAS u32x4*)(gp + bj * HALF), g0, g1);
;                     f32x4 v0 = g0 * acc[ai][bj][m][0], v1 = g1 * acc[ai][bj][m][1];
;                     if (MODE == 1) { f32x4 t0, t1; unpack8(*(const GAS u32x4*)(T1 + off + bj * HALF), t0, t1); v0 += t0; v1 += t1; }
;                     const u32x4 w = pack8(v0, v1);
;                     if (MODE == 0 && samp) asm volatile("global_store_dwordx4 %0, %1, off sc1\n\ts_nop 1" :: "v"(O + off + bj * HALF), "v"(w) : "memory");
;                     else *(GAS u32x4*)(O + off + bj * HALF) = w; } }
.LBB0_1086:
	v_or_b32_e32 v102, 32, v146
	v_mov_b64_e32 v[100:101], s[8:9]
	v_mad_i64_i32 v[100:101], s[0:1], v102, s95, v[100:101]
	v_lshl_add_u64 v[100:101], v[100:101], 0, v[144:145]
	v_add_co_u32_e32 v104, vcc, 0x1000, v100
	v_ashrrev_i32_e32 v103, 31, v102
	s_nop 0
	v_addc_co_u32_e32 v105, vcc, 0, v101, vcc
	v_lshlrev_b64 v[102:103], 12, v[102:103]
	v_lshl_add_u64 v[102:103], s[10:11], 0, v[102:103]
	v_lshl_add_u64 v[102:103], v[102:103], 0, v[144:145]
	s_and_b64 vcc, exec, s[42:43]
	s_mov_b64 s[54:55], -1
	s_waitcnt vmcnt(7)
	s_nop 1
	v_mov_b32_e32 v104, v238
	v_mov_b32_e32 v105, v239
	v_mov_b32_e32 v106, v240
	v_mov_b32_e32 v107, v241
	v_lshlrev_b32_e32 v108, 16, v104
	v_and_b32_e32 v109, 0xffff0000, v104
	v_lshlrev_b32_e32 v104, 16, v105
	v_and_b32_e32 v105, 0xffff0000, v105
	v_lshlrev_b32_e32 v110, 16, v106
	v_and_b32_e32 v111, 0xffff0000, v106
	v_lshlrev_b32_e32 v106, 16, v107
	v_and_b32_e32 v107, 0xffff0000, v107
	v_pk_mul_f32 v[96:97], v[96:97], v[104:105]
	v_pk_mul_f32 v[94:95], v[94:95], v[108:109]
	v_pk_mul_f32 v[104:105], v[92:93], v[106:107]
	v_pk_mul_f32 v[92:93], v[90:91], v[110:111]
	v_cvt_pk_bf16_f32 v90, v94, v95
	v_cvt_pk_bf16_f32 v91, v96, v97
	v_cvt_pk_bf16_f32 v92, v92, v93
	v_cvt_pk_bf16_f32 v93, v104, v105
	s_cbranch_vccnz .LBB0_1088
	s_mov_b64 s[54:55], 0
	global_store_dwordx4 v[102:103], v[90:93], off

; #define GAS __attribute__((address_space(1)))
; __device__ __forceinline__ u32x4 pack8(f32x4 v0, f32x4 v1) { u32x4 w; w.x = cvt_pk_bf16(v0[0], v0[1]); w.y = cvt_pk_bf16(v0[2], v0[3]); w.z = cvt_pk_bf16(v1[0], v1[1]); w.w = cvt_pk_bf16(v1[2], v1[3]); return w; }
; __device__ __forceinline__ void unpack8(u32x4 w, f32x4& v0, f32x4& v1) { v0 = (f32x4){bflo(w.x), bfhi(w.x), bflo(w.y), bfhi(w.y)}; v1 = (f32x4){bflo(w.z), bfhi(w.z), bflo(w.w), bfhi(w.w)}; }
; #define GAS __attribute__((address_space(1)))
;     __device__ __forceinline__ void operator()(const f32x4 (&acc)[2][2][4][2], const Unit& u, int wr, int wc, int fr, int fq) const {
;     ...
;             for (int m = 0; m < 4; ++m) { const size_t r = (size_t)(row0 + ai * HALF + m * 16); const size_t off = r * 2048 + col0; const bf16_t* gp = P + r * NPJ + 2560 + MODE * 2048 + col0;
; #pragma unroll
;                 for (int bj = 0; bj < 2; ++bj) { f32x4 g0, g1; unpack8(*(const GAS u32x4*)(gp + bj * HALF), g0, g1);
;                     f32x4 v0 = g0 * acc[ai][bj][m][0], v1 = g1 * acc[ai][bj][m][1];
;                     if (MODE == 1) { f32x4 t0, t1; unpack8(*(const GAS u32x4*)(T1 + off + bj * HALF), t0, t1); v0 += t0; v1 += t1; }
;                     const u32x4 w = pack8(v0, v1);
;                     if (MODE == 0 && samp) asm volatile("global_store_dwordx4 %0, %1, off sc1\n\ts_nop 1" :: "v"(O + off + bj * HALF), "v"(w) : "memory");
;                     else *(GAS u32x4*)(O + off + bj * HALF) = w; } }
.LBB0_1090:
	v_lshl_add_u64 v[90:91], v[100:101], 0, s[2:3]
	v_lshl_add_u64 v[90:91], v[102:103], 0, s[86:87]
	s_and_b64 vcc, exec, s[42:43]
	s_mov_b64 s[54:55], -1
	s_waitcnt vmcnt(7)
	s_nop 1
	v_mov_b32_e32 v92, v242
	v_mov_b32_e32 v93, v243
	v_mov_b32_e32 v94, v244
	v_mov_b32_e32 v95, v245
	v_lshlrev_b32_e32 v96, 16, v92
	v_and_b32_e32 v97, 0xffff0000, v92
	v_lshlrev_b32_e32 v92, 16, v93
	v_and_b32_e32 v93, 0xffff0000, v93
	v_lshlrev_b32_e32 v100, 16, v94
	v_and_b32_e32 v101, 0xffff0000, v94
	v_lshlrev_b32_e32 v94, 16, v95
	v_and_b32_e32 v95, 0xffff0000, v95
	v_pk_mul_f32 v[88:89], v[88:89], v[92:93]
	v_pk_mul_f32 v[86:87], v[86:87], v[96:97]
	v_pk_mul_f32 v[92:93], v[84:85], v[94:95]
	v_pk_mul_f32 v[84:85], v[82:83], v[100:101]
	v_cvt_pk_bf16_f32 v82, v86, v87
	v_cvt_pk_bf16_f32 v83, v88, v89
	v_cvt_pk_bf16_f32 v84, v84, v85
	v_cvt_pk_bf16_f32 v85, v92, v93
	s_cbranch_vccnz .LBB0_1092
	s_mov_b64 s[54:55], 0
	global_store_dwordx4 v[90:91], v[82:85], off

; #define GAS __attribute__((address_space(1)))
; __device__ __forceinline__ u32x4 pack8(f32x4 v0, f32x4 v1) { u32x4 w; w.x = cvt_pk_bf16(v0[0], v0[1]); w.y = cvt_pk_bf16(v0[2], v0[3]); w.z = cvt_pk_bf16(v1[0], v1[1]); w.w = cvt_pk_bf16(v1[2], v1[3]); return w; }
; __device__ __forceinline__ void unpack8(u32x4 w, f32x4& v0, f32x4& v1) { v0 = (f32x4){bflo(w.x), bfhi(w.x), bflo(w.y), bfhi(w.y)}; v1 = (f32x4){bflo(w.z), bfhi(w.z), bflo(w.w), bfhi(w.w)}; }
; #define GAS __attribute__((address_space(1)))
;     __device__ __forceinline__ void operator()(const f32x4 (&acc)[2][2][4][2], const Unit& u, int wr, int wc, int fr, int fq) const {
;     ...
;             for (int m = 0; m < 4; ++m) { const size_t r = (size_t)(row0 + ai * HALF + m * 16); const size_t off = r * 2048 + col0; const bf16_t* gp = P + r * NPJ + 2560 + MODE * 2048 + col0;
; #pragma unroll
;                 for (int bj = 0; bj < 2; ++bj) { f32x4 g0, g1; unpack8(*(const GAS u32x4*)(gp + bj * HALF), g0, g1);
;                     f32x4 v0 = g0 * acc[ai][bj][m][0], v1 = g1 * acc[ai][bj][m][1];
;                     if (MODE == 1) { f32x4 t0, t1; unpack8(*(const GAS u32x4*)(T1 + off + bj * HALF), t0, t1); v0 += t0; v1 += t1; }
;                     const u32x4 w = pack8(v0, v1);
;                     if (MODE == 0 && samp) asm volatile("global_store_dwordx4 %0, %1, off sc1\n\ts_nop 1" :: "v"(O + off + bj * HALF), "v"(w) : "memory");
;                     else *(GAS u32x4*)(O + off + bj * HALF) = w; } }
.LBB0_1094:
	v_or_b32_e32 v84, 48, v146
	v_mov_b64_e32 v[82:83], s[8:9]
	v_mad_i64_i32 v[82:83], s[0:1], v84, s95, v[82:83]
	v_lshl_add_u64 v[82:83], v[82:83], 0, v[144:145]
	v_add_co_u32_e32 v86, vcc, 0x1000, v82
	v_ashrrev_i32_e32 v85, 31, v84
	s_nop 0
	v_addc_co_u32_e32 v87, vcc, 0, v83, vcc
	v_lshlrev_b64 v[84:85], 12, v[84:85]
	v_lshl_add_u64 v[84:85], s[10:11], 0, v[84:85]
	v_lshl_add_u64 v[84:85], v[84:85], 0, v[144:145]
	s_and_b64 vcc, exec, s[42:43]
	s_mov_b64 s[54:55], -1
	s_waitcnt vmcnt(7)
	s_nop 1
	v_mov_b32_e32 v86, v180
	v_mov_b32_e32 v87, v181
	v_mov_b32_e32 v88, v182
	v_mov_b32_e32 v89, v183
	v_lshlrev_b32_e32 v90, 16, v86
	v_and_b32_e32 v91, 0xffff0000, v86
	v_lshlrev_b32_e32 v86, 16, v87
	v_and_b32_e32 v87, 0xffff0000, v87
	v_lshlrev_b32_e32 v92, 16, v88
	v_and_b32_e32 v93, 0xffff0000, v88
	v_lshlrev_b32_e32 v88, 16, v89
	v_and_b32_e32 v89, 0xffff0000, v89
	v_pk_mul_f32 v[80:81], v[80:81], v[86:87]
	v_pk_mul_f32 v[78:79], v[78:79], v[90:91]
	v_pk_mul_f32 v[86:87], v[76:77], v[88:89]
	v_pk_mul_f32 v[76:77], v[74:75], v[92:93]
	v_cvt_pk_bf16_f32 v74, v78, v79
	v_cvt_pk_bf16_f32 v75, v80, v81
	v_cvt_pk_bf16_f32 v76, v76, v77
	v_cvt_pk_bf16_f32 v77, v86, v87
	s_cbranch_vccnz .LBB0_1096
	s_mov_b64 s[54:55], 0
	global_store_dwordx4 v[84:85], v[74:77], off

; #define GAS __attribute__((address_space(1)))
; __device__ __forceinline__ u32x4 pack8(f32x4 v0, f32x4 v1) { u32x4 w; w.x = cvt_pk_bf16(v0[0], v0[1]); w.y = cvt_pk_bf16(v0[2], v0[3]); w.z = cvt_pk_bf16(v1[0], v1[1]); w.w = cvt_pk_bf16(v1[2], v1[3]); return w; }
; __device__ __forceinline__ void unpack8(u32x4 w, f32x4& v0, f32x4& v1) { v0 = (f32x4){bflo(w.x), bfhi(w.x), bflo(w.y), bfhi(w.y)}; v1 = (f32x4){bflo(w.z), bfhi(w.z), bflo(w.w), bfhi(w.w)}; }
; #define GAS __attribute__((address_space(1)))
;     __device__ __forceinline__ void operator()(const f32x4 (&acc)[2][2][4][2], const Unit& u, int wr, int wc, int fr, int fq) const {
;     ...
;             for (int m = 0; m < 4; ++m) { const size_t r = (size_t)(row0 + ai * HALF + m * 16); const size_t off = r * 2048 + col0; const bf16_t* gp = P + r * NPJ + 2560 + MODE * 2048 + col0;
; #pragma unroll
;                 for (int bj = 0; bj < 2; ++bj) { f32x4 g0, g1; unpack8(*(const GAS u32x4*)(gp + bj * HALF), g0, g1);
;                     f32x4 v0 = g0 * acc[ai][bj][m][0], v1 = g1 * acc[ai][bj][m][1];
;                     if (MODE == 1) { f32x4 t0, t1; unpack8(*(const GAS u32x4*)(T1 + off + bj * HALF), t0, t1); v0 += t0; v1 += t1; }
;                     const u32x4 w = pack8(v0, v1);
;                     if (MODE == 0 && samp) asm volatile("global_store_dwordx4 %0, %1, off sc1\n\ts_nop 1" :: "v"(O + off + bj * HALF), "v"(w) : "memory");
;                     else *(GAS u32x4*)(O + off + bj * HALF) = w; } }
.LBB0_1098:
	v_lshl_add_u64 v[74:75], v[82:83], 0, s[2:3]
	v_lshl_add_u64 v[74:75], v[84:85], 0, s[86:87]
	s_and_b64 vcc, exec, s[42:43]
	s_mov_b64 s[54:55], -1
	s_waitcnt vmcnt(7)
	s_nop 1
	v_mov_b32_e32 v76, v184
	v_mov_b32_e32 v77, v185
	v_mov_b32_e32 v78, v186
	v_mov_b32_e32 v79, v187
	v_lshlrev_b32_e32 v80, 16, v76
	v_and_b32_e32 v81, 0xffff0000, v76
	v_lshlrev_b32_e32 v76, 16, v77
	v_and_b32_e32 v77, 0xffff0000, v77
	v_lshlrev_b32_e32 v82, 16, v78
	v_and_b32_e32 v83, 0xffff0000, v78
	v_lshlrev_b32_e32 v78, 16, v79
	v_and_b32_e32 v79, 0xffff0000, v79
	v_pk_mul_f32 v[72:73], v[72:73], v[76:77]
	v_pk_mul_f32 v[70:71], v[70:71], v[80:81]
	v_pk_mul_f32 v[76:77], v[68:69], v[78:79]
	v_pk_mul_f32 v[68:69], v[66:67], v[82:83]
	v_cvt_pk_bf16_f32 v66, v70, v71
	v_cvt_pk_bf16_f32 v67, v72, v73
	v_cvt_pk_bf16_f32 v68, v68, v69
	v_cvt_pk_bf16_f32 v69, v76, v77
	s_cbranch_vccnz .LBB0_1100
	s_mov_b64 s[54:55], 0
	global_store_dwordx4 v[74:75], v[66:69], off

; #define GAS __attribute__((address_space(1)))
; __device__ __forceinline__ u32x4 pack8(f32x4 v0, f32x4 v1) { u32x4 w; w.x = cvt_pk_bf16(v0[0], v0[1]); w.y = cvt_pk_bf16(v0[2], v0[3]); w.z = cvt_pk_bf16(v1[0], v1[1]); w.w = cvt_pk_bf16(v1[2], v1[3]); return w; }
; __device__ __forceinline__ void unpack8(u32x4 w, f32x4& v0, f32x4& v1) { v0 = (f32x4){bflo(w.x), bfhi(w.x), bflo(w.y), bfhi(w.y)}; v1 = (f32x4){bflo(w.z), bfhi(w.z), bflo(w.w), bfhi(w.w)}; }
; #define GAS __attribute__((address_space(1)))
;     __device__ __forceinline__ void operator()(const f32x4 (&acc)[2][2][4][2], const Unit& u, int wr, int wc, int fr, int fq) const {
;     ...
;             for (int m = 0; m < 4; ++m) { const size_t r = (size_t)(row0 + ai * HALF + m * 16); const size_t off = r * 2048 + col0; const bf16_t* gp = P + r * NPJ + 2560 + MODE * 2048 + col0;
; #pragma unroll
;                 for (int bj = 0; bj < 2; ++bj) { f32x4 g0, g1; unpack8(*(const GAS u32x4*)(gp + bj * HALF), g0, g1);
;                     f32x4 v0 = g0 * acc[ai][bj][m][0], v1 = g1 * acc[ai][bj][m][1];
;                     if (MODE == 1) { f32x4 t0, t1; unpack8(*(const GAS u32x4*)(T1 + off + bj * HALF), t0, t1); v0 += t0; v1 += t1; }
;                     const u32x4 w = pack8(v0, v1);
;                     if (MODE == 0 && samp) asm volatile("global_store_dwordx4 %0, %1, off sc1\n\ts_nop 1" :: "v"(O + off + bj * HALF), "v"(w) : "memory");
;                     else *(GAS u32x4*)(O + off + bj * HALF) = w; } }
.LBB0_1102:
	v_add_u32_e32 v68, 0x80, v146
	v_mov_b64_e32 v[66:67], s[8:9]
	v_mad_i64_i32 v[66:67], s[0:1], v68, s95, v[66:67]
	v_lshl_add_u64 v[66:67], v[66:67], 0, v[144:145]
	v_add_co_u32_e32 v70, vcc, 0x1000, v66
	v_ashrrev_i32_e32 v69, 31, v68
	s_nop 0
	v_addc_co_u32_e32 v71, vcc, 0, v67, vcc
	global_load_dwordx4 v[222:225], v[70:71], off offset:1024
	global_load_dwordx4 v[226:229], v[70:71], off offset:1280
	v_add_co_u32_e32 v188, vcc, 0x34000, v70
	s_nop 1
	v_addc_co_u32_e32 v189, vcc, 0, v71, vcc
	global_load_dwordx4 v[230:233], v[188:189], off offset:1024
	global_load_dwordx4 v[234:237], v[188:189], off offset:1280
	v_add_co_u32_e32 v188, vcc, 0x68000, v70
	s_nop 1
	v_addc_co_u32_e32 v189, vcc, 0, v71, vcc
	global_load_dwordx4 v[238:241], v[188:189], off offset:1024
	global_load_dwordx4 v[242:245], v[188:189], off offset:1280
	v_add_co_u32_e32 v188, vcc, 0x9c000, v70
	s_nop 1
	v_addc_co_u32_e32 v189, vcc, 0, v71, vcc
	global_load_dwordx4 v[180:183], v[188:189], off offset:1024
	global_load_dwordx4 v[184:187], v[188:189], off offset:1280
	v_lshlrev_b64 v[68:69], 12, v[68:69]
	v_lshl_add_u64 v[68:69], s[10:11], 0, v[68:69]
	v_lshl_add_u64 v[68:69], v[68:69], 0, v[144:145]
	s_and_b64 vcc, exec, s[42:43]
	s_mov_b64 s[54:55], -1
	s_waitcnt vmcnt(7)
	s_nop 1
	v_mov_b32_e32 v70, v222
	v_mov_b32_e32 v71, v223
	v_mov_b32_e32 v72, v224
	v_mov_b32_e32 v73, v225
	v_lshlrev_b32_e32 v74, 16, v70
	v_and_b32_e32 v75, 0xffff0000, v70
	v_lshlrev_b32_e32 v70, 16, v71
	v_and_b32_e32 v71, 0xffff0000, v71
	v_lshlrev_b32_e32 v76, 16, v72
	v_and_b32_e32 v77, 0xffff0000, v72
	v_lshlrev_b32_e32 v72, 16, v73
	v_and_b32_e32 v73, 0xffff0000, v73
	v_pk_mul_f32 v[64:65], v[64:65], v[70:71]
	v_pk_mul_f32 v[62:63], v[62:63], v[74:75]
	v_pk_mul_f32 v[70:71], v[60:61], v[72:73]
	v_pk_mul_f32 v[60:61], v[58:59], v[76:77]
	v_cvt_pk_bf16_f32 v58, v62, v63
	v_cvt_pk_bf16_f32 v59, v64, v65
	v_cvt_pk_bf16_f32 v60, v60, v61
	v_cvt_pk_bf16_f32 v61, v70, v71
	s_cbranch_vccnz .LBB0_1104
	s_mov_b64 s[54:55], 0
	global_store_dwordx4 v[68:69], v[58:61], off

; #define GAS __attribute__((address_space(1)))
; __device__ __forceinline__ u32x4 pack8(f32x4 v0, f32x4 v1) { u32x4 w; w.x = cvt_pk_bf16(v0[0], v0[1]); w.y = cvt_pk_bf16(v0[2], v0[3]); w.z = cvt_pk_bf16(v1[0], v1[1]); w.w = cvt_pk_bf16(v1[2], v1[3]); return w; }
; __device__ __forceinline__ void unpack8(u32x4 w, f32x4& v0, f32x4& v1) { v0 = (f32x4){bflo(w.x), bfhi(w.x), bflo(w.y), bfhi(w.y)}; v1 = (f32x4){bflo(w.z), bfhi(w.z), bflo(w.w), bfhi(w.w)}; }
; #define GAS __attribute__((address_space(1)))
;     __device__ __forceinline__ void operator()(const f32x4 (&acc)[2][2][4][2], const Unit& u, int wr, int wc, int fr, int fq) const {
;     ...
;             for (int m = 0; m < 4; ++m) { const size_t r = (size_t)(row0 + ai * HALF + m * 16); const size_t off = r * 2048 + col0; const bf16_t* gp = P + r * NPJ + 2560 + MODE * 2048 + col0;
; #pragma unroll
;                 for (int bj = 0; bj < 2; ++bj) { f32x4 g0, g1; unpack8(*(const GAS u32x4*)(gp + bj * HALF), g0, g1);
;                     f32x4 v0 = g0 * acc[ai][bj][m][0], v1 = g1 * acc[ai][bj][m][1];
;                     if (MODE == 1) { f32x4 t0, t1; unpack8(*(const GAS u32x4*)(T1 + off + bj * HALF), t0, t1); v0 += t0; v1 += t1; }
;                     const u32x4 w = pack8(v0, v1);
;                     if (MODE == 0 && samp) asm volatile("global_store_dwordx4 %0, %1, off sc1\n\ts_nop 1" :: "v"(O + off + bj * HALF), "v"(w) : "memory");
;                     else *(GAS u32x4*)(O + off + bj * HALF) = w; } }
.LBB0_1106:
	v_lshl_add_u64 v[58:59], v[66:67], 0, s[2:3]
	v_lshl_add_u64 v[58:59], v[68:69], 0, s[86:87]
	s_and_b64 vcc, exec, s[42:43]
	s_mov_b64 s[54:55], -1
	s_waitcnt vmcnt(7)
	s_nop 1
	v_mov_b32_e32 v60, v226
	v_mov_b32_e32 v61, v227
	v_mov_b32_e32 v62, v228
	v_mov_b32_e32 v63, v229
	v_lshlrev_b32_e32 v64, 16, v60
	v_and_b32_e32 v65, 0xffff0000, v60
	v_lshlrev_b32_e32 v60, 16, v61
	v_and_b32_e32 v61, 0xffff0000, v61
	v_lshlrev_b32_e32 v66, 16, v62
	v_and_b32_e32 v67, 0xffff0000, v62
	v_lshlrev_b32_e32 v62, 16, v63
	v_and_b32_e32 v63, 0xffff0000, v63
	v_pk_mul_f32 v[56:57], v[56:57], v[60:61]
	v_pk_mul_f32 v[54:55], v[54:55], v[64:65]
	v_pk_mul_f32 v[60:61], v[52:53], v[62:63]
	v_pk_mul_f32 v[52:53], v[50:51], v[66:67]
	v_cvt_pk_bf16_f32 v50, v54, v55
	v_cvt_pk_bf16_f32 v51, v56, v57
	v_cvt_pk_bf16_f32 v52, v52, v53
	v_cvt_pk_bf16_f32 v53, v60, v61
	s_cbranch_vccnz .LBB0_1108
	s_mov_b64 s[54:55], 0
	global_store_dwordx4 v[58:59], v[50:53], off

; #define GAS __attribute__((address_space(1)))
; __device__ __forceinline__ u32x4 pack8(f32x4 v0, f32x4 v1) { u32x4 w; w.x = cvt_pk_bf16(v0[0], v0[1]); w.y = cvt_pk_bf16(v0[2], v0[3]); w.z = cvt_pk_bf16(v1[0], v1[1]); w.w = cvt_pk_bf16(v1[2], v1[3]); return w; }
; __device__ __forceinline__ void unpack8(u32x4 w, f32x4& v0, f32x4& v1) { v0 = (f32x4){bflo(w.x), bfhi(w.x), bflo(w.y), bfhi(w.y)}; v1 = (f32x4){bflo(w.z), bfhi(w.z), bflo(w.w), bfhi(w.w)}; }
; #define GAS __attribute__((address_space(1)))
;     __device__ __forceinline__ void operator()(const f32x4 (&acc)[2][2][4][2], const Unit& u, int wr, int wc, int fr, int fq) const {
;     ...
;             for (int m = 0; m < 4; ++m) { const size_t r = (size_t)(row0 + ai * HALF + m * 16); const size_t off = r * 2048 + col0; const bf16_t* gp = P + r * NPJ + 2560 + MODE * 2048 + col0;
; #pragma unroll
;                 for (int bj = 0; bj < 2; ++bj) { f32x4 g0, g1; unpack8(*(const GAS u32x4*)(gp + bj * HALF), g0, g1);
;                     f32x4 v0 = g0 * acc[ai][bj][m][0], v1 = g1 * acc[ai][bj][m][1];
;                     if (MODE == 1) { f32x4 t0, t1; unpack8(*(const GAS u32x4*)(T1 + off + bj * HALF), t0, t1); v0 += t0; v1 += t1; }
;                     const u32x4 w = pack8(v0, v1);
;                     if (MODE == 0 && samp) asm volatile("global_store_dwordx4 %0, %1, off sc1\n\ts_nop 1" :: "v"(O + off + bj * HALF), "v"(w) : "memory");
;                     else *(GAS u32x4*)(O + off + bj * HALF) = w; } }
.LBB0_1110:
	v_add_u32_e32 v52, 0x90, v146
	v_mov_b64_e32 v[50:51], s[8:9]
	v_mad_i64_i32 v[50:51], s[0:1], v52, s95, v[50:51]
	v_lshl_add_u64 v[50:51], v[50:51], 0, v[144:145]
	v_add_co_u32_e32 v54, vcc, 0x1000, v50
	v_ashrrev_i32_e32 v53, 31, v52
	s_nop 0
	v_addc_co_u32_e32 v55, vcc, 0, v51, vcc
	v_lshlrev_b64 v[52:53], 12, v[52:53]
	v_lshl_add_u64 v[52:53], s[10:11], 0, v[52:53]
	v_lshl_add_u64 v[52:53], v[52:53], 0, v[144:145]
	s_and_b64 vcc, exec, s[42:43]
	s_mov_b64 s[54:55], -1
	s_waitcnt vmcnt(7)
	s_nop 1
	v_mov_b32_e32 v54, v230
	v_mov_b32_e32 v55, v231
	v_mov_b32_e32 v56, v232
	v_mov_b32_e32 v57, v233
	v_lshlrev_b32_e32 v58, 16, v54
	v_and_b32_e32 v59, 0xffff0000, v54
	v_lshlrev_b32_e32 v54, 16, v55
	v_and_b32_e32 v55, 0xffff0000, v55
	v_lshlrev_b32_e32 v60, 16, v56
	v_and_b32_e32 v61, 0xffff0000, v56
	v_lshlrev_b32_e32 v56, 16, v57
	v_and_b32_e32 v57, 0xffff0000, v57
	v_pk_mul_f32 v[48:49], v[48:49], v[54:55]
	v_pk_mul_f32 v[46:47], v[46:47], v[58:59]
	v_pk_mul_f32 v[54:55], v[44:45], v[56:57]
	v_pk_mul_f32 v[44:45], v[42:43], v[60:61]
	v_cvt_pk_bf16_f32 v42, v46, v47
	v_cvt_pk_bf16_f32 v43, v48, v49
	v_cvt_pk_bf16_f32 v44, v44, v45
	v_cvt_pk_bf16_f32 v45, v54, v55
	s_cbranch_vccnz .LBB0_1112
	s_mov_b64 s[54:55], 0
	global_store_dwordx4 v[52:53], v[42:45], off

; #define GAS __attribute__((address_space(1)))
; __device__ __forceinline__ u32x4 pack8(f32x4 v0, f32x4 v1) { u32x4 w; w.x = cvt_pk_bf16(v0[0], v0[1]); w.y = cvt_pk_bf16(v0[2], v0[3]); w.z = cvt_pk_bf16(v1[0], v1[1]); w.w = cvt_pk_bf16(v1[2], v1[3]); return w; }
; __device__ __forceinline__ void unpack8(u32x4 w, f32x4& v0, f32x4& v1) { v0 = (f32x4){bflo(w.x), bfhi(w.x), bflo(w.y), bfhi(w.y)}; v1 = (f32x4){bflo(w.z), bfhi(w.z), bflo(w.w), bfhi(w.w)}; }
; #define GAS __attribute__((address_space(1)))
;     __device__ __forceinline__ void operator()(const f32x4 (&acc)[2][2][4][2], const Unit& u, int wr, int wc, int fr, int fq) const {
;     ...
;             for (int m = 0; m < 4; ++m) { const size_t r = (size_t)(row0 + ai * HALF + m * 16); const size_t off = r * 2048 + col0; const bf16_t* gp = P + r * NPJ + 2560 + MODE * 2048 + col0;
; #pragma unroll
;                 for (int bj = 0; bj < 2; ++bj) { f32x4 g0, g1; unpack8(*(const GAS u32x4*)(gp + bj * HALF), g0, g1);
;                     f32x4 v0 = g0 * acc[ai][bj][m][0], v1 = g1 * acc[ai][bj][m][1];
;                     if (MODE == 1) { f32x4 t0, t1; unpack8(*(const GAS u32x4*)(T1 + off + bj * HALF), t0, t1); v0 += t0; v1 += t1; }
;                     const u32x4 w = pack8(v0, v1);
;                     if (MODE == 0 && samp) asm volatile("global_store_dwordx4 %0, %1, off sc1\n\ts_nop 1" :: "v"(O + off + bj * HALF), "v"(w) : "memory");
;                     else *(GAS u32x4*)(O + off + bj * HALF) = w; } }
.LBB0_1114:
	v_lshl_add_u64 v[42:43], v[50:51], 0, s[2:3]
	v_lshl_add_u64 v[42:43], v[52:53], 0, s[86:87]
	s_and_b64 vcc, exec, s[42:43]
	s_mov_b64 s[54:55], -1
	s_waitcnt vmcnt(7)
	s_nop 1
	v_mov_b32_e32 v44, v234
	v_mov_b32_e32 v45, v235
	v_mov_b32_e32 v46, v236
	v_mov_b32_e32 v47, v237
	v_lshlrev_b32_e32 v48, 16, v44
	v_and_b32_e32 v49, 0xffff0000, v44
	v_lshlrev_b32_e32 v44, 16, v45
	v_and_b32_e32 v45, 0xffff0000, v45
	v_lshlrev_b32_e32 v50, 16, v46
	v_and_b32_e32 v51, 0xffff0000, v46
	v_lshlrev_b32_e32 v46, 16, v47
	v_and_b32_e32 v47, 0xffff0000, v47
	v_pk_mul_f32 v[40:41], v[40:41], v[44:45]
	v_pk_mul_f32 v[38:39], v[38:39], v[48:49]
	v_pk_mul_f32 v[44:45], v[36:37], v[46:47]
	v_pk_mul_f32 v[36:37], v[34:35], v[50:51]
	v_cvt_pk_bf16_f32 v34, v38, v39
	v_cvt_pk_bf16_f32 v35, v40, v41
	v_cvt_pk_bf16_f32 v36, v36, v37
	v_cvt_pk_bf16_f32 v37, v44, v45
	s_cbranch_vccnz .LBB0_1116
	s_mov_b64 s[54:55], 0
	global_store_dwordx4 v[42:43], v[34:37], off

; #define GAS __attribute__((address_space(1)))
; __device__ __forceinline__ u32x4 pack8(f32x4 v0, f32x4 v1) { u32x4 w; w.x = cvt_pk_bf16(v0[0], v0[1]); w.y = cvt_pk_bf16(v0[2], v0[3]); w.z = cvt_pk_bf16(v1[0], v1[1]); w.w = cvt_pk_bf16(v1[2], v1[3]); return w; }
; __device__ __forceinline__ void unpack8(u32x4 w, f32x4& v0, f32x4& v1) { v0 = (f32x4){bflo(w.x), bfhi(w.x), bflo(w.y), bfhi(w.y)}; v1 = (f32x4){bflo(w.z), bfhi(w.z), bflo(w.w), bfhi(w.w)}; }
; #define GAS __attribute__((address_space(1)))
;     __device__ __forceinline__ void operator()(const f32x4 (&acc)[2][2][4][2], const Unit& u, int wr, int wc, int fr, int fq) const {
;     ...
;             for (int m = 0; m < 4; ++m) { const size_t r = (size_t)(row0 + ai * HALF + m * 16); const size_t off = r * 2048 + col0; const bf16_t* gp = P + r * NPJ + 2560 + MODE * 2048 + col0;
; #pragma unroll
;                 for (int bj = 0; bj < 2; ++bj) { f32x4 g0, g1; unpack8(*(const GAS u32x4*)(gp + bj * HALF), g0, g1);
;                     f32x4 v0 = g0 * acc[ai][bj][m][0], v1 = g1 * acc[ai][bj][m][1];
;                     if (MODE == 1) { f32x4 t0, t1; unpack8(*(const GAS u32x4*)(T1 + off + bj * HALF), t0, t1); v0 += t0; v1 += t1; }
;                     const u32x4 w = pack8(v0, v1);
;                     if (MODE == 0 && samp) asm volatile("global_store_dwordx4 %0, %1, off sc1\n\ts_nop 1" :: "v"(O + off + bj * HALF), "v"(w) : "memory");
;                     else *(GAS u32x4*)(O + off + bj * HALF) = w; } }
.LBB0_1118:
	v_add_u32_e32 v36, 0xa0, v146
	v_mov_b64_e32 v[34:35], s[8:9]
	v_mad_i64_i32 v[34:35], s[0:1], v36, s95, v[34:35]
	v_lshl_add_u64 v[34:35], v[34:35], 0, v[144:145]
	v_add_co_u32_e32 v38, vcc, 0x1000, v34
	v_ashrrev_i32_e32 v37, 31, v36
	s_nop 0
	v_addc_co_u32_e32 v39, vcc, 0, v35, vcc
	v_lshlrev_b64 v[36:37], 12, v[36:37]
	v_lshl_add_u64 v[36:37], s[10:11], 0, v[36:37]
	v_lshl_add_u64 v[36:37], v[36:37], 0, v[144:145]
	s_and_b64 vcc, exec, s[42:43]
	s_mov_b64 s[54:55], -1
	s_waitcnt vmcnt(7)
	s_nop 1
	v_mov_b32_e32 v38, v238
	v_mov_b32_e32 v39, v239
	v_mov_b32_e32 v40, v240
	v_mov_b32_e32 v41, v241
	v_lshlrev_b32_e32 v42, 16, v38
	v_and_b32_e32 v43, 0xffff0000, v38
	v_lshlrev_b32_e32 v38, 16, v39
	v_and_b32_e32 v39, 0xffff0000, v39
	v_lshlrev_b32_e32 v44, 16, v40
	v_and_b32_e32 v45, 0xffff0000, v40
	v_lshlrev_b32_e32 v40, 16, v41
	v_and_b32_e32 v41, 0xffff0000, v41
	v_pk_mul_f32 v[32:33], v[32:33], v[38:39]
	v_pk_mul_f32 v[30:31], v[30:31], v[42:43]
	v_pk_mul_f32 v[38:39], v[28:29], v[40:41]
	v_pk_mul_f32 v[28:29], v[26:27], v[44:45]
	v_cvt_pk_bf16_f32 v26, v30, v31
	v_cvt_pk_bf16_f32 v27, v32, v33
	v_cvt_pk_bf16_f32 v28, v28, v29
	v_cvt_pk_bf16_f32 v29, v38, v39
	s_cbranch_vccnz .LBB0_1120
	s_mov_b64 s[54:55], 0
	global_store_dwordx4 v[36:37], v[26:29], off

; #define GAS __attribute__((address_space(1)))
; __device__ __forceinline__ u32x4 pack8(f32x4 v0, f32x4 v1) { u32x4 w; w.x = cvt_pk_bf16(v0[0], v0[1]); w.y = cvt_pk_bf16(v0[2], v0[3]); w.z = cvt_pk_bf16(v1[0], v1[1]); w.w = cvt_pk_bf16(v1[2], v1[3]); return w; }
; __device__ __forceinline__ void unpack8(u32x4 w, f32x4& v0, f32x4& v1) { v0 = (f32x4){bflo(w.x), bfhi(w.x), bflo(w.y), bfhi(w.y)}; v1 = (f32x4){bflo(w.z), bfhi(w.z), bflo(w.w), bfhi(w.w)}; }
; #define GAS __attribute__((address_space(1)))
;     __device__ __forceinline__ void operator()(const f32x4 (&acc)[2][2][4][2], const Unit& u, int wr, int wc, int fr, int fq) const {
;     ...
;             for (int m = 0; m < 4; ++m) { const size_t r = (size_t)(row0 + ai * HALF + m * 16); const size_t off = r * 2048 + col0; const bf16_t* gp = P + r * NPJ + 2560 + MODE * 2048 + col0;
; #pragma unroll
;                 for (int bj = 0; bj < 2; ++bj) { f32x4 g0, g1; unpack8(*(const GAS u32x4*)(gp + bj * HALF), g0, g1);
;                     f32x4 v0 = g0 * acc[ai][bj][m][0], v1 = g1 * acc[ai][bj][m][1];
;                     if (MODE == 1) { f32x4 t0, t1; unpack8(*(const GAS u32x4*)(T1 + off + bj * HALF), t0, t1); v0 += t0; v1 += t1; }
;                     const u32x4 w = pack8(v0, v1);
;                     if (MODE == 0 && samp) asm volatile("global_store_dwordx4 %0, %1, off sc1\n\ts_nop 1" :: "v"(O + off + bj * HALF), "v"(w) : "memory");
;                     else *(GAS u32x4*)(O + off + bj * HALF) = w; } }
.LBB0_1122:
	v_lshl_add_u64 v[26:27], v[34:35], 0, s[2:3]
	v_lshl_add_u64 v[26:27], v[36:37], 0, s[86:87]
	s_and_b64 vcc, exec, s[42:43]
	s_mov_b64 s[54:55], -1
	s_waitcnt vmcnt(7)
	s_nop 1
	v_mov_b32_e32 v28, v242
	v_mov_b32_e32 v29, v243
	v_mov_b32_e32 v30, v244
	v_mov_b32_e32 v31, v245
	v_lshlrev_b32_e32 v32, 16, v28
	v_and_b32_e32 v33, 0xffff0000, v28
	v_lshlrev_b32_e32 v28, 16, v29
	v_and_b32_e32 v29, 0xffff0000, v29
	v_lshlrev_b32_e32 v34, 16, v30
	v_and_b32_e32 v35, 0xffff0000, v30
	v_lshlrev_b32_e32 v30, 16, v31
	v_and_b32_e32 v31, 0xffff0000, v31
	v_pk_mul_f32 v[24:25], v[24:25], v[28:29]
	v_pk_mul_f32 v[22:23], v[22:23], v[32:33]
	v_pk_mul_f32 v[28:29], v[20:21], v[30:31]
	v_pk_mul_f32 v[20:21], v[18:19], v[34:35]
	v_cvt_pk_bf16_f32 v18, v22, v23
	v_cvt_pk_bf16_f32 v19, v24, v25
	v_cvt_pk_bf16_f32 v20, v20, v21
	v_cvt_pk_bf16_f32 v21, v28, v29
	s_cbranch_vccnz .LBB0_1124
	s_mov_b64 s[54:55], 0
	global_store_dwordx4 v[26:27], v[18:21], off

; #define GAS __attribute__((address_space(1)))
; __device__ __forceinline__ u32x4 pack8(f32x4 v0, f32x4 v1) { u32x4 w; w.x = cvt_pk_bf16(v0[0], v0[1]); w.y = cvt_pk_bf16(v0[2], v0[3]); w.z = cvt_pk_bf16(v1[0], v1[1]); w.w = cvt_pk_bf16(v1[2], v1[3]); return w; }
; __device__ __forceinline__ void unpack8(u32x4 w, f32x4& v0, f32x4& v1) { v0 = (f32x4){bflo(w.x), bfhi(w.x), bflo(w.y), bfhi(w.y)}; v1 = (f32x4){bflo(w.z), bfhi(w.z), bflo(w.w), bfhi(w.w)}; }
; #define GAS __attribute__((address_space(1)))
;     __device__ __forceinline__ void operator()(const f32x4 (&acc)[2][2][4][2], const Unit& u, int wr, int wc, int fr, int fq) const {
;     ...
;             for (int m = 0; m < 4; ++m) { const size_t r = (size_t)(row0 + ai * HALF + m * 16); const size_t off = r * 2048 + col0; const bf16_t* gp = P + r * NPJ + 2560 + MODE * 2048 + col0;
; #pragma unroll
;                 for (int bj = 0; bj < 2; ++bj) { f32x4 g0, g1; unpack8(*(const GAS u32x4*)(gp + bj * HALF), g0, g1);
;                     f32x4 v0 = g0 * acc[ai][bj][m][0], v1 = g1 * acc[ai][bj][m][1];
;                     if (MODE == 1) { f32x4 t0, t1; unpack8(*(const GAS u32x4*)(T1 + off + bj * HALF), t0, t1); v0 += t0; v1 += t1; }
;                     const u32x4 w = pack8(v0, v1);
;                     if (MODE == 0 && samp) asm volatile("global_store_dwordx4 %0, %1, off sc1\n\ts_nop 1" :: "v"(O + off + bj * HALF), "v"(w) : "memory");
;                     else *(GAS u32x4*)(O + off + bj * HALF) = w; } }
.LBB0_1126:
	v_add_u32_e32 v20, 0xb0, v146
	v_mov_b64_e32 v[18:19], s[8:9]
	v_mad_i64_i32 v[18:19], s[0:1], v20, s95, v[18:19]
	v_lshl_add_u64 v[18:19], v[18:19], 0, v[144:145]
	v_add_co_u32_e32 v22, vcc, 0x1000, v18
	v_ashrrev_i32_e32 v21, 31, v20
	s_nop 0
	v_addc_co_u32_e32 v23, vcc, 0, v19, vcc
	v_lshlrev_b64 v[20:21], 12, v[20:21]
	v_lshl_add_u64 v[20:21], s[10:11], 0, v[20:21]
	v_lshl_add_u64 v[20:21], v[20:21], 0, v[144:145]
	s_and_b64 vcc, exec, s[42:43]
	s_mov_b64 s[54:55], -1
	s_waitcnt vmcnt(7)
	s_nop 1
	v_mov_b32_e32 v22, v180
	v_mov_b32_e32 v23, v181
	v_mov_b32_e32 v24, v182
	v_mov_b32_e32 v25, v183
	v_lshlrev_b32_e32 v26, 16, v22
	v_and_b32_e32 v27, 0xffff0000, v22
	v_lshlrev_b32_e32 v22, 16, v23
	v_and_b32_e32 v23, 0xffff0000, v23
	v_lshlrev_b32_e32 v28, 16, v24
	v_and_b32_e32 v29, 0xffff0000, v24
	v_lshlrev_b32_e32 v24, 16, v25
	v_and_b32_e32 v25, 0xffff0000, v25
	v_pk_mul_f32 v[16:17], v[16:17], v[22:23]
	v_pk_mul_f32 v[14:15], v[14:15], v[26:27]
	v_pk_mul_f32 v[22:23], v[12:13], v[24:25]
	v_pk_mul_f32 v[12:13], v[10:11], v[28:29]
	v_cvt_pk_bf16_f32 v10, v14, v15
	v_cvt_pk_bf16_f32 v11, v16, v17
	v_cvt_pk_bf16_f32 v12, v12, v13
	v_cvt_pk_bf16_f32 v13, v22, v23
	s_cbranch_vccnz .LBB0_1128
	s_mov_b64 s[54:55], 0
	global_store_dwordx4 v[20:21], v[10:13], off

; #define GAS __attribute__((address_space(1)))
; __device__ __forceinline__ u32x4 pack8(f32x4 v0, f32x4 v1) { u32x4 w; w.x = cvt_pk_bf16(v0[0], v0[1]); w.y = cvt_pk_bf16(v0[2], v0[3]); w.z = cvt_pk_bf16(v1[0], v1[1]); w.w = cvt_pk_bf16(v1[2], v1[3]); return w; }
; __device__ __forceinline__ void unpack8(u32x4 w, f32x4& v0, f32x4& v1) { v0 = (f32x4){bflo(w.x), bfhi(w.x), bflo(w.y), bfhi(w.y)}; v1 = (f32x4){bflo(w.z), bfhi(w.z), bflo(w.w), bfhi(w.w)}; }
; #define GAS __attribute__((address_space(1)))
;     __device__ __forceinline__ void operator()(const f32x4 (&acc)[2][2][4][2], const Unit& u, int wr, int wc, int fr, int fq) const {
;     ...
;             for (int m = 0; m < 4; ++m) { const size_t r = (size_t)(row0 + ai * HALF + m * 16); const size_t off = r * 2048 + col0; const bf16_t* gp = P + r * NPJ + 2560 + MODE * 2048 + col0;
; #pragma unroll
;                 for (int bj = 0; bj < 2; ++bj) { f32x4 g0, g1; unpack8(*(const GAS u32x4*)(gp + bj * HALF), g0, g1);
;                     f32x4 v0 = g0 * acc[ai][bj][m][0], v1 = g1 * acc[ai][bj][m][1];
;                     if (MODE == 1) { f32x4 t0, t1; unpack8(*(const GAS u32x4*)(T1 + off + bj * HALF), t0, t1); v0 += t0; v1 += t1; }
;                     const u32x4 w = pack8(v0, v1);
;                     if (MODE == 0 && samp) asm volatile("global_store_dwordx4 %0, %1, off sc1\n\ts_nop 1" :: "v"(O + off + bj * HALF), "v"(w) : "memory");
;                     else *(GAS u32x4*)(O + off + bj * HALF) = w; } }
.LBB0_1130:
	v_lshl_add_u64 v[10:11], v[18:19], 0, s[2:3]
	v_lshl_add_u64 v[10:11], v[20:21], 0, s[86:87]
	s_and_b64 vcc, exec, s[42:43]
	s_mov_b64 s[42:43], -1
	s_waitcnt vmcnt(7)
	s_nop 1
	v_mov_b32_e32 v12, v184
	v_mov_b32_e32 v13, v185
	v_mov_b32_e32 v14, v186
	v_mov_b32_e32 v15, v187
	v_lshlrev_b32_e32 v16, 16, v12
	v_and_b32_e32 v17, 0xffff0000, v12
	v_lshlrev_b32_e32 v12, 16, v13
	v_and_b32_e32 v13, 0xffff0000, v13
	v_lshlrev_b32_e32 v18, 16, v14
	v_and_b32_e32 v19, 0xffff0000, v14
	v_lshlrev_b32_e32 v14, 16, v15
	v_and_b32_e32 v15, 0xffff0000, v15
	v_pk_mul_f32 v[8:9], v[8:9], v[12:13]
	v_pk_mul_f32 v[6:7], v[6:7], v[16:17]
	v_pk_mul_f32 v[12:13], v[4:5], v[14:15]
	v_pk_mul_f32 v[4:5], v[2:3], v[18:19]
	v_cvt_pk_bf16_f32 v2, v6, v7
	v_cvt_pk_bf16_f32 v3, v8, v9
	v_cvt_pk_bf16_f32 v4, v4, v5
	v_cvt_pk_bf16_f32 v5, v12, v13
	s_cbranch_vccz .LBB0_1134
	s_andn2_b64 vcc, exec, s[42:43]
	s_cbranch_vccz .LBB0_1135

; #define GAS __attribute__((address_space(1)))
; __device__ __forceinline__ u32x4 pack8(f32x4 v0, f32x4 v1) { u32x4 w; w.x = cvt_pk_bf16(v0[0], v0[1]); w.y = cvt_pk_bf16(v0[2], v0[3]); w.z = cvt_pk_bf16(v1[0], v1[1]); w.w = cvt_pk_bf16(v1[2], v1[3]); return w; }
; __device__ __forceinline__ void unpack8(u32x4 w, f32x4& v0, f32x4& v1) { v0 = (f32x4){bflo(w.x), bfhi(w.x), bflo(w.y), bfhi(w.y)}; v1 = (f32x4){bflo(w.z), bfhi(w.z), bflo(w.w), bfhi(w.w)}; }
; #define GAS __attribute__((address_space(1)))
;     __device__ __forceinline__ void operator()(const f32x4 (&acc)[2][2][4][2], const Unit& u, int wr, int wc, int fr, int fq) const {
;     ...
;             for (int m = 0; m < 4; ++m) { const size_t r = (size_t)(row0 + ai * HALF + m * 16); const size_t off = r * 2048 + col0; const bf16_t* gp = P + r * NPJ + 2560 + MODE * 2048 + col0;
; #pragma unroll
;                 for (int bj = 0; bj < 2; ++bj) { f32x4 g0, g1; unpack8(*(const GAS u32x4*)(gp + bj * HALF), g0, g1);
;                     f32x4 v0 = g0 * acc[ai][bj][m][0], v1 = g1 * acc[ai][bj][m][1];
;                     if (MODE == 1) { f32x4 t0, t1; unpack8(*(const GAS u32x4*)(T1 + off + bj * HALF), t0, t1); v0 += t0; v1 += t1; }
;                     const u32x4 w = pack8(v0, v1);
;                     if (MODE == 0 && samp) asm volatile("global_store_dwordx4 %0, %1, off sc1\n\ts_nop 1" :: "v"(O + off + bj * HALF), "v"(w) : "memory");
;                     else *(GAS u32x4*)(O + off + bj * HALF) = w; } }
.LBB0_1178:
	v_or_b32_e32 v144, s19, v152
	v_lshl_add_u32 v146, s90, 8, v1
	v_ashrrev_i32_e32 v145, 31, v144
	v_mov_b64_e32 v[148:149], s[8:9]
	v_ashrrev_i32_e32 v147, 31, v146
	v_mad_i64_i32 v[154:155], s[0:1], v146, s95, v[148:149]
	v_lshlrev_b64 v[150:151], 1, v[144:145]
	v_lshlrev_b64 v[158:159], 11, v[146:147]
	v_lshl_add_u64 v[162:163], v[154:155], 0, v[150:151]
	v_lshl_add_u64 v[158:159], v[158:159], 0, v[144:145]
	v_add_co_u32_e32 v154, vcc, 0x2000, v162
	v_lshlrev_b64 v[164:165], 1, v[158:159]
	s_nop 0
	v_addc_co_u32_e32 v155, vcc, 0, v163, vcc
	v_lshl_add_u64 v[166:167], s[10:11], 0, v[164:165]
	global_load_dwordx4 v[222:225], v[154:155], off offset:1024
	global_load_dwordx4 v[226:229], v[166:167], off
	global_load_dwordx4 v[230:233], v[154:155], off offset:1280
	global_load_dwordx4 v[234:237], v[166:167], off offset:256
	v_add_co_u32_e32 v192, vcc, 0x34000, v154
	s_nop 1
	v_addc_co_u32_e32 v193, vcc, 0, v155, vcc
	global_load_dwordx4 v[238:241], v[192:193], off offset:1024
	v_add_co_u32_e32 v194, vcc, 0x10000, v166
	s_nop 1
	v_addc_co_u32_e32 v195, vcc, 0, v167, vcc
	global_load_dwordx4 v[242:245], v[194:195], off
	global_load_dwordx4 v[184:187], v[192:193], off offset:1280
	global_load_dwordx4 v[188:191], v[194:195], off offset:256
	s_mov_b64 s[2:3], 0x2400
	v_lshl_add_u64 v[164:165], s[14:15], 0, v[164:165]
	v_lshl_add_u64 v[162:163], v[162:163], 0, s[2:3]
	s_movk_i32 s19, 0x2000
	s_waitcnt vmcnt(6)
	s_nop 1
	v_mov_b32_e32 v154, v222
	v_mov_b32_e32 v155, v223
	v_mov_b32_e32 v156, v224
	v_mov_b32_e32 v157, v225
	v_mov_b32_e32 v158, v226
	v_mov_b32_e32 v159, v227
	v_mov_b32_e32 v160, v228
	v_mov_b32_e32 v161, v229
	v_lshlrev_b32_e32 v168, 16, v154
	v_and_b32_e32 v169, 0xffff0000, v154
	v_lshlrev_b32_e32 v154, 16, v155
	v_and_b32_e32 v155, 0xffff0000, v155
	v_lshlrev_b32_e32 v172, 16, v156
	v_and_b32_e32 v173, 0xffff0000, v156
	v_lshlrev_b32_e32 v156, 16, v157
	v_and_b32_e32 v157, 0xffff0000, v157
	v_lshlrev_b32_e32 v180, 16, v158
	v_and_b32_e32 v181, 0xffff0000, v158
	v_lshlrev_b32_e32 v158, 16, v159
	v_and_b32_e32 v159, 0xffff0000, v159
	v_lshlrev_b32_e32 v182, 16, v160
	v_and_b32_e32 v183, 0xffff0000, v160
	v_lshlrev_b32_e32 v160, 16, v161
	v_and_b32_e32 v161, 0xffff0000, v161
	v_pk_fma_f32 v[130:131], v[130:131], v[154:155], v[158:159]
	v_pk_fma_f32 v[128:129], v[128:129], v[168:169], v[180:181]
	v_pk_fma_f32 v[154:155], v[126:127], v[156:157], v[160:161]
	v_pk_fma_f32 v[126:127], v[124:125], v[172:173], v[182:183]
	v_cvt_pk_bf16_f32 v124, v128, v129
	v_cvt_pk_bf16_f32 v125, v130, v131
	v_cvt_pk_bf16_f32 v126, v126, v127
	v_cvt_pk_bf16_f32 v127, v154, v155
	global_store_dwordx4 v[164:165], v[124:127], off
	s_nop 0
	v_or_b32_e32 v154, 16, v146
	v_ashrrev_i32_e32 v155, 31, v154
	v_mad_i64_i32 v[156:157], s[0:1], v154, s95, v[148:149]
	v_lshl_add_u64 v[156:157], v[156:157], 0, v[150:151]
	v_add_co_u32_e32 v158, vcc, s19, v156
	s_waitcnt vmcnt(6)
	s_nop 1
	v_mov_b32_e32 v124, v230
	v_mov_b32_e32 v125, v231
	v_mov_b32_e32 v126, v232
	v_mov_b32_e32 v127, v233
	v_lshlrev_b32_e32 v160, 16, v124
	v_and_b32_e32 v161, 0xffff0000, v124
	s_waitcnt vmcnt(5)
	s_nop 1
	v_mov_b32_e32 v128, v234
	v_mov_b32_e32 v129, v235
	v_mov_b32_e32 v130, v236
	v_mov_b32_e32 v131, v237
	v_lshlrev_b32_e32 v166, 16, v128
	v_and_b32_e32 v167, 0xffff0000, v128
	v_lshlrev_b32_e32 v124, 16, v125
	v_and_b32_e32 v125, 0xffff0000, v125
	v_lshlrev_b32_e32 v162, 16, v126
	v_and_b32_e32 v163, 0xffff0000, v126
	v_lshlrev_b32_e32 v126, 16, v127
	v_and_b32_e32 v127, 0xffff0000, v127
	v_lshlrev_b32_e32 v128, 16, v129
	v_and_b32_e32 v129, 0xffff0000, v129
	v_lshlrev_b32_e32 v168, 16, v130
	v_and_b32_e32 v169, 0xffff0000, v130
	v_lshlrev_b32_e32 v130, 16, v131
	v_and_b32_e32 v131, 0xffff0000, v131
	v_pk_fma_f32 v[120:121], v[120:121], v[160:161], v[166:167]
	v_pk_fma_f32 v[122:123], v[122:123], v[124:125], v[128:129]
	v_pk_fma_f32 v[124:125], v[118:119], v[126:127], v[130:131]
	v_pk_fma_f32 v[118:119], v[116:117], v[162:163], v[168:169]
	v_cvt_pk_bf16_f32 v116, v120, v121
	v_lshlrev_b64 v[120:121], 11, v[154:155]
	v_lshl_add_u64 v[120:121], v[120:121], 0, v[144:145]
	v_cvt_pk_bf16_f32 v117, v122, v123
	v_cvt_pk_bf16_f32 v118, v118, v119
	v_cvt_pk_bf16_f32 v119, v124, v125
	v_lshlrev_b64 v[124:125], 1, v[120:121]
	v_addc_co_u32_e32 v159, vcc, 0, v157, vcc
	global_store_dwordx4 v[164:165], v[116:119], off offset:256
	v_lshl_add_u64 v[126:127], s[10:11], 0, v[124:125]
	v_lshl_add_u64 v[128:129], v[156:157], 0, s[2:3]
	v_lshl_add_u64 v[124:125], s[14:15], 0, v[124:125]
	s_waitcnt vmcnt(5)
	s_nop 1
	v_mov_b32_e32 v116, v238
	v_mov_b32_e32 v117, v239
	v_mov_b32_e32 v118, v240
	v_mov_b32_e32 v119, v241
	v_lshlrev_b32_e32 v130, 16, v116
	v_and_b32_e32 v131, 0xffff0000, v116
	v_lshlrev_b32_e32 v116, 16, v117
	v_and_b32_e32 v117, 0xffff0000, v117
	v_lshlrev_b32_e32 v154, 16, v118
	v_and_b32_e32 v155, 0xffff0000, v118
	v_lshlrev_b32_e32 v118, 16, v119
	v_and_b32_e32 v119, 0xffff0000, v119
	s_waitcnt vmcnt(4)
	s_nop 1
	v_mov_b32_e32 v120, v242
	v_mov_b32_e32 v121, v243
	v_mov_b32_e32 v122, v244
	v_mov_b32_e32 v123, v245
	v_lshlrev_b32_e32 v156, 16, v120
	v_and_b32_e32 v157, 0xffff0000, v120
	v_lshlrev_b32_e32 v120, 16, v121
	v_and_b32_e32 v121, 0xffff0000, v121
	v_lshlrev_b32_e32 v158, 16, v122
	v_and_b32_e32 v159, 0xffff0000, v122
	v_lshlrev_b32_e32 v122, 16, v123
	v_and_b32_e32 v123, 0xffff0000, v123
	v_pk_fma_f32 v[114:115], v[114:115], v[116:117], v[120:121]
	v_pk_fma_f32 v[112:113], v[112:113], v[130:131], v[156:157]
	v_pk_fma_f32 v[116:117], v[110:111], v[118:119], v[122:123]
	v_pk_fma_f32 v[110:111], v[108:109], v[154:155], v[158:159]
	v_cvt_pk_bf16_f32 v108, v112, v113
	v_cvt_pk_bf16_f32 v109, v114, v115
	v_cvt_pk_bf16_f32 v110, v110, v111
	v_cvt_pk_bf16_f32 v111, v116, v117
	global_store_dwordx4 v[124:125], v[108:111], off
	s_nop 0
	v_or_b32_e32 v116, 32, v146
	v_ashrrev_i32_e32 v117, 31, v116
	v_mad_i64_i32 v[118:119], s[0:1], v116, s95, v[148:149]
	v_lshl_add_u64 v[118:119], v[118:119], 0, v[150:151]
	v_add_co_u32_e32 v120, vcc, s19, v118
	s_waitcnt vmcnt(4)
; #define GAS __attribute__((address_space(1)))
; __device__ __forceinline__ u32x4 pack8(f32x4 v0, f32x4 v1) { u32x4 w; w.x = cvt_pk_bf16(v0[0], v0[1]); w.y = cvt_pk_bf16(v0[2], v0[3]); w.z = cvt_pk_bf16(v1[0], v1[1]); w.w = cvt_pk_bf16(v1[2], v1[3]); return w; }
; __device__ __forceinline__ void unpack8(u32x4 w, f32x4& v0, f32x4& v1) { v0 = (f32x4){bflo(w.x), bfhi(w.x), bflo(w.y), bfhi(w.y)}; v1 = (f32x4){bflo(w.z), bfhi(w.z), bflo(w.w), bfhi(w.w)}; }
; #define GAS __attribute__((address_space(1)))
;     __device__ __forceinline__ void operator()(const f32x4 (&acc)[2][2][4][2], const Unit& u, int wr, int wc, int fr, int fq) const {
;     ...
;             for (int m = 0; m < 4; ++m) { const size_t r = (size_t)(row0 + ai * HALF + m * 16); const size_t off = r * 2048 + col0; const bf16_t* gp = P + r * NPJ + 2560 + MODE * 2048 + col0;
; #pragma unroll
;                 for (int bj = 0; bj < 2; ++bj) { f32x4 g0, g1; unpack8(*(const GAS u32x4*)(gp + bj * HALF), g0, g1);
;                     f32x4 v0 = g0 * acc[ai][bj][m][0], v1 = g1 * acc[ai][bj][m][1];
;                     if (MODE == 1) { f32x4 t0, t1; unpack8(*(const GAS u32x4*)(T1 + off + bj * HALF), t0, t1); v0 += t0; v1 += t1; }
;                     const u32x4 w = pack8(v0, v1);
;                     if (MODE == 0 && samp) asm volatile("global_store_dwordx4 %0, %1, off sc1\n\ts_nop 1" :: "v"(O + off + bj * HALF), "v"(w) : "memory");
;                     else *(GAS u32x4*)(O + off + bj * HALF) = w; } }
	s_nop 1
	v_mov_b32_e32 v108, v184
	v_mov_b32_e32 v109, v185
	v_mov_b32_e32 v110, v186
	v_mov_b32_e32 v111, v187
	v_lshlrev_b32_e32 v122, 16, v108
	v_and_b32_e32 v123, 0xffff0000, v108
	s_waitcnt vmcnt(3)
	s_nop 1
	v_mov_b32_e32 v112, v188
	v_mov_b32_e32 v113, v189
	v_mov_b32_e32 v114, v190
	v_mov_b32_e32 v115, v191
	v_lshlrev_b32_e32 v128, 16, v112
	v_and_b32_e32 v129, 0xffff0000, v112
	v_lshlrev_b32_e32 v108, 16, v109
	v_and_b32_e32 v109, 0xffff0000, v109
	v_lshlrev_b32_e32 v126, 16, v110
	v_and_b32_e32 v127, 0xffff0000, v110
	v_lshlrev_b32_e32 v110, 16, v111
	v_and_b32_e32 v111, 0xffff0000, v111
	v_lshlrev_b32_e32 v112, 16, v113
	v_and_b32_e32 v113, 0xffff0000, v113
	v_lshlrev_b32_e32 v130, 16, v114
	v_and_b32_e32 v131, 0xffff0000, v114
	v_lshlrev_b32_e32 v114, 16, v115
	v_and_b32_e32 v115, 0xffff0000, v115
	v_pk_fma_f32 v[104:105], v[104:105], v[122:123], v[128:129]
	v_pk_fma_f32 v[106:107], v[106:107], v[108:109], v[112:113]
	v_pk_fma_f32 v[108:109], v[102:103], v[110:111], v[114:115]
	v_pk_fma_f32 v[102:103], v[100:101], v[126:127], v[130:131]
	v_cvt_pk_bf16_f32 v100, v104, v105
	v_lshlrev_b64 v[104:105], 11, v[116:117]
	v_lshl_add_u64 v[104:105], v[104:105], 0, v[144:145]
	v_cvt_pk_bf16_f32 v101, v106, v107
	v_cvt_pk_bf16_f32 v102, v102, v103
	v_cvt_pk_bf16_f32 v103, v108, v109
	v_lshlrev_b64 v[108:109], 1, v[104:105]
	v_addc_co_u32_e32 v121, vcc, 0, v119, vcc
	global_store_dwordx4 v[124:125], v[100:103], off offset:256
	v_lshl_add_u64 v[110:111], s[10:11], 0, v[108:109]
	global_load_dwordx4 v[222:225], v[120:121], off offset:1024
	global_load_dwordx4 v[226:229], v[110:111], off
	global_load_dwordx4 v[230:233], v[120:121], off offset:1280
	global_load_dwordx4 v[234:237], v[110:111], off offset:256
	v_add_co_u32_e32 v192, vcc, 0x34000, v120
	s_nop 1
	v_addc_co_u32_e32 v193, vcc, 0, v121, vcc
	global_load_dwordx4 v[238:241], v[192:193], off offset:1024
	v_add_co_u32_e32 v194, vcc, 0x10000, v110
	s_nop 1
	v_addc_co_u32_e32 v195, vcc, 0, v111, vcc
	global_load_dwordx4 v[242:245], v[194:195], off
	global_load_dwordx4 v[184:187], v[192:193], off offset:1280
	global_load_dwordx4 v[188:191], v[194:195], off offset:256
	v_lshl_add_u64 v[112:113], v[118:119], 0, s[2:3]
	v_lshl_add_u64 v[108:109], s[14:15], 0, v[108:109]
	s_waitcnt vmcnt(7)
	s_nop 1
	v_mov_b32_e32 v100, v222
	v_mov_b32_e32 v101, v223
	v_mov_b32_e32 v102, v224
	v_mov_b32_e32 v103, v225
	v_lshlrev_b32_e32 v114, 16, v100
	v_and_b32_e32 v115, 0xffff0000, v100
	v_lshlrev_b32_e32 v100, 16, v101
	v_and_b32_e32 v101, 0xffff0000, v101
	v_lshlrev_b32_e32 v116, 16, v102
	v_and_b32_e32 v117, 0xffff0000, v102
	v_lshlrev_b32_e32 v102, 16, v103
	v_and_b32_e32 v103, 0xffff0000, v103
	s_waitcnt vmcnt(6)
	s_nop 1
	v_mov_b32_e32 v104, v226
	v_mov_b32_e32 v105, v227
	v_mov_b32_e32 v106, v228
	v_mov_b32_e32 v107, v229
	v_lshlrev_b32_e32 v118, 16, v104
	v_and_b32_e32 v119, 0xffff0000, v104
	v_lshlrev_b32_e32 v104, 16, v105
	v_and_b32_e32 v105, 0xffff0000, v105
	v_lshlrev_b32_e32 v120, 16, v106
	v_and_b32_e32 v121, 0xffff0000, v106
	v_lshlrev_b32_e32 v106, 16, v107
	v_and_b32_e32 v107, 0xffff0000, v107
	v_pk_fma_f32 v[96:97], v[96:97], v[100:101], v[104:105]
	v_pk_fma_f32 v[94:95], v[94:95], v[114:115], v[118:119]
	v_pk_fma_f32 v[100:101], v[92:93], v[102:103], v[106:107]
	v_pk_fma_f32 v[92:93], v[90:91], v[116:117], v[120:121]
	v_cvt_pk_bf16_f32 v90, v94, v95
	v_cvt_pk_bf16_f32 v91, v96, v97
	v_cvt_pk_bf16_f32 v92, v92, v93
	v_cvt_pk_bf16_f32 v93, v100, v101
	global_store_dwordx4 v[108:109], v[90:93], off
	s_nop 0
	v_or_b32_e32 v100, 48, v146
	v_ashrrev_i32_e32 v101, 31, v100
	v_mad_i64_i32 v[102:103], s[0:1], v100, s95, v[148:149]
	v_lshl_add_u64 v[102:103], v[102:103], 0, v[150:151]
	v_add_co_u32_e32 v104, vcc, s19, v102
	s_waitcnt vmcnt(6)
	s_nop 1
	v_mov_b32_e32 v90, v230
	v_mov_b32_e32 v91, v231
	v_mov_b32_e32 v92, v232
	v_mov_b32_e32 v93, v233
	v_lshlrev_b32_e32 v106, 16, v90
	v_and_b32_e32 v107, 0xffff0000, v90
	s_waitcnt vmcnt(5)
	s_nop 1
	v_mov_b32_e32 v94, v234
	v_mov_b32_e32 v95, v235
	v_mov_b32_e32 v96, v236
	v_mov_b32_e32 v97, v237
	v_lshlrev_b32_e32 v112, 16, v94
	v_and_b32_e32 v113, 0xffff0000, v94
	v_lshlrev_b32_e32 v90, 16, v91
	v_and_b32_e32 v91, 0xffff0000, v91
	v_lshlrev_b32_e32 v110, 16, v92
	v_and_b32_e32 v111, 0xffff0000, v92
	v_lshlrev_b32_e32 v92, 16, v93
	v_and_b32_e32 v93, 0xffff0000, v93
	v_lshlrev_b32_e32 v94, 16, v95
	v_and_b32_e32 v95, 0xffff0000, v95
	v_lshlrev_b32_e32 v114, 16, v96
	v_and_b32_e32 v115, 0xffff0000, v96
	v_lshlrev_b32_e32 v96, 16, v97
	v_and_b32_e32 v97, 0xffff0000, v97
	v_pk_fma_f32 v[86:87], v[86:87], v[106:107], v[112:113]
	v_pk_fma_f32 v[88:89], v[88:89], v[90:91], v[94:95]
	v_pk_fma_f32 v[90:91], v[84:85], v[92:93], v[96:97]
	v_pk_fma_f32 v[84:85], v[82:83], v[110:111], v[114:115]
	v_cvt_pk_bf16_f32 v82, v86, v87
	v_lshlrev_b64 v[86:87], 11, v[100:101]
	v_lshl_add_u64 v[86:87], v[86:87], 0, v[144:145]
	v_cvt_pk_bf16_f32 v83, v88, v89
	v_cvt_pk_bf16_f32 v84, v84, v85
	v_cvt_pk_bf16_f32 v85, v90, v91
	v_lshlrev_b64 v[90:91], 1, v[86:87]
	v_addc_co_u32_e32 v105, vcc, 0, v103, vcc
	global_store_dwordx4 v[108:109], v[82:85], off offset:256
	v_lshl_add_u64 v[92:93], s[10:11], 0, v[90:91]
	v_lshl_add_u64 v[94:95], v[102:103], 0, s[2:3]
	v_lshl_add_u64 v[90:91], s[14:15], 0, v[90:91]
	s_waitcnt vmcnt(5)
	s_nop 1
	v_mov_b32_e32 v82, v238
	v_mov_b32_e32 v83, v239
	v_mov_b32_e32 v84, v240
	v_mov_b32_e32 v85, v241
	v_lshlrev_b32_e32 v96, 16, v82
	v_and_b32_e32 v97, 0xffff0000, v82
	v_lshlrev_b32_e32 v82, 16, v83
	v_and_b32_e32 v83, 0xffff0000, v83
	v_lshlrev_b32_e32 v100, 16, v84
	v_and_b32_e32 v101, 0xffff0000, v84
	v_lshlrev_b32_e32 v84, 16, v85
	v_and_b32_e32 v85, 0xffff0000, v85
	s_waitcnt vmcnt(4)
; #define GAS __attribute__((address_space(1)))
; __device__ __forceinline__ u32x4 pack8(f32x4 v0, f32x4 v1) { u32x4 w; w.x = cvt_pk_bf16(v0[0], v0[1]); w.y = cvt_pk_bf16(v0[2], v0[3]); w.z = cvt_pk_bf16(v1[0], v1[1]); w.w = cvt_pk_bf16(v1[2], v1[3]); return w; }
; __device__ __forceinline__ void unpack8(u32x4 w, f32x4& v0, f32x4& v1) { v0 = (f32x4){bflo(w.x), bfhi(w.x), bflo(w.y), bfhi(w.y)}; v1 = (f32x4){bflo(w.z), bfhi(w.z), bflo(w.w), bfhi(w.w)}; }
; #define GAS __attribute__((address_space(1)))
;     __device__ __forceinline__ void operator()(const f32x4 (&acc)[2][2][4][2], const Unit& u, int wr, int wc, int fr, int fq) const {
;     ...
;             for (int m = 0; m < 4; ++m) { const size_t r = (size_t)(row0 + ai * HALF + m * 16); const size_t off = r * 2048 + col0; const bf16_t* gp = P + r * NPJ + 2560 + MODE * 2048 + col0;
; #pragma unroll
;                 for (int bj = 0; bj < 2; ++bj) { f32x4 g0, g1; unpack8(*(const GAS u32x4*)(gp + bj * HALF), g0, g1);
;                     f32x4 v0 = g0 * acc[ai][bj][m][0], v1 = g1 * acc[ai][bj][m][1];
;                     if (MODE == 1) { f32x4 t0, t1; unpack8(*(const GAS u32x4*)(T1 + off + bj * HALF), t0, t1); v0 += t0; v1 += t1; }
;                     const u32x4 w = pack8(v0, v1);
;                     if (MODE == 0 && samp) asm volatile("global_store_dwordx4 %0, %1, off sc1\n\ts_nop 1" :: "v"(O + off + bj * HALF), "v"(w) : "memory");
;                     else *(GAS u32x4*)(O + off + bj * HALF) = w; } }
	s_nop 1
	v_mov_b32_e32 v86, v242
	v_mov_b32_e32 v87, v243
	v_mov_b32_e32 v88, v244
	v_mov_b32_e32 v89, v245
	v_lshlrev_b32_e32 v102, 16, v86
	v_and_b32_e32 v103, 0xffff0000, v86
	v_lshlrev_b32_e32 v86, 16, v87
	v_and_b32_e32 v87, 0xffff0000, v87
	v_lshlrev_b32_e32 v104, 16, v88
	v_and_b32_e32 v105, 0xffff0000, v88
	v_lshlrev_b32_e32 v88, 16, v89
	v_and_b32_e32 v89, 0xffff0000, v89
	v_pk_fma_f32 v[80:81], v[80:81], v[82:83], v[86:87]
	v_pk_fma_f32 v[78:79], v[78:79], v[96:97], v[102:103]
	v_pk_fma_f32 v[82:83], v[76:77], v[84:85], v[88:89]
	v_pk_fma_f32 v[76:77], v[74:75], v[100:101], v[104:105]
	v_cvt_pk_bf16_f32 v74, v78, v79
	v_cvt_pk_bf16_f32 v75, v80, v81
	v_cvt_pk_bf16_f32 v76, v76, v77
	v_cvt_pk_bf16_f32 v77, v82, v83
	global_store_dwordx4 v[90:91], v[74:77], off
	s_nop 0
	v_add_u32_e32 v82, 0x80, v146
	v_ashrrev_i32_e32 v83, 31, v82
	v_mad_i64_i32 v[84:85], s[0:1], v82, s95, v[148:149]
	v_lshl_add_u64 v[84:85], v[84:85], 0, v[150:151]
	v_add_co_u32_e32 v86, vcc, s19, v84
	s_waitcnt vmcnt(4)
	s_nop 1
	v_mov_b32_e32 v74, v184
	v_mov_b32_e32 v75, v185
	v_mov_b32_e32 v76, v186
	v_mov_b32_e32 v77, v187
	v_lshlrev_b32_e32 v88, 16, v74
	v_and_b32_e32 v89, 0xffff0000, v74
	s_waitcnt vmcnt(3)
	s_nop 1
	v_mov_b32_e32 v78, v188
	v_mov_b32_e32 v79, v189
	v_mov_b32_e32 v80, v190
	v_mov_b32_e32 v81, v191
	v_lshlrev_b32_e32 v94, 16, v78
	v_and_b32_e32 v95, 0xffff0000, v78
	v_lshlrev_b32_e32 v74, 16, v75
	v_and_b32_e32 v75, 0xffff0000, v75
	v_lshlrev_b32_e32 v92, 16, v76
	v_and_b32_e32 v93, 0xffff0000, v76
	v_lshlrev_b32_e32 v76, 16, v77
	v_and_b32_e32 v77, 0xffff0000, v77
	v_lshlrev_b32_e32 v78, 16, v79
	v_and_b32_e32 v79, 0xffff0000, v79
	v_lshlrev_b32_e32 v96, 16, v80
	v_and_b32_e32 v97, 0xffff0000, v80
	v_lshlrev_b32_e32 v80, 16, v81
	v_and_b32_e32 v81, 0xffff0000, v81
	v_pk_fma_f32 v[70:71], v[70:71], v[88:89], v[94:95]
	v_pk_fma_f32 v[72:73], v[72:73], v[74:75], v[78:79]
	v_pk_fma_f32 v[74:75], v[68:69], v[76:77], v[80:81]
	v_pk_fma_f32 v[68:69], v[66:67], v[92:93], v[96:97]
	v_cvt_pk_bf16_f32 v66, v70, v71
	v_lshlrev_b64 v[70:71], 11, v[82:83]
	v_lshl_add_u64 v[70:71], v[70:71], 0, v[144:145]
	v_cvt_pk_bf16_f32 v67, v72, v73
	v_cvt_pk_bf16_f32 v68, v68, v69
	v_cvt_pk_bf16_f32 v69, v74, v75
	v_lshlrev_b64 v[74:75], 1, v[70:71]
	v_addc_co_u32_e32 v87, vcc, 0, v85, vcc
	global_store_dwordx4 v[90:91], v[66:69], off offset:256
	v_lshl_add_u64 v[76:77], s[10:11], 0, v[74:75]
	global_load_dwordx4 v[222:225], v[86:87], off offset:1024
	global_load_dwordx4 v[226:229], v[76:77], off
	global_load_dwordx4 v[230:233], v[86:87], off offset:1280
	global_load_dwordx4 v[234:237], v[76:77], off offset:256
	v_add_co_u32_e32 v192, vcc, 0x34000, v86
	s_nop 1
	v_addc_co_u32_e32 v193, vcc, 0, v87, vcc
	global_load_dwordx4 v[238:241], v[192:193], off offset:1024
	v_add_co_u32_e32 v194, vcc, 0x10000, v76
	s_nop 1
	v_addc_co_u32_e32 v195, vcc, 0, v77, vcc
	global_load_dwordx4 v[242:245], v[194:195], off
	global_load_dwordx4 v[184:187], v[192:193], off offset:1280
	global_load_dwordx4 v[188:191], v[194:195], off offset:256
	v_lshl_add_u64 v[78:79], v[84:85], 0, s[2:3]
	v_lshl_add_u64 v[74:75], s[14:15], 0, v[74:75]
	s_waitcnt vmcnt(7)
	s_nop 1
	v_mov_b32_e32 v66, v222
	v_mov_b32_e32 v67, v223
	v_mov_b32_e32 v68, v224
	v_mov_b32_e32 v69, v225
	v_lshlrev_b32_e32 v80, 16, v66
	v_and_b32_e32 v81, 0xffff0000, v66
	v_lshlrev_b32_e32 v66, 16, v67
	v_and_b32_e32 v67, 0xffff0000, v67
	v_lshlrev_b32_e32 v82, 16, v68
	v_and_b32_e32 v83, 0xffff0000, v68
	v_lshlrev_b32_e32 v68, 16, v69
	v_and_b32_e32 v69, 0xffff0000, v69
	s_waitcnt vmcnt(6)
	s_nop 1
	v_mov_b32_e32 v70, v226
	v_mov_b32_e32 v71, v227
	v_mov_b32_e32 v72, v228
	v_mov_b32_e32 v73, v229
	v_lshlrev_b32_e32 v84, 16, v70
	v_and_b32_e32 v85, 0xffff0000, v70
	v_lshlrev_b32_e32 v70, 16, v71
	v_and_b32_e32 v71, 0xffff0000, v71
	v_lshlrev_b32_e32 v86, 16, v72
	v_and_b32_e32 v87, 0xffff0000, v72
	v_lshlrev_b32_e32 v72, 16, v73
	v_and_b32_e32 v73, 0xffff0000, v73
	v_pk_fma_f32 v[64:65], v[64:65], v[66:67], v[70:71]
	v_pk_fma_f32 v[62:63], v[62:63], v[80:81], v[84:85]
	v_pk_fma_f32 v[66:67], v[60:61], v[68:69], v[72:73]
	v_pk_fma_f32 v[60:61], v[58:59], v[82:83], v[86:87]
	v_cvt_pk_bf16_f32 v58, v62, v63
	v_cvt_pk_bf16_f32 v59, v64, v65
	v_cvt_pk_bf16_f32 v60, v60, v61
	v_cvt_pk_bf16_f32 v61, v66, v67
	global_store_dwordx4 v[74:75], v[58:61], off
	s_nop 0
	v_add_u32_e32 v66, 0x90, v146
	v_ashrrev_i32_e32 v67, 31, v66
	v_mad_i64_i32 v[68:69], s[0:1], v66, s95, v[148:149]
	v_lshl_add_u64 v[68:69], v[68:69], 0, v[150:151]
	v_add_co_u32_e32 v70, vcc, s19, v68
	s_waitcnt vmcnt(6)
	s_nop 1
	v_mov_b32_e32 v58, v230
	v_mov_b32_e32 v59, v231
	v_mov_b32_e32 v60, v232
	v_mov_b32_e32 v61, v233
	v_lshlrev_b32_e32 v72, 16, v58
	v_and_b32_e32 v73, 0xffff0000, v58
	s_waitcnt vmcnt(5)
	s_nop 1
	v_mov_b32_e32 v62, v234
	v_mov_b32_e32 v63, v235
	v_mov_b32_e32 v64, v236
	v_mov_b32_e32 v65, v237
	v_lshlrev_b32_e32 v78, 16, v62
	v_and_b32_e32 v79, 0xffff0000, v62
	v_lshlrev_b32_e32 v58, 16, v59
	v_and_b32_e32 v59, 0xffff0000, v59
	v_lshlrev_b32_e32 v76, 16, v60
	v_and_b32_e32 v77, 0xffff0000, v60
	v_lshlrev_b32_e32 v60, 16, v61
	v_and_b32_e32 v61, 0xffff0000, v61
	v_lshlrev_b32_e32 v62, 16, v63
	v_and_b32_e32 v63, 0xffff0000, v63
	v_lshlrev_b32_e32 v80, 16, v64
	v_and_b32_e32 v81, 0xffff0000, v64
	v_lshlrev_b32_e32 v64, 16, v65
	v_and_b32_e32 v65, 0xffff0000, v65
	v_pk_fma_f32 v[54:55], v[54:55], v[72:73], v[78:79]
	v_pk_fma_f32 v[56:57], v[56:57], v[58:59], v[62:63]
	v_pk_fma_f32 v[58:59], v[52:53], v[60:61], v[64:65]
	v_pk_fma_f32 v[52:53], v[50:51], v[76:77], v[80:81]
	v_cvt_pk_bf16_f32 v50, v54, v55
	v_lshlrev_b64 v[54:55], 11, v[66:67]
	v_lshl_add_u64 v[54:55], v[54:55], 0, v[144:145]
	v_cvt_pk_bf16_f32 v51, v56, v57
	v_cvt_pk_bf16_f32 v52, v52, v53
	v_cvt_pk_bf16_f32 v53, v58, v59
	v_lshlrev_b64 v[58:59], 1, v[54:55]
	v_addc_co_u32_e32 v71, vcc, 0, v69, vcc
	global_store_dwordx4 v[74:75], v[50:53], off offset:256
	v_lshl_add_u64 v[60:61], s[10:11], 0, v[58:59]
	v_lshl_add_u64 v[62:63], v[68:69], 0, s[2:3]
	v_lshl_add_u64 v[58:59], s[14:15], 0, v[58:59]
	s_waitcnt vmcnt(5)
; #define GAS __attribute__((address_space(1)))
; __device__ __forceinline__ u32x4 pack8(f32x4 v0, f32x4 v1) { u32x4 w; w.x = cvt_pk_bf16(v0[0], v0[1]); w.y = cvt_pk_bf16(v0[2], v0[3]); w.z = cvt_pk_bf16(v1[0], v1[1]); w.w = cvt_pk_bf16(v1[2], v1[3]); return w; }
; __device__ __forceinline__ void unpack8(u32x4 w, f32x4& v0, f32x4& v1) { v0 = (f32x4){bflo(w.x), bfhi(w.x), bflo(w.y), bfhi(w.y)}; v1 = (f32x4){bflo(w.z), bfhi(w.z), bflo(w.w), bfhi(w.w)}; }
; #define GAS __attribute__((address_space(1)))
;     __device__ __forceinline__ void operator()(const f32x4 (&acc)[2][2][4][2], const Unit& u, int wr, int wc, int fr, int fq) const {
;     ...
;             for (int m = 0; m < 4; ++m) { const size_t r = (size_t)(row0 + ai * HALF + m * 16); const size_t off = r * 2048 + col0; const bf16_t* gp = P + r * NPJ + 2560 + MODE * 2048 + col0;
; #pragma unroll
;                 for (int bj = 0; bj < 2; ++bj) { f32x4 g0, g1; unpack8(*(const GAS u32x4*)(gp + bj * HALF), g0, g1);
;                     f32x4 v0 = g0 * acc[ai][bj][m][0], v1 = g1 * acc[ai][bj][m][1];
;                     if (MODE == 1) { f32x4 t0, t1; unpack8(*(const GAS u32x4*)(T1 + off + bj * HALF), t0, t1); v0 += t0; v1 += t1; }
;                     const u32x4 w = pack8(v0, v1);
;                     if (MODE == 0 && samp) asm volatile("global_store_dwordx4 %0, %1, off sc1\n\ts_nop 1" :: "v"(O + off + bj * HALF), "v"(w) : "memory");
;                     else *(GAS u32x4*)(O + off + bj * HALF) = w; } }
	s_nop 1
	v_mov_b32_e32 v50, v238
	v_mov_b32_e32 v51, v239
	v_mov_b32_e32 v52, v240
	v_mov_b32_e32 v53, v241
	v_lshlrev_b32_e32 v64, 16, v50
	v_and_b32_e32 v65, 0xffff0000, v50
	v_lshlrev_b32_e32 v50, 16, v51
	v_and_b32_e32 v51, 0xffff0000, v51
	v_lshlrev_b32_e32 v66, 16, v52
	v_and_b32_e32 v67, 0xffff0000, v52
	v_lshlrev_b32_e32 v52, 16, v53
	v_and_b32_e32 v53, 0xffff0000, v53
	s_waitcnt vmcnt(4)
	s_nop 1
	v_mov_b32_e32 v54, v242
	v_mov_b32_e32 v55, v243
	v_mov_b32_e32 v56, v244
	v_mov_b32_e32 v57, v245
	v_lshlrev_b32_e32 v68, 16, v54
	v_and_b32_e32 v69, 0xffff0000, v54
	v_lshlrev_b32_e32 v54, 16, v55
	v_and_b32_e32 v55, 0xffff0000, v55
	v_lshlrev_b32_e32 v70, 16, v56
	v_and_b32_e32 v71, 0xffff0000, v56
	v_lshlrev_b32_e32 v56, 16, v57
	v_and_b32_e32 v57, 0xffff0000, v57
	v_pk_fma_f32 v[48:49], v[48:49], v[50:51], v[54:55]
	v_pk_fma_f32 v[46:47], v[46:47], v[64:65], v[68:69]
	v_pk_fma_f32 v[50:51], v[44:45], v[52:53], v[56:57]
	v_pk_fma_f32 v[44:45], v[42:43], v[66:67], v[70:71]
	v_cvt_pk_bf16_f32 v42, v46, v47
	v_cvt_pk_bf16_f32 v43, v48, v49
	v_cvt_pk_bf16_f32 v44, v44, v45
	v_cvt_pk_bf16_f32 v45, v50, v51
	global_store_dwordx4 v[58:59], v[42:45], off
	s_nop 0
	v_add_u32_e32 v50, 0xa0, v146
	v_ashrrev_i32_e32 v51, 31, v50
	v_mad_i64_i32 v[52:53], s[0:1], v50, s95, v[148:149]
	v_lshl_add_u64 v[52:53], v[52:53], 0, v[150:151]
	v_add_co_u32_e32 v54, vcc, s19, v52
	s_waitcnt vmcnt(4)
	s_nop 1
	v_mov_b32_e32 v42, v184
	v_mov_b32_e32 v43, v185
	v_mov_b32_e32 v44, v186
	v_mov_b32_e32 v45, v187
	v_lshlrev_b32_e32 v56, 16, v42
	v_and_b32_e32 v57, 0xffff0000, v42
	s_waitcnt vmcnt(3)
	s_nop 1
	v_mov_b32_e32 v46, v188
	v_mov_b32_e32 v47, v189
	v_mov_b32_e32 v48, v190
	v_mov_b32_e32 v49, v191
	v_lshlrev_b32_e32 v62, 16, v46
	v_and_b32_e32 v63, 0xffff0000, v46
	v_lshlrev_b32_e32 v42, 16, v43
	v_and_b32_e32 v43, 0xffff0000, v43
	v_lshlrev_b32_e32 v60, 16, v44
	v_and_b32_e32 v61, 0xffff0000, v44
	v_lshlrev_b32_e32 v44, 16, v45
	v_and_b32_e32 v45, 0xffff0000, v45
	v_lshlrev_b32_e32 v46, 16, v47
	v_and_b32_e32 v47, 0xffff0000, v47
	v_lshlrev_b32_e32 v64, 16, v48
	v_and_b32_e32 v65, 0xffff0000, v48
	v_lshlrev_b32_e32 v48, 16, v49
	v_and_b32_e32 v49, 0xffff0000, v49
	v_pk_fma_f32 v[38:39], v[38:39], v[56:57], v[62:63]
	v_pk_fma_f32 v[40:41], v[40:41], v[42:43], v[46:47]
	v_pk_fma_f32 v[42:43], v[36:37], v[44:45], v[48:49]
	v_pk_fma_f32 v[36:37], v[34:35], v[60:61], v[64:65]
	v_cvt_pk_bf16_f32 v34, v38, v39
	v_lshlrev_b64 v[38:39], 11, v[50:51]
	v_lshl_add_u64 v[38:39], v[38:39], 0, v[144:145]
	v_cvt_pk_bf16_f32 v35, v40, v41
	v_cvt_pk_bf16_f32 v36, v36, v37
	v_cvt_pk_bf16_f32 v37, v42, v43
	v_lshlrev_b64 v[42:43], 1, v[38:39]
	v_addc_co_u32_e32 v55, vcc, 0, v53, vcc
	global_store_dwordx4 v[58:59], v[34:37], off offset:256
	v_lshl_add_u64 v[44:45], s[10:11], 0, v[42:43]
	global_load_dwordx4 v[222:225], v[54:55], off offset:1024
	global_load_dwordx4 v[226:229], v[44:45], off
	global_load_dwordx4 v[230:233], v[54:55], off offset:1280
	global_load_dwordx4 v[234:237], v[44:45], off offset:256
	v_add_co_u32_e32 v192, vcc, 0x34000, v54
	s_nop 1
	v_addc_co_u32_e32 v193, vcc, 0, v55, vcc
	global_load_dwordx4 v[238:241], v[192:193], off offset:1024
	v_add_co_u32_e32 v194, vcc, 0x10000, v44
	s_nop 1
	v_addc_co_u32_e32 v195, vcc, 0, v45, vcc
	global_load_dwordx4 v[242:245], v[194:195], off
	global_load_dwordx4 v[184:187], v[192:193], off offset:1280
	global_load_dwordx4 v[188:191], v[194:195], off offset:256
	v_lshl_add_u64 v[46:47], v[52:53], 0, s[2:3]
	v_lshl_add_u64 v[42:43], s[14:15], 0, v[42:43]
	s_waitcnt vmcnt(7)
	s_nop 1
	v_mov_b32_e32 v34, v222
	v_mov_b32_e32 v35, v223
	v_mov_b32_e32 v36, v224
	v_mov_b32_e32 v37, v225
	v_lshlrev_b32_e32 v48, 16, v34
	v_and_b32_e32 v49, 0xffff0000, v34
	v_lshlrev_b32_e32 v34, 16, v35
	v_and_b32_e32 v35, 0xffff0000, v35
	v_lshlrev_b32_e32 v50, 16, v36
	v_and_b32_e32 v51, 0xffff0000, v36
	v_lshlrev_b32_e32 v36, 16, v37
	v_and_b32_e32 v37, 0xffff0000, v37
	s_waitcnt vmcnt(6)
	s_nop 1
	v_mov_b32_e32 v38, v226
	v_mov_b32_e32 v39, v227
	v_mov_b32_e32 v40, v228
	v_mov_b32_e32 v41, v229
	v_lshlrev_b32_e32 v52, 16, v38
	v_and_b32_e32 v53, 0xffff0000, v38
	v_lshlrev_b32_e32 v38, 16, v39
	v_and_b32_e32 v39, 0xffff0000, v39
	v_lshlrev_b32_e32 v54, 16, v40
	v_and_b32_e32 v55, 0xffff0000, v40
	v_lshlrev_b32_e32 v40, 16, v41
	v_and_b32_e32 v41, 0xffff0000, v41
	v_pk_fma_f32 v[32:33], v[32:33], v[34:35], v[38:39]
	v_pk_fma_f32 v[30:31], v[30:31], v[48:49], v[52:53]
	v_pk_fma_f32 v[34:35], v[28:29], v[36:37], v[40:41]
	v_pk_fma_f32 v[28:29], v[26:27], v[50:51], v[54:55]
	v_cvt_pk_bf16_f32 v26, v30, v31
	v_cvt_pk_bf16_f32 v27, v32, v33
	v_cvt_pk_bf16_f32 v28, v28, v29
	v_cvt_pk_bf16_f32 v29, v34, v35
	global_store_dwordx4 v[42:43], v[26:29], off
	s_nop 0
	v_add_u32_e32 v34, 0xb0, v146
	v_ashrrev_i32_e32 v35, 31, v34
	v_mad_i64_i32 v[36:37], s[0:1], v34, s95, v[148:149]
	v_lshl_add_u64 v[36:37], v[36:37], 0, v[150:151]
	v_add_co_u32_e32 v38, vcc, s19, v36
	s_waitcnt vmcnt(6)
; #define GAS __attribute__((address_space(1)))
; __device__ __forceinline__ u32x4 pack8(f32x4 v0, f32x4 v1) { u32x4 w; w.x = cvt_pk_bf16(v0[0], v0[1]); w.y = cvt_pk_bf16(v0[2], v0[3]); w.z = cvt_pk_bf16(v1[0], v1[1]); w.w = cvt_pk_bf16(v1[2], v1[3]); return w; }
; __device__ __forceinline__ void unpack8(u32x4 w, f32x4& v0, f32x4& v1) { v0 = (f32x4){bflo(w.x), bfhi(w.x), bflo(w.y), bfhi(w.y)}; v1 = (f32x4){bflo(w.z), bfhi(w.z), bflo(w.w), bfhi(w.w)}; }
; #define GAS __attribute__((address_space(1)))
;     __device__ __forceinline__ void operator()(const f32x4 (&acc)[2][2][4][2], const Unit& u, int wr, int wc, int fr, int fq) const {
;     ...
;             for (int m = 0; m < 4; ++m) { const size_t r = (size_t)(row0 + ai * HALF + m * 16); const size_t off = r * 2048 + col0; const bf16_t* gp = P + r * NPJ + 2560 + MODE * 2048 + col0;
; #pragma unroll
;                 for (int bj = 0; bj < 2; ++bj) { f32x4 g0, g1; unpack8(*(const GAS u32x4*)(gp + bj * HALF), g0, g1);
;                     f32x4 v0 = g0 * acc[ai][bj][m][0], v1 = g1 * acc[ai][bj][m][1];
;                     if (MODE == 1) { f32x4 t0, t1; unpack8(*(const GAS u32x4*)(T1 + off + bj * HALF), t0, t1); v0 += t0; v1 += t1; }
;                     const u32x4 w = pack8(v0, v1);
;                     if (MODE == 0 && samp) asm volatile("global_store_dwordx4 %0, %1, off sc1\n\ts_nop 1" :: "v"(O + off + bj * HALF), "v"(w) : "memory");
;                     else *(GAS u32x4*)(O + off + bj * HALF) = w; } }
	s_nop 1
	v_mov_b32_e32 v26, v230
	v_mov_b32_e32 v27, v231
	v_mov_b32_e32 v28, v232
	v_mov_b32_e32 v29, v233
	v_lshlrev_b32_e32 v40, 16, v26
	v_and_b32_e32 v41, 0xffff0000, v26
	s_waitcnt vmcnt(5)
	s_nop 1
	v_mov_b32_e32 v30, v234
	v_mov_b32_e32 v31, v235
	v_mov_b32_e32 v32, v236
	v_mov_b32_e32 v33, v237
	v_lshlrev_b32_e32 v46, 16, v30
	v_and_b32_e32 v47, 0xffff0000, v30
	v_lshlrev_b32_e32 v26, 16, v27
	v_and_b32_e32 v27, 0xffff0000, v27
	v_lshlrev_b32_e32 v44, 16, v28
	v_and_b32_e32 v45, 0xffff0000, v28
	v_lshlrev_b32_e32 v28, 16, v29
	v_and_b32_e32 v29, 0xffff0000, v29
	v_lshlrev_b32_e32 v30, 16, v31
	v_and_b32_e32 v31, 0xffff0000, v31
	v_lshlrev_b32_e32 v48, 16, v32
	v_and_b32_e32 v49, 0xffff0000, v32
	v_lshlrev_b32_e32 v32, 16, v33
	v_and_b32_e32 v33, 0xffff0000, v33
	v_pk_fma_f32 v[22:23], v[22:23], v[40:41], v[46:47]
	v_pk_fma_f32 v[24:25], v[24:25], v[26:27], v[30:31]
	v_pk_fma_f32 v[26:27], v[20:21], v[28:29], v[32:33]
	v_pk_fma_f32 v[20:21], v[18:19], v[44:45], v[48:49]
	v_cvt_pk_bf16_f32 v18, v22, v23
	v_lshlrev_b64 v[22:23], 11, v[34:35]
	v_lshl_add_u64 v[22:23], v[22:23], 0, v[144:145]
	v_cvt_pk_bf16_f32 v19, v24, v25
	v_cvt_pk_bf16_f32 v20, v20, v21
	v_cvt_pk_bf16_f32 v21, v26, v27
	v_lshlrev_b64 v[26:27], 1, v[22:23]
	v_addc_co_u32_e32 v39, vcc, 0, v37, vcc
	global_store_dwordx4 v[42:43], v[18:21], off offset:256
	v_lshl_add_u64 v[28:29], s[10:11], 0, v[26:27]
	v_lshl_add_u64 v[30:31], v[36:37], 0, s[2:3]
	v_lshl_add_u64 v[26:27], s[14:15], 0, v[26:27]
	s_andn2_b64 vcc, exec, s[42:43]
	s_mov_b64 s[42:43], -1
	s_waitcnt vmcnt(5)
	s_nop 1
	v_mov_b32_e32 v18, v238
	v_mov_b32_e32 v19, v239
	v_mov_b32_e32 v20, v240
	v_mov_b32_e32 v21, v241
	v_lshlrev_b32_e32 v32, 16, v18
	v_and_b32_e32 v33, 0xffff0000, v18
	v_lshlrev_b32_e32 v18, 16, v19
	v_and_b32_e32 v19, 0xffff0000, v19
	v_lshlrev_b32_e32 v34, 16, v20
	v_and_b32_e32 v35, 0xffff0000, v20
	v_lshlrev_b32_e32 v20, 16, v21
	v_and_b32_e32 v21, 0xffff0000, v21
	s_waitcnt vmcnt(4)
	s_nop 1
	v_mov_b32_e32 v22, v242
	v_mov_b32_e32 v23, v243
	v_mov_b32_e32 v24, v244
	v_mov_b32_e32 v25, v245
	v_lshlrev_b32_e32 v36, 16, v22
	v_and_b32_e32 v37, 0xffff0000, v22
	v_lshlrev_b32_e32 v22, 16, v23
	v_and_b32_e32 v23, 0xffff0000, v23
	v_lshlrev_b32_e32 v38, 16, v24
	v_and_b32_e32 v39, 0xffff0000, v24
	v_lshlrev_b32_e32 v24, 16, v25
	v_and_b32_e32 v25, 0xffff0000, v25
	v_pk_fma_f32 v[16:17], v[16:17], v[18:19], v[22:23]
	v_pk_fma_f32 v[14:15], v[14:15], v[32:33], v[36:37]
	v_pk_fma_f32 v[18:19], v[12:13], v[20:21], v[24:25]
	v_pk_fma_f32 v[12:13], v[10:11], v[34:35], v[38:39]
	v_cvt_pk_bf16_f32 v10, v14, v15
	v_cvt_pk_bf16_f32 v11, v16, v17
	v_cvt_pk_bf16_f32 v12, v12, v13
	v_cvt_pk_bf16_f32 v13, v18, v19
	global_store_dwordx4 v[26:27], v[10:13], off
	s_nop 0
	s_waitcnt vmcnt(4)
	s_nop 1
	v_mov_b32_e32 v10, v184
	v_mov_b32_e32 v11, v185
	v_mov_b32_e32 v12, v186
	v_mov_b32_e32 v13, v187
	v_lshlrev_b32_e32 v18, 16, v10
	v_and_b32_e32 v19, 0xffff0000, v10
	v_lshlrev_b32_e32 v10, 16, v11
	v_and_b32_e32 v11, 0xffff0000, v11
	v_lshlrev_b32_e32 v20, 16, v12
	v_and_b32_e32 v21, 0xffff0000, v12
	v_lshlrev_b32_e32 v12, 16, v13
	v_and_b32_e32 v13, 0xffff0000, v13
	s_waitcnt vmcnt(3)
	s_nop 1
	v_mov_b32_e32 v14, v188
	v_mov_b32_e32 v15, v189
	v_mov_b32_e32 v16, v190
	v_mov_b32_e32 v17, v191
	v_lshlrev_b32_e32 v22, 16, v14
	v_and_b32_e32 v23, 0xffff0000, v14
	v_lshlrev_b32_e32 v14, 16, v15
	v_and_b32_e32 v15, 0xffff0000, v15
	v_lshlrev_b32_e32 v24, 16, v16
	v_and_b32_e32 v25, 0xffff0000, v16
	v_lshlrev_b32_e32 v16, 16, v17
	v_and_b32_e32 v17, 0xffff0000, v17
	v_pk_fma_f32 v[8:9], v[8:9], v[10:11], v[14:15]
	v_pk_fma_f32 v[6:7], v[6:7], v[18:19], v[22:23]
	v_pk_fma_f32 v[10:11], v[4:5], v[12:13], v[16:17]
	v_pk_fma_f32 v[4:5], v[2:3], v[20:21], v[24:25]
	v_cvt_pk_bf16_f32 v2, v6, v7
	v_cvt_pk_bf16_f32 v3, v8, v9
	v_cvt_pk_bf16_f32 v4, v4, v5
	v_cvt_pk_bf16_f32 v5, v10, v11
	global_store_dwordx4 v[26:27], v[2:5], off offset:256
	s_cbranch_vccnz .LBB0_1148
	s_andn2_b64 vcc, exec, s[12:13]
	s_cbranch_vccnz .LBB0_1147
	s_barrier
	s_branch .LBB0_1147

; #define GAS __attribute__((address_space(1)))
; __device__ __forceinline__ u32x4 pack8(f32x4 v0, f32x4 v1) { u32x4 w; w.x = cvt_pk_bf16(v0[0], v0[1]); w.y = cvt_pk_bf16(v0[2], v0[3]); w.z = cvt_pk_bf16(v1[0], v1[1]); w.w = cvt_pk_bf16(v1[2], v1[3]); return w; }
; __device__ __forceinline__ void unpack8(u32x4 w, f32x4& v0, f32x4& v1) { v0 = (f32x4){bflo(w.x), bfhi(w.x), bflo(w.y), bfhi(w.y)}; v1 = (f32x4){bflo(w.z), bfhi(w.z), bflo(w.w), bfhi(w.w)}; }
; #define GAS __attribute__((address_space(1)))
;     __device__ __forceinline__ void operator()(const f32x4 (&acc)[2][2][4][2], const Unit& u, int wr, int wc, int fr, int fq) const {
;     ...
;         for (int ai = 0; ai < 2; ++ai) {
;             const int rb = u.pm * BM + ai * HALF + wr * 64;
;             const int cb = rb < 8192 ? (rb >> 11) : 4 + ((rb - 8192) >> 6);
;             const float* g = gmod + (size_t)cb * 12288 + col0;
;             f32x4 gv[2][2];
; #pragma unroll
;             for (int bj = 0; bj < 2; ++bj)
; #pragma unroll
;                 for (int n = 0; n < 2; ++n) gv[bj][n] = *(const GAS f32x4*)(g + bj * HALF + 4 * n);
;             if (part) { bf16_t* base = SL + ((size_t)u.slab * 1024 + (size_t)(rb - 8192 + fr)) * 2048 + col0;
; #pragma unroll
;                 for (int m = 0; m < 4; ++m)
; #pragma unroll
;                     for (int bj = 0; bj < 2; ++bj) *(GAS u32x4*)(base + (size_t)(m * 16) * 2048 + bj * HALF) = pack8(gv[bj][0] * acc[ai][bj][m][0], gv[bj][1] * acc[ai][bj][m][1]);
;             } else { const size_t o0 = (size_t)(rb + fr) * 2048 + col0;
; #pragma unroll
;                 for (int m = 0; m < 4; ++m)
; #pragma unroll
;                     for (int bj = 0; bj < 2; ++bj) { const size_t o = o0 + (size_t)(m * 16) * 2048 + bj * HALF; f32x4 x0, x1; unpack8(*(const GAS u32x4*)(XB + o), x0, x1);
;                         const f32x4 v0 = x0 + gv[bj][0] * acc[ai][bj][m][0], v1 = x1 + gv[bj][1] * acc[ai][bj][m][1];
;                         if (OUTF != nullptr) { *(GAS f32x4*)(OUTF + o) = v0; *(GAS f32x4*)(OUTF + o + 4) = v1; } else *(GAS u32x4*)(XB + o) = pack8(v0, v1); }
.LBB0_1311:
	s_cmp_lt_i32 s78, 0
	s_cselect_b64 s[34:35], -1, 0
	s_lshl_b32 s11, s69, 8
	s_add_i32 s11, s11, s58
	s_add_i32 s13, s11, 0xffffe000
	s_lshr_b32 s1, s13, 6
	s_ashr_i32 s0, s11, 11
	s_add_i32 s1, s1, 4
	s_cmpk_lt_i32 s11, 0x2000
	s_cselect_b32 s0, s0, s1
	s_mul_hi_i32 s1, s0, 0xc000
	s_mul_i32 s0, s0, 0xc000
	v_lshl_or_b32 v164, s70, 8, v180
	s_add_u32 s0, s54, s0
	v_ashrrev_i32_e32 v165, 31, v164
	s_addc_u32 s1, s55, s1
	v_lshl_add_u64 v[136:137], v[164:165], 2, s[0:1]
	global_load_dwordx4 v[140:143], v[136:137], off offset:16
	global_load_dwordx4 v[144:147], v[136:137], off
	global_load_dwordx4 v[132:135], v[136:137], off offset:528
	s_nop 0
	global_load_dwordx4 v[136:139], v[136:137], off offset:512
	s_mov_b64 s[36:37], -1
	s_and_b64 vcc, exec, s[34:35]
	s_cbranch_vccz .LBB0_1313
	v_or_b32_e32 v148, s11, v1
	v_ashrrev_i32_e32 v149, 31, v148
	v_lshlrev_b64 v[148:149], 12, v[148:149]
	v_lshl_add_u64 v[148:149], s[6:7], 0, v[148:149]
	v_lshl_add_u64 v[148:149], v[164:165], 1, v[148:149]
	global_load_dwordx4 v[222:225], v[148:149], off
	global_load_dwordx4 v[226:229], v[148:149], off offset:256
	v_add_co_u32_e32 v188, vcc, s73, v148
	s_nop 1
	v_addc_co_u32_e32 v189, vcc, 0, v149, vcc
	global_load_dwordx4 v[230:233], v[188:189], off
	global_load_dwordx4 v[234:237], v[188:189], off offset:256
	v_add_co_u32_e32 v188, vcc, s3, v148
	s_nop 1
	v_addc_co_u32_e32 v189, vcc, 0, v149, vcc
	global_load_dwordx4 v[238:241], v[188:189], off
	global_load_dwordx4 v[242:245], v[188:189], off offset:256
	v_add_co_u32_e32 v188, vcc, s46, v148
	s_nop 1
	v_addc_co_u32_e32 v189, vcc, 0, v149, vcc
	global_load_dwordx4 v[194:197], v[188:189], off
	global_load_dwordx4 v[198:201], v[188:189], off offset:256
	s_mov_b64 s[36:37], 0
	s_waitcnt vmcnt(7)
	s_nop 1
	v_mov_b32_e32 v182, v222
	v_mov_b32_e32 v183, v223
	v_mov_b32_e32 v184, v224
	v_mov_b32_e32 v185, v225
	v_lshlrev_b32_e32 v150, 16, v182
	v_and_b32_e32 v151, 0xffff0000, v182
	v_lshlrev_b32_e32 v166, 16, v183
	v_and_b32_e32 v167, 0xffff0000, v183
	v_lshlrev_b32_e32 v168, 16, v184
	v_and_b32_e32 v169, 0xffff0000, v184
	v_lshlrev_b32_e32 v172, 16, v185
	v_and_b32_e32 v173, 0xffff0000, v185
	v_pk_fma_f32 v[166:167], v[130:131], v[146:147], v[166:167]
	v_pk_fma_f32 v[150:151], v[128:129], v[144:145], v[150:151]
	v_pk_fma_f32 v[172:173], v[126:127], v[142:143], v[172:173]
	v_pk_fma_f32 v[168:169], v[124:125], v[140:141], v[168:169]
	v_cvt_pk_bf16_f32 v182, v150, v151
	v_cvt_pk_bf16_f32 v183, v166, v167
	v_cvt_pk_bf16_f32 v184, v168, v169
	v_cvt_pk_bf16_f32 v185, v172, v173
	global_store_dwordx4 v[148:149], v[182:185], off
	s_waitcnt vmcnt(7)
	s_nop 1
	v_mov_b32_e32 v182, v226
	v_mov_b32_e32 v183, v227
	v_mov_b32_e32 v184, v228
	v_mov_b32_e32 v185, v229
	v_lshlrev_b32_e32 v150, 16, v182
	v_and_b32_e32 v151, 0xffff0000, v182
	v_lshlrev_b32_e32 v166, 16, v183
	v_and_b32_e32 v167, 0xffff0000, v183
	v_lshlrev_b32_e32 v168, 16, v184
	v_and_b32_e32 v169, 0xffff0000, v184
	v_lshlrev_b32_e32 v172, 16, v185
	v_and_b32_e32 v173, 0xffff0000, v185
	v_pk_fma_f32 v[150:151], v[116:117], v[136:137], v[150:151]
	v_pk_fma_f32 v[166:167], v[118:119], v[138:139], v[166:167]
	v_pk_fma_f32 v[172:173], v[110:111], v[134:135], v[172:173]
	v_pk_fma_f32 v[168:169], v[108:109], v[132:133], v[168:169]
	v_cvt_pk_bf16_f32 v182, v150, v151
	v_add_co_u32_e32 v150, vcc, s73, v148
	v_cvt_pk_bf16_f32 v183, v166, v167
	v_cvt_pk_bf16_f32 v184, v168, v169
	v_cvt_pk_bf16_f32 v185, v172, v173
	v_addc_co_u32_e32 v151, vcc, 0, v149, vcc
	global_store_dwordx4 v[148:149], v[182:185], off offset:256
	s_waitcnt vmcnt(7)
	s_nop 1
	v_mov_b32_e32 v182, v230
	v_mov_b32_e32 v183, v231
	v_mov_b32_e32 v184, v232
	v_mov_b32_e32 v185, v233
	v_lshlrev_b32_e32 v166, 16, v182
	v_and_b32_e32 v167, 0xffff0000, v182
	v_lshlrev_b32_e32 v168, 16, v183
	v_and_b32_e32 v169, 0xffff0000, v183
	v_lshlrev_b32_e32 v172, 16, v184
	v_and_b32_e32 v173, 0xffff0000, v184
	v_lshlrev_b32_e32 v182, 16, v185
	v_and_b32_e32 v183, 0xffff0000, v185
	v_pk_fma_f32 v[168:169], v[122:123], v[146:147], v[168:169]
	v_pk_fma_f32 v[166:167], v[120:121], v[144:145], v[166:167]
	v_pk_fma_f32 v[186:187], v[114:115], v[142:143], v[182:183]
	v_pk_fma_f32 v[172:173], v[112:113], v[140:141], v[172:173]
	v_cvt_pk_bf16_f32 v182, v166, v167
	v_cvt_pk_bf16_f32 v183, v168, v169
	v_cvt_pk_bf16_f32 v184, v172, v173
	v_cvt_pk_bf16_f32 v185, v186, v187
	global_store_dwordx4 v[150:151], v[182:185], off
	s_waitcnt vmcnt(7)
; #define GAS __attribute__((address_space(1)))
; __device__ __forceinline__ u32x4 pack8(f32x4 v0, f32x4 v1) { u32x4 w; w.x = cvt_pk_bf16(v0[0], v0[1]); w.y = cvt_pk_bf16(v0[2], v0[3]); w.z = cvt_pk_bf16(v1[0], v1[1]); w.w = cvt_pk_bf16(v1[2], v1[3]); return w; }
; __device__ __forceinline__ void unpack8(u32x4 w, f32x4& v0, f32x4& v1) { v0 = (f32x4){bflo(w.x), bfhi(w.x), bflo(w.y), bfhi(w.y)}; v1 = (f32x4){bflo(w.z), bfhi(w.z), bflo(w.w), bfhi(w.w)}; }
; #define GAS __attribute__((address_space(1)))
;     __device__ __forceinline__ void operator()(const f32x4 (&acc)[2][2][4][2], const Unit& u, int wr, int wc, int fr, int fq) const {
;     ...
;         for (int ai = 0; ai < 2; ++ai) {
;             const int rb = u.pm * BM + ai * HALF + wr * 64;
;             const int cb = rb < 8192 ? (rb >> 11) : 4 + ((rb - 8192) >> 6);
;             const float* g = gmod + (size_t)cb * 12288 + col0;
;             f32x4 gv[2][2];
; #pragma unroll
;             for (int bj = 0; bj < 2; ++bj)
; #pragma unroll
;                 for (int n = 0; n < 2; ++n) gv[bj][n] = *(const GAS f32x4*)(g + bj * HALF + 4 * n);
;             if (part) { bf16_t* base = SL + ((size_t)u.slab * 1024 + (size_t)(rb - 8192 + fr)) * 2048 + col0;
; #pragma unroll
;                 for (int m = 0; m < 4; ++m)
; #pragma unroll
;                     for (int bj = 0; bj < 2; ++bj) *(GAS u32x4*)(base + (size_t)(m * 16) * 2048 + bj * HALF) = pack8(gv[bj][0] * acc[ai][bj][m][0], gv[bj][1] * acc[ai][bj][m][1]);
;             } else { const size_t o0 = (size_t)(rb + fr) * 2048 + col0;
; #pragma unroll
;                 for (int m = 0; m < 4; ++m)
; #pragma unroll
;                     for (int bj = 0; bj < 2; ++bj) { const size_t o = o0 + (size_t)(m * 16) * 2048 + bj * HALF; f32x4 x0, x1; unpack8(*(const GAS u32x4*)(XB + o), x0, x1);
;                         const f32x4 v0 = x0 + gv[bj][0] * acc[ai][bj][m][0], v1 = x1 + gv[bj][1] * acc[ai][bj][m][1];
;                         if (OUTF != nullptr) { *(GAS f32x4*)(OUTF + o) = v0; *(GAS f32x4*)(OUTF + o + 4) = v1; } else *(GAS u32x4*)(XB + o) = pack8(v0, v1); }
	s_nop 1
	v_mov_b32_e32 v182, v234
	v_mov_b32_e32 v183, v235
	v_mov_b32_e32 v184, v236
	v_mov_b32_e32 v185, v237
	v_lshlrev_b32_e32 v166, 16, v182
	v_and_b32_e32 v167, 0xffff0000, v182
	v_lshlrev_b32_e32 v168, 16, v183
	v_and_b32_e32 v169, 0xffff0000, v183
	v_lshlrev_b32_e32 v172, 16, v184
	v_and_b32_e32 v173, 0xffff0000, v184
	v_lshlrev_b32_e32 v182, 16, v185
	v_and_b32_e32 v183, 0xffff0000, v185
	v_pk_fma_f32 v[168:169], v[102:103], v[138:139], v[168:169]
	v_pk_fma_f32 v[166:167], v[100:101], v[136:137], v[166:167]
	v_pk_fma_f32 v[186:187], v[92:93], v[134:135], v[182:183]
	v_pk_fma_f32 v[172:173], v[90:91], v[132:133], v[172:173]
	v_cvt_pk_bf16_f32 v182, v166, v167
	v_cvt_pk_bf16_f32 v183, v168, v169
	v_cvt_pk_bf16_f32 v184, v172, v173
	v_cvt_pk_bf16_f32 v185, v186, v187
	global_store_dwordx4 v[150:151], v[182:185], off offset:256
	v_add_co_u32_e32 v150, vcc, s3, v148
	s_nop 1
	v_addc_co_u32_e32 v151, vcc, 0, v149, vcc
	s_waitcnt vmcnt(7)
	s_nop 1
	v_mov_b32_e32 v182, v238
	v_mov_b32_e32 v183, v239
	v_mov_b32_e32 v184, v240
	v_mov_b32_e32 v185, v241
	v_lshlrev_b32_e32 v166, 16, v182
	v_and_b32_e32 v167, 0xffff0000, v182
	v_lshlrev_b32_e32 v168, 16, v183
	v_and_b32_e32 v169, 0xffff0000, v183
	v_lshlrev_b32_e32 v172, 16, v184
	v_and_b32_e32 v173, 0xffff0000, v184
	v_lshlrev_b32_e32 v182, 16, v185
	v_and_b32_e32 v183, 0xffff0000, v185
	v_pk_fma_f32 v[168:169], v[106:107], v[146:147], v[168:169]
	v_pk_fma_f32 v[166:167], v[104:105], v[144:145], v[166:167]
	v_pk_fma_f32 v[186:187], v[96:97], v[142:143], v[182:183]
	v_pk_fma_f32 v[172:173], v[94:95], v[140:141], v[172:173]
	v_cvt_pk_bf16_f32 v182, v166, v167
	v_cvt_pk_bf16_f32 v183, v168, v169
	v_cvt_pk_bf16_f32 v184, v172, v173
	v_cvt_pk_bf16_f32 v185, v186, v187
	global_store_dwordx4 v[150:151], v[182:185], off
	s_waitcnt vmcnt(7)
	s_nop 1
	v_mov_b32_e32 v182, v242
	v_mov_b32_e32 v183, v243
	v_mov_b32_e32 v184, v244
	v_mov_b32_e32 v185, v245
	v_lshlrev_b32_e32 v166, 16, v182
	v_and_b32_e32 v167, 0xffff0000, v182
	v_lshlrev_b32_e32 v168, 16, v183
	v_and_b32_e32 v169, 0xffff0000, v183
	v_lshlrev_b32_e32 v172, 16, v184
	v_and_b32_e32 v173, 0xffff0000, v184
	v_lshlrev_b32_e32 v182, 16, v185
	v_and_b32_e32 v183, 0xffff0000, v185
	v_pk_fma_f32 v[166:167], v[82:83], v[136:137], v[166:167]
	v_pk_fma_f32 v[168:169], v[84:85], v[138:139], v[168:169]
	v_pk_fma_f32 v[186:187], v[76:77], v[134:135], v[182:183]
	v_pk_fma_f32 v[172:173], v[74:75], v[132:133], v[172:173]
	v_cvt_pk_bf16_f32 v182, v166, v167
	v_add_co_u32_e32 v166, vcc, s46, v148
	v_cvt_pk_bf16_f32 v183, v168, v169
	v_cvt_pk_bf16_f32 v184, v172, v173
	v_cvt_pk_bf16_f32 v185, v186, v187
	v_addc_co_u32_e32 v167, vcc, 0, v149, vcc
	global_store_dwordx4 v[150:151], v[182:185], off offset:256
	s_waitcnt vmcnt(7)
	s_nop 1
	v_mov_b32_e32 v148, v194
	v_mov_b32_e32 v149, v195
	v_mov_b32_e32 v150, v196
	v_mov_b32_e32 v151, v197
	v_lshlrev_b32_e32 v168, 16, v148
	v_and_b32_e32 v169, 0xffff0000, v148
	v_lshlrev_b32_e32 v148, 16, v149
	v_and_b32_e32 v149, 0xffff0000, v149
	v_lshlrev_b32_e32 v172, 16, v150
	v_and_b32_e32 v173, 0xffff0000, v150
	v_lshlrev_b32_e32 v150, 16, v151
	v_and_b32_e32 v151, 0xffff0000, v151
	v_pk_fma_f32 v[182:183], v[88:89], v[146:147], v[148:149]
	v_pk_fma_f32 v[148:149], v[86:87], v[144:145], v[168:169]
	v_pk_fma_f32 v[168:169], v[80:81], v[142:143], v[150:151]
	v_pk_fma_f32 v[150:151], v[78:79], v[140:141], v[172:173]
	v_cvt_pk_bf16_f32 v148, v148, v149
	v_cvt_pk_bf16_f32 v149, v182, v183
	v_cvt_pk_bf16_f32 v150, v150, v151
	v_cvt_pk_bf16_f32 v151, v168, v169
	global_store_dwordx4 v[166:167], v[148:151], off
	s_waitcnt vmcnt(7)
	s_nop 1
	v_mov_b32_e32 v148, v198
	v_mov_b32_e32 v149, v199
	v_mov_b32_e32 v150, v200
	v_mov_b32_e32 v151, v201
	v_lshlrev_b32_e32 v168, 16, v148
	v_and_b32_e32 v169, 0xffff0000, v148
	v_lshlrev_b32_e32 v148, 16, v149
	v_and_b32_e32 v149, 0xffff0000, v149
	v_lshlrev_b32_e32 v172, 16, v150
	v_and_b32_e32 v173, 0xffff0000, v150
	v_lshlrev_b32_e32 v150, 16, v151
	v_and_b32_e32 v151, 0xffff0000, v151
	v_pk_fma_f32 v[182:183], v[72:73], v[138:139], v[148:149]
	v_pk_fma_f32 v[148:149], v[70:71], v[136:137], v[168:169]
	v_pk_fma_f32 v[168:169], v[68:69], v[134:135], v[150:151]
	v_pk_fma_f32 v[150:151], v[66:67], v[132:133], v[172:173]
	v_cvt_pk_bf16_f32 v148, v148, v149
	v_cvt_pk_bf16_f32 v149, v182, v183
	v_cvt_pk_bf16_f32 v150, v150, v151
	v_cvt_pk_bf16_f32 v151, v168, v169
	global_store_dwordx4 v[166:167], v[148:151], off offset:256

; #define GAS __attribute__((address_space(1)))
; __device__ __forceinline__ u32x4 pack8(f32x4 v0, f32x4 v1) { u32x4 w; w.x = cvt_pk_bf16(v0[0], v0[1]); w.y = cvt_pk_bf16(v0[2], v0[3]); w.z = cvt_pk_bf16(v1[0], v1[1]); w.w = cvt_pk_bf16(v1[2], v1[3]); return w; }
; __device__ __forceinline__ void unpack8(u32x4 w, f32x4& v0, f32x4& v1) { v0 = (f32x4){bflo(w.x), bfhi(w.x), bflo(w.y), bfhi(w.y)}; v1 = (f32x4){bflo(w.z), bfhi(w.z), bflo(w.w), bfhi(w.w)}; }
; #define GAS __attribute__((address_space(1)))
;     __device__ __forceinline__ void operator()(const f32x4 (&acc)[2][2][4][2], const Unit& u, int wr, int wc, int fr, int fq) const {
;     ...
;             } else { const size_t o0 = (size_t)(rb + fr) * 2048 + col0;
; #pragma unroll
;                 for (int m = 0; m < 4; ++m)
; #pragma unroll
;                     for (int bj = 0; bj < 2; ++bj) { const size_t o = o0 + (size_t)(m * 16) * 2048 + bj * HALF; f32x4 x0, x1; unpack8(*(const GAS u32x4*)(XB + o), x0, x1);
;                         const f32x4 v0 = x0 + gv[bj][0] * acc[ai][bj][m][0], v1 = x1 + gv[bj][1] * acc[ai][bj][m][1];
;                         if (OUTF != nullptr) { *(GAS f32x4*)(OUTF + o) = v0; *(GAS f32x4*)(OUTF + o + 4) = v1; } else *(GAS u32x4*)(XB + o) = pack8(v0, v1); }
.LBB0_1318:
	v_or_b32_e32 v82, s0, v1
	v_ashrrev_i32_e32 v83, 31, v82
	v_lshlrev_b64 v[82:83], 12, v[82:83]
	v_lshl_add_u64 v[82:83], s[6:7], 0, v[82:83]
	v_lshl_add_u64 v[82:83], v[164:165], 1, v[82:83]
	global_load_dwordx4 v[222:225], v[82:83], off
	global_load_dwordx4 v[226:229], v[82:83], off offset:256
	v_add_co_u32_e32 v188, vcc, s73, v82
	s_nop 1
	v_addc_co_u32_e32 v189, vcc, 0, v83, vcc
	global_load_dwordx4 v[230:233], v[188:189], off
	global_load_dwordx4 v[234:237], v[188:189], off offset:256
	v_add_co_u32_e32 v188, vcc, s3, v82
	s_nop 1
	v_addc_co_u32_e32 v189, vcc, 0, v83, vcc
	global_load_dwordx4 v[238:241], v[188:189], off
	global_load_dwordx4 v[242:245], v[188:189], off offset:256
	v_add_co_u32_e32 v188, vcc, s46, v82
	s_nop 1
	v_addc_co_u32_e32 v189, vcc, 0, v83, vcc
	global_load_dwordx4 v[194:197], v[188:189], off
	global_load_dwordx4 v[198:201], v[188:189], off offset:256
	s_waitcnt vmcnt(7)
	s_nop 1
	v_mov_b32_e32 v84, v222
	v_mov_b32_e32 v85, v223
	v_mov_b32_e32 v86, v224
	v_mov_b32_e32 v87, v225
	v_lshlrev_b32_e32 v88, 16, v84
	v_and_b32_e32 v89, 0xffff0000, v84
	v_lshlrev_b32_e32 v84, 16, v85
	v_and_b32_e32 v85, 0xffff0000, v85
	v_lshlrev_b32_e32 v90, 16, v86
	v_and_b32_e32 v91, 0xffff0000, v86
	v_lshlrev_b32_e32 v86, 16, v87
	v_and_b32_e32 v87, 0xffff0000, v87
	v_pk_fma_f32 v[92:93], v[64:65], v[80:81], v[84:85]
	v_pk_fma_f32 v[84:85], v[62:63], v[78:79], v[88:89]
	v_pk_fma_f32 v[88:89], v[60:61], v[76:77], v[86:87]
	v_pk_fma_f32 v[86:87], v[58:59], v[74:75], v[90:91]
	v_cvt_pk_bf16_f32 v84, v84, v85
	v_cvt_pk_bf16_f32 v85, v92, v93
	v_cvt_pk_bf16_f32 v86, v86, v87
	v_cvt_pk_bf16_f32 v87, v88, v89
	global_store_dwordx4 v[82:83], v[84:87], off
	s_waitcnt vmcnt(7)
	s_nop 1
	v_mov_b32_e32 v84, v226
	v_mov_b32_e32 v85, v227
	v_mov_b32_e32 v86, v228
	v_mov_b32_e32 v87, v229
	v_lshlrev_b32_e32 v88, 16, v84
	v_and_b32_e32 v89, 0xffff0000, v84
	v_lshlrev_b32_e32 v84, 16, v85
	v_and_b32_e32 v85, 0xffff0000, v85
	v_lshlrev_b32_e32 v90, 16, v86
	v_and_b32_e32 v91, 0xffff0000, v86
	v_lshlrev_b32_e32 v86, 16, v87
	v_and_b32_e32 v87, 0xffff0000, v87
	v_pk_fma_f32 v[92:93], v[52:53], v[72:73], v[84:85]
	v_pk_fma_f32 v[84:85], v[50:51], v[70:71], v[88:89]
	v_pk_fma_f32 v[88:89], v[44:45], v[68:69], v[86:87]
	v_pk_fma_f32 v[86:87], v[42:43], v[66:67], v[90:91]
	v_cvt_pk_bf16_f32 v84, v84, v85
	v_cvt_pk_bf16_f32 v86, v86, v87
	v_cvt_pk_bf16_f32 v87, v88, v89
	v_add_co_u32_e32 v88, vcc, s73, v82
	v_cvt_pk_bf16_f32 v85, v92, v93
	s_nop 0
	v_addc_co_u32_e32 v89, vcc, 0, v83, vcc
	global_store_dwordx4 v[82:83], v[84:87], off offset:256
	s_waitcnt vmcnt(7)
	s_nop 1
	v_mov_b32_e32 v84, v230
	v_mov_b32_e32 v85, v231
	v_mov_b32_e32 v86, v232
	v_mov_b32_e32 v87, v233
	v_lshlrev_b32_e32 v90, 16, v84
	v_and_b32_e32 v91, 0xffff0000, v84
	v_lshlrev_b32_e32 v84, 16, v85
	v_and_b32_e32 v85, 0xffff0000, v85
	v_lshlrev_b32_e32 v92, 16, v86
	v_and_b32_e32 v93, 0xffff0000, v86
	v_lshlrev_b32_e32 v86, 16, v87
	v_and_b32_e32 v87, 0xffff0000, v87
	v_pk_fma_f32 v[94:95], v[56:57], v[80:81], v[84:85]
	v_pk_fma_f32 v[84:85], v[54:55], v[78:79], v[90:91]
	v_pk_fma_f32 v[90:91], v[48:49], v[76:77], v[86:87]
	v_pk_fma_f32 v[86:87], v[46:47], v[74:75], v[92:93]
	v_cvt_pk_bf16_f32 v84, v84, v85
	v_cvt_pk_bf16_f32 v85, v94, v95
	v_cvt_pk_bf16_f32 v86, v86, v87
	v_cvt_pk_bf16_f32 v87, v90, v91
	global_store_dwordx4 v[88:89], v[84:87], off
	s_waitcnt vmcnt(7)
; #define GAS __attribute__((address_space(1)))
; __device__ __forceinline__ u32x4 pack8(f32x4 v0, f32x4 v1) { u32x4 w; w.x = cvt_pk_bf16(v0[0], v0[1]); w.y = cvt_pk_bf16(v0[2], v0[3]); w.z = cvt_pk_bf16(v1[0], v1[1]); w.w = cvt_pk_bf16(v1[2], v1[3]); return w; }
; __device__ __forceinline__ void unpack8(u32x4 w, f32x4& v0, f32x4& v1) { v0 = (f32x4){bflo(w.x), bfhi(w.x), bflo(w.y), bfhi(w.y)}; v1 = (f32x4){bflo(w.z), bfhi(w.z), bflo(w.w), bfhi(w.w)}; }
; #define GAS __attribute__((address_space(1)))
;     __device__ __forceinline__ void operator()(const f32x4 (&acc)[2][2][4][2], const Unit& u, int wr, int wc, int fr, int fq) const {
;     ...
;             } else { const size_t o0 = (size_t)(rb + fr) * 2048 + col0;
; #pragma unroll
;                 for (int m = 0; m < 4; ++m)
; #pragma unroll
;                     for (int bj = 0; bj < 2; ++bj) { const size_t o = o0 + (size_t)(m * 16) * 2048 + bj * HALF; f32x4 x0, x1; unpack8(*(const GAS u32x4*)(XB + o), x0, x1);
;                         const f32x4 v0 = x0 + gv[bj][0] * acc[ai][bj][m][0], v1 = x1 + gv[bj][1] * acc[ai][bj][m][1];
;                         if (OUTF != nullptr) { *(GAS f32x4*)(OUTF + o) = v0; *(GAS f32x4*)(OUTF + o + 4) = v1; } else *(GAS u32x4*)(XB + o) = pack8(v0, v1); }
	s_nop 1
	v_mov_b32_e32 v84, v234
	v_mov_b32_e32 v85, v235
	v_mov_b32_e32 v86, v236
	v_mov_b32_e32 v87, v237
	v_lshlrev_b32_e32 v90, 16, v84
	v_and_b32_e32 v91, 0xffff0000, v84
	v_lshlrev_b32_e32 v84, 16, v85
	v_and_b32_e32 v85, 0xffff0000, v85
	v_lshlrev_b32_e32 v92, 16, v86
	v_and_b32_e32 v93, 0xffff0000, v86
	v_lshlrev_b32_e32 v86, 16, v87
	v_and_b32_e32 v87, 0xffff0000, v87
	v_pk_fma_f32 v[94:95], v[36:37], v[72:73], v[84:85]
	v_pk_fma_f32 v[84:85], v[34:35], v[70:71], v[90:91]
	v_pk_fma_f32 v[90:91], v[28:29], v[68:69], v[86:87]
	v_pk_fma_f32 v[86:87], v[26:27], v[66:67], v[92:93]
	v_cvt_pk_bf16_f32 v84, v84, v85
	v_cvt_pk_bf16_f32 v85, v94, v95
	v_cvt_pk_bf16_f32 v86, v86, v87
	v_cvt_pk_bf16_f32 v87, v90, v91
	global_store_dwordx4 v[88:89], v[84:87], off offset:256
	v_add_co_u32_e32 v88, vcc, s3, v82
	s_nop 1
	v_addc_co_u32_e32 v89, vcc, 0, v83, vcc
	s_waitcnt vmcnt(7)
	s_nop 1
	v_mov_b32_e32 v84, v238
	v_mov_b32_e32 v85, v239
	v_mov_b32_e32 v86, v240
	v_mov_b32_e32 v87, v241
	v_lshlrev_b32_e32 v90, 16, v84
	v_and_b32_e32 v91, 0xffff0000, v84
	v_lshlrev_b32_e32 v84, 16, v85
	v_and_b32_e32 v85, 0xffff0000, v85
	v_lshlrev_b32_e32 v92, 16, v86
	v_and_b32_e32 v93, 0xffff0000, v86
	v_lshlrev_b32_e32 v86, 16, v87
	v_and_b32_e32 v87, 0xffff0000, v87
	v_pk_fma_f32 v[94:95], v[40:41], v[80:81], v[84:85]
	v_pk_fma_f32 v[84:85], v[38:39], v[78:79], v[90:91]
	v_pk_fma_f32 v[90:91], v[32:33], v[76:77], v[86:87]
	v_pk_fma_f32 v[86:87], v[30:31], v[74:75], v[92:93]
	v_cvt_pk_bf16_f32 v84, v84, v85
	v_cvt_pk_bf16_f32 v85, v94, v95
	v_cvt_pk_bf16_f32 v86, v86, v87
	v_cvt_pk_bf16_f32 v87, v90, v91
	global_store_dwordx4 v[88:89], v[84:87], off
	s_waitcnt vmcnt(7)
	s_nop 1
	v_mov_b32_e32 v84, v242
	v_mov_b32_e32 v85, v243
	v_mov_b32_e32 v86, v244
	v_mov_b32_e32 v87, v245
	v_lshlrev_b32_e32 v90, 16, v84
	v_and_b32_e32 v91, 0xffff0000, v84
	v_lshlrev_b32_e32 v84, 16, v85
	v_and_b32_e32 v85, 0xffff0000, v85
	v_lshlrev_b32_e32 v92, 16, v86
	v_and_b32_e32 v93, 0xffff0000, v86
	v_lshlrev_b32_e32 v86, 16, v87
	v_and_b32_e32 v87, 0xffff0000, v87
	v_pk_fma_f32 v[94:95], v[20:21], v[72:73], v[84:85]
	v_pk_fma_f32 v[84:85], v[18:19], v[70:71], v[90:91]
	v_pk_fma_f32 v[90:91], v[12:13], v[68:69], v[86:87]
	v_pk_fma_f32 v[86:87], v[10:11], v[66:67], v[92:93]
	v_cvt_pk_bf16_f32 v84, v84, v85
	v_cvt_pk_bf16_f32 v85, v94, v95
	v_cvt_pk_bf16_f32 v86, v86, v87
	v_cvt_pk_bf16_f32 v87, v90, v91
	global_store_dwordx4 v[88:89], v[84:87], off offset:256
	s_nop 1
	v_add_co_u32_e32 v86, vcc, s46, v82
	s_nop 1
	v_addc_co_u32_e32 v87, vcc, 0, v83, vcc
	s_waitcnt vmcnt(7)
	s_nop 1
	v_mov_b32_e32 v82, v194
	v_mov_b32_e32 v83, v195
	v_mov_b32_e32 v84, v196
	v_mov_b32_e32 v85, v197
	v_lshlrev_b32_e32 v88, 16, v82
	v_and_b32_e32 v89, 0xffff0000, v82
	v_lshlrev_b32_e32 v82, 16, v83
	v_and_b32_e32 v83, 0xffff0000, v83
	v_lshlrev_b32_e32 v90, 16, v84
	v_and_b32_e32 v91, 0xffff0000, v84
	v_lshlrev_b32_e32 v84, 16, v85
	v_and_b32_e32 v85, 0xffff0000, v85
	v_pk_fma_f32 v[92:93], v[24:25], v[80:81], v[82:83]
	v_pk_fma_f32 v[82:83], v[22:23], v[78:79], v[88:89]
	v_pk_fma_f32 v[88:89], v[16:17], v[76:77], v[84:85]
	v_pk_fma_f32 v[84:85], v[14:15], v[74:75], v[90:91]
	v_cvt_pk_bf16_f32 v82, v82, v83
	v_cvt_pk_bf16_f32 v83, v92, v93
	v_cvt_pk_bf16_f32 v84, v84, v85
	v_cvt_pk_bf16_f32 v85, v88, v89
	global_store_dwordx4 v[86:87], v[82:85], off
	s_waitcnt vmcnt(7)
	s_nop 1
	v_mov_b32_e32 v82, v198
	v_mov_b32_e32 v83, v199
	v_mov_b32_e32 v84, v200
	v_mov_b32_e32 v85, v201
	v_lshlrev_b32_e32 v88, 16, v82
	v_and_b32_e32 v89, 0xffff0000, v82
	v_lshlrev_b32_e32 v82, 16, v83
	v_and_b32_e32 v83, 0xffff0000, v83
	v_lshlrev_b32_e32 v90, 16, v84
	v_and_b32_e32 v91, 0xffff0000, v84
	v_lshlrev_b32_e32 v84, 16, v85
	v_and_b32_e32 v85, 0xffff0000, v85
	v_pk_fma_f32 v[92:93], v[8:9], v[72:73], v[82:83]
	v_pk_fma_f32 v[82:83], v[6:7], v[70:71], v[88:89]
	v_pk_fma_f32 v[88:89], v[4:5], v[68:69], v[84:85]
	v_pk_fma_f32 v[84:85], v[2:3], v[66:67], v[90:91]
	v_cvt_pk_bf16_f32 v82, v82, v83
	v_cvt_pk_bf16_f32 v83, v92, v93
	v_cvt_pk_bf16_f32 v84, v84, v85
	v_cvt_pk_bf16_f32 v85, v88, v89
	global_store_dwordx4 v[86:87], v[82:85], off offset:256
	s_cbranch_execnz .LBB0_1317

; #define GAS __attribute__((address_space(1)))
; __device__ __forceinline__ u32x4 pack8(f32x4 v0, f32x4 v1) { u32x4 w; w.x = cvt_pk_bf16(v0[0], v0[1]); w.y = cvt_pk_bf16(v0[2], v0[3]); w.z = cvt_pk_bf16(v1[0], v1[1]); w.w = cvt_pk_bf16(v1[2], v1[3]); return w; }
; __device__ __forceinline__ void unpack8(u32x4 w, f32x4& v0, f32x4& v1) { v0 = (f32x4){bflo(w.x), bfhi(w.x), bflo(w.y), bfhi(w.y)}; v1 = (f32x4){bflo(w.z), bfhi(w.z), bflo(w.w), bfhi(w.w)}; }
; #define GAS __attribute__((address_space(1)))
;     __device__ __forceinline__ void operator()(const f32x4 (&acc)[2][2][4][2], const Unit& u, int wr, int wc, int fr, int fq) const {
;     ...
;         for (int ai = 0; ai < 2; ++ai) {
;             const int rb = u.pm * BM + ai * HALF + wr * 64;
;             const int cb = rb < 8192 ? (rb >> 11) : 4 + ((rb - 8192) >> 6);
;             const float* g = gmod + (size_t)cb * 12288 + col0;
;             f32x4 gv[2][2];
; #pragma unroll
;             for (int bj = 0; bj < 2; ++bj)
; #pragma unroll
;                 for (int n = 0; n < 2; ++n) gv[bj][n] = *(const GAS f32x4*)(g + bj * HALF + 4 * n);
;             if (part) { bf16_t* base = SL + ((size_t)u.slab * 1024 + (size_t)(rb - 8192 + fr)) * 2048 + col0;
; #pragma unroll
;                 for (int m = 0; m < 4; ++m)
; #pragma unroll
;                     for (int bj = 0; bj < 2; ++bj) *(GAS u32x4*)(base + (size_t)(m * 16) * 2048 + bj * HALF) = pack8(gv[bj][0] * acc[ai][bj][m][0], gv[bj][1] * acc[ai][bj][m][1]);
;             } else { const size_t o0 = (size_t)(rb + fr) * 2048 + col0;
; #pragma unroll
;                 for (int m = 0; m < 4; ++m)
; #pragma unroll
;                     for (int bj = 0; bj < 2; ++bj) { const size_t o = o0 + (size_t)(m * 16) * 2048 + bj * HALF; f32x4 x0, x1; unpack8(*(const GAS u32x4*)(XB + o), x0, x1);
;                         const f32x4 v0 = x0 + gv[bj][0] * acc[ai][bj][m][0], v1 = x1 + gv[bj][1] * acc[ai][bj][m][1];
;                         if (OUTF != nullptr) { *(GAS f32x4*)(OUTF + o) = v0; *(GAS f32x4*)(OUTF + o + 4) = v1; } else *(GAS u32x4*)(XB + o) = pack8(v0, v1); }
.LBB0_1657:
	s_cmp_lt_i32 s78, 0
	s_cselect_b64 s[34:35], -1, 0
	s_lshl_b32 s15, s71, 8
	s_add_i32 s15, s15, s59
	s_add_i32 s42, s15, 0xffffe000
	s_lshr_b32 s1, s42, 6
	s_ashr_i32 s0, s15, 11
	s_add_i32 s1, s1, 4
	s_cmpk_lt_i32 s15, 0x2000
	s_cselect_b32 s0, s0, s1
	s_mul_hi_i32 s1, s0, 0xc000
	s_mul_i32 s0, s0, 0xc000
	v_lshl_or_b32 v180, s75, 8, v188
	s_add_u32 s0, s55, s0
	v_ashrrev_i32_e32 v181, 31, v180
	s_addc_u32 s1, s56, s1
	v_lshl_add_u64 v[136:137], v[180:181], 2, s[0:1]
	global_load_dwordx4 v[140:143], v[136:137], off offset:16
	global_load_dwordx4 v[144:147], v[136:137], off
	global_load_dwordx4 v[132:135], v[136:137], off offset:528
	s_nop 0
	global_load_dwordx4 v[136:139], v[136:137], off offset:512
	v_cndmask_b32_e64 v148, 0, 1, s[8:9]
	s_mov_b64 s[40:41], -1
	s_and_b64 vcc, exec, s[34:35]
	v_cmp_ne_u32_e64 s[38:39], 1, v148
	s_cbranch_vccz .LBB0_1684
	v_or_b32_e32 v148, s15, v1
	v_ashrrev_i32_e32 v149, 31, v148
	v_lshlrev_b64 v[148:149], 11, v[148:149]
	v_lshl_add_u64 v[186:187], v[148:149], 0, v[180:181]
	v_lshl_add_u64 v[182:183], v[186:187], 1, s[10:11]
	global_load_dwordx4 v[222:225], v[182:183], off
	global_load_dwordx4 v[226:229], v[182:183], off offset:256
	v_add_co_u32_e32 v198, vcc, 0x10000, v182
	s_nop 1
	v_addc_co_u32_e32 v199, vcc, 0, v183, vcc
	global_load_dwordx4 v[230:233], v[198:199], off
	global_load_dwordx4 v[234:237], v[198:199], off offset:256
	v_add_co_u32_e32 v198, vcc, 0x20000, v182
	s_nop 1
	v_addc_co_u32_e32 v199, vcc, 0, v183, vcc
	global_load_dwordx4 v[238:241], v[198:199], off
	global_load_dwordx4 v[242:245], v[198:199], off offset:256
	v_add_co_u32_e32 v198, vcc, 0x30000, v182
	s_nop 1
	v_addc_co_u32_e32 v199, vcc, 0, v183, vcc
	global_load_dwordx4 v[190:193], v[198:199], off
	global_load_dwordx4 v[194:197], v[198:199], off offset:256
	s_and_b64 vcc, exec, s[38:39]
	v_lshl_add_u64 v[184:185], v[186:187], 2, s[6:7]
	s_waitcnt vmcnt(7)
	s_nop 1
	v_mov_b32_e32 v148, v222
	v_mov_b32_e32 v149, v223
	v_mov_b32_e32 v150, v224
	v_mov_b32_e32 v151, v225
	v_lshlrev_b32_e32 v152, 16, v148
	v_and_b32_e32 v153, 0xffff0000, v148
	v_lshlrev_b32_e32 v148, 16, v149
	v_and_b32_e32 v149, 0xffff0000, v149
	v_lshlrev_b32_e32 v168, 16, v150
	v_and_b32_e32 v169, 0xffff0000, v150
	v_lshlrev_b32_e32 v150, 16, v151
	v_and_b32_e32 v151, 0xffff0000, v151
	v_pk_fma_f32 v[154:155], v[130:131], v[146:147], v[148:149]
	v_pk_fma_f32 v[152:153], v[128:129], v[144:145], v[152:153]
	v_pk_fma_f32 v[150:151], v[126:127], v[142:143], v[150:151]
	v_pk_fma_f32 v[148:149], v[124:125], v[140:141], v[168:169]
	s_cbranch_vccnz .LBB0_1660
	s_mov_b64 s[40:41], 0
	global_store_dwordx4 v[184:185], v[152:155], off
	global_store_dwordx4 v[184:185], v[148:151], off offset:16

; #define GAS __attribute__((address_space(1)))
; __device__ __forceinline__ u32x4 pack8(f32x4 v0, f32x4 v1) { u32x4 w; w.x = cvt_pk_bf16(v0[0], v0[1]); w.y = cvt_pk_bf16(v0[2], v0[3]); w.z = cvt_pk_bf16(v1[0], v1[1]); w.w = cvt_pk_bf16(v1[2], v1[3]); return w; }
; __device__ __forceinline__ void unpack8(u32x4 w, f32x4& v0, f32x4& v1) { v0 = (f32x4){bflo(w.x), bfhi(w.x), bflo(w.y), bfhi(w.y)}; v1 = (f32x4){bflo(w.z), bfhi(w.z), bflo(w.w), bfhi(w.w)}; }
; #define GAS __attribute__((address_space(1)))
;     __device__ __forceinline__ void operator()(const f32x4 (&acc)[2][2][4][2], const Unit& u, int wr, int wc, int fr, int fq) const {
;     ...
;             } else { const size_t o0 = (size_t)(rb + fr) * 2048 + col0;
; #pragma unroll
;                 for (int m = 0; m < 4; ++m)
; #pragma unroll
;                     for (int bj = 0; bj < 2; ++bj) { const size_t o = o0 + (size_t)(m * 16) * 2048 + bj * HALF; f32x4 x0, x1; unpack8(*(const GAS u32x4*)(XB + o), x0, x1);
;                         const f32x4 v0 = x0 + gv[bj][0] * acc[ai][bj][m][0], v1 = x1 + gv[bj][1] * acc[ai][bj][m][1];
;                         if (OUTF != nullptr) { *(GAS f32x4*)(OUTF + o) = v0; *(GAS f32x4*)(OUTF + o + 4) = v1; } else *(GAS u32x4*)(XB + o) = pack8(v0, v1); }
.LBB0_1662:
	v_lshlrev_b64 v[148:149], 1, v[186:187]
	v_or_b32_e32 v148, 0x100, v148
	v_lshl_add_u64 v[186:187], s[10:11], 0, v[148:149]
	s_and_b64 vcc, exec, s[38:39]
	s_waitcnt vmcnt(7)
	s_nop 1
	v_mov_b32_e32 v148, v226
	v_mov_b32_e32 v149, v227
	v_mov_b32_e32 v150, v228
	v_mov_b32_e32 v151, v229
	v_lshlrev_b32_e32 v152, 16, v148
	v_and_b32_e32 v153, 0xffff0000, v148
	v_lshlrev_b32_e32 v148, 16, v149
	v_and_b32_e32 v149, 0xffff0000, v149
	v_lshlrev_b32_e32 v168, 16, v150
	v_and_b32_e32 v169, 0xffff0000, v150
	v_lshlrev_b32_e32 v150, 16, v151
	v_and_b32_e32 v151, 0xffff0000, v151
	v_pk_fma_f32 v[154:155], v[118:119], v[138:139], v[148:149]
	v_pk_fma_f32 v[152:153], v[116:117], v[136:137], v[152:153]
	v_pk_fma_f32 v[150:151], v[110:111], v[134:135], v[150:151]
	v_pk_fma_f32 v[148:149], v[108:109], v[132:133], v[168:169]
	s_cbranch_vccnz .LBB0_1718
	global_store_dwordx4 v[184:185], v[152:155], off offset:512
	global_store_dwordx4 v[184:185], v[148:151], off offset:528
	s_cbranch_execnz .LBB0_1665

; #define GAS __attribute__((address_space(1)))
; __device__ __forceinline__ u32x4 pack8(f32x4 v0, f32x4 v1) { u32x4 w; w.x = cvt_pk_bf16(v0[0], v0[1]); w.y = cvt_pk_bf16(v0[2], v0[3]); w.z = cvt_pk_bf16(v1[0], v1[1]); w.w = cvt_pk_bf16(v1[2], v1[3]); return w; }
; __device__ __forceinline__ void unpack8(u32x4 w, f32x4& v0, f32x4& v1) { v0 = (f32x4){bflo(w.x), bfhi(w.x), bflo(w.y), bfhi(w.y)}; v1 = (f32x4){bflo(w.z), bfhi(w.z), bflo(w.w), bfhi(w.w)}; }
; #define GAS __attribute__((address_space(1)))
;     __device__ __forceinline__ void operator()(const f32x4 (&acc)[2][2][4][2], const Unit& u, int wr, int wc, int fr, int fq) const {
;     ...
;             } else { const size_t o0 = (size_t)(rb + fr) * 2048 + col0;
; #pragma unroll
;                 for (int m = 0; m < 4; ++m)
; #pragma unroll
;                     for (int bj = 0; bj < 2; ++bj) { const size_t o = o0 + (size_t)(m * 16) * 2048 + bj * HALF; f32x4 x0, x1; unpack8(*(const GAS u32x4*)(XB + o), x0, x1);
;                         const f32x4 v0 = x0 + gv[bj][0] * acc[ai][bj][m][0], v1 = x1 + gv[bj][1] * acc[ai][bj][m][1];
;                         if (OUTF != nullptr) { *(GAS f32x4*)(OUTF + o) = v0; *(GAS f32x4*)(OUTF + o + 4) = v1; } else *(GAS u32x4*)(XB + o) = pack8(v0, v1); }
.LBB0_1665:
	s_nop 0
	v_add_co_u32_e32 v148, vcc, 0x10000, v182
	s_nop 1
	v_addc_co_u32_e32 v149, vcc, 0, v183, vcc
	s_and_b64 vcc, exec, s[38:39]
	s_waitcnt vmcnt(7)
	s_nop 1
	v_mov_b32_e32 v148, v230
	v_mov_b32_e32 v149, v231
	v_mov_b32_e32 v150, v232
	v_mov_b32_e32 v151, v233
	v_lshlrev_b32_e32 v152, 16, v148
	v_and_b32_e32 v153, 0xffff0000, v148
	v_lshlrev_b32_e32 v148, 16, v149
	v_and_b32_e32 v149, 0xffff0000, v149
	v_lshlrev_b32_e32 v168, 16, v150
	v_and_b32_e32 v169, 0xffff0000, v150
	v_lshlrev_b32_e32 v150, 16, v151
	v_and_b32_e32 v151, 0xffff0000, v151
	v_pk_fma_f32 v[154:155], v[122:123], v[146:147], v[148:149]
	v_pk_fma_f32 v[152:153], v[120:121], v[144:145], v[152:153]
	v_pk_fma_f32 v[150:151], v[114:115], v[142:143], v[150:151]
	v_pk_fma_f32 v[148:149], v[112:113], v[140:141], v[168:169]
	s_cbranch_vccnz .LBB0_1719
	v_add_co_u32_e32 v172, vcc, 0x20000, v184
	s_mov_b64 s[0:1], 0x20000
	s_nop 0
	v_addc_co_u32_e32 v173, vcc, 0, v185, vcc
	v_lshl_add_u64 v[168:169], v[184:185], 0, s[0:1]
	global_store_dwordx4 v[172:173], v[152:155], off
	global_store_dwordx4 v[168:169], v[148:151], off offset:16
	s_cbranch_execnz .LBB0_1668

; #define GAS __attribute__((address_space(1)))
; __device__ __forceinline__ u32x4 pack8(f32x4 v0, f32x4 v1) { u32x4 w; w.x = cvt_pk_bf16(v0[0], v0[1]); w.y = cvt_pk_bf16(v0[2], v0[3]); w.z = cvt_pk_bf16(v1[0], v1[1]); w.w = cvt_pk_bf16(v1[2], v1[3]); return w; }
; __device__ __forceinline__ void unpack8(u32x4 w, f32x4& v0, f32x4& v1) { v0 = (f32x4){bflo(w.x), bfhi(w.x), bflo(w.y), bfhi(w.y)}; v1 = (f32x4){bflo(w.z), bfhi(w.z), bflo(w.w), bfhi(w.w)}; }
; #define GAS __attribute__((address_space(1)))
;     __device__ __forceinline__ void operator()(const f32x4 (&acc)[2][2][4][2], const Unit& u, int wr, int wc, int fr, int fq) const {
;     ...
;             } else { const size_t o0 = (size_t)(rb + fr) * 2048 + col0;
; #pragma unroll
;                 for (int m = 0; m < 4; ++m)
; #pragma unroll
;                     for (int bj = 0; bj < 2; ++bj) { const size_t o = o0 + (size_t)(m * 16) * 2048 + bj * HALF; f32x4 x0, x1; unpack8(*(const GAS u32x4*)(XB + o), x0, x1);
;                         const f32x4 v0 = x0 + gv[bj][0] * acc[ai][bj][m][0], v1 = x1 + gv[bj][1] * acc[ai][bj][m][1];
;                         if (OUTF != nullptr) { *(GAS f32x4*)(OUTF + o) = v0; *(GAS f32x4*)(OUTF + o + 4) = v1; } else *(GAS u32x4*)(XB + o) = pack8(v0, v1); }
.LBB0_1668:
	s_nop 0
	v_add_co_u32_e32 v148, vcc, 0x10000, v182
	s_nop 1
	v_addc_co_u32_e32 v149, vcc, 0, v183, vcc
	s_and_b64 vcc, exec, s[38:39]
	s_waitcnt vmcnt(7)
	s_nop 1
	v_mov_b32_e32 v148, v234
	v_mov_b32_e32 v149, v235
	v_mov_b32_e32 v150, v236
	v_mov_b32_e32 v151, v237
	v_lshlrev_b32_e32 v152, 16, v148
	v_and_b32_e32 v153, 0xffff0000, v148
	v_lshlrev_b32_e32 v148, 16, v149
	v_and_b32_e32 v149, 0xffff0000, v149
	v_lshlrev_b32_e32 v168, 16, v150
	v_and_b32_e32 v169, 0xffff0000, v150
	v_lshlrev_b32_e32 v150, 16, v151
	v_and_b32_e32 v151, 0xffff0000, v151
	v_pk_fma_f32 v[154:155], v[102:103], v[138:139], v[148:149]
	v_pk_fma_f32 v[152:153], v[100:101], v[136:137], v[152:153]
	v_pk_fma_f32 v[150:151], v[92:93], v[134:135], v[150:151]
	v_pk_fma_f32 v[148:149], v[90:91], v[132:133], v[168:169]
	s_cbranch_vccnz .LBB0_1720
	v_add_co_u32_e32 v172, vcc, 0x20000, v184
	s_mov_b64 s[0:1], 0x20200
	s_nop 0
	v_addc_co_u32_e32 v173, vcc, 0, v185, vcc
	v_lshl_add_u64 v[168:169], v[184:185], 0, s[0:1]
	global_store_dwordx4 v[172:173], v[152:155], off offset:512
	global_store_dwordx4 v[168:169], v[148:151], off offset:16
	s_cbranch_execnz .LBB0_1671

; #define GAS __attribute__((address_space(1)))
; __device__ __forceinline__ u32x4 pack8(f32x4 v0, f32x4 v1) { u32x4 w; w.x = cvt_pk_bf16(v0[0], v0[1]); w.y = cvt_pk_bf16(v0[2], v0[3]); w.z = cvt_pk_bf16(v1[0], v1[1]); w.w = cvt_pk_bf16(v1[2], v1[3]); return w; }
; __device__ __forceinline__ void unpack8(u32x4 w, f32x4& v0, f32x4& v1) { v0 = (f32x4){bflo(w.x), bfhi(w.x), bflo(w.y), bfhi(w.y)}; v1 = (f32x4){bflo(w.z), bfhi(w.z), bflo(w.w), bfhi(w.w)}; }
; #define GAS __attribute__((address_space(1)))
;     __device__ __forceinline__ void operator()(const f32x4 (&acc)[2][2][4][2], const Unit& u, int wr, int wc, int fr, int fq) const {
;     ...
;             } else { const size_t o0 = (size_t)(rb + fr) * 2048 + col0;
; #pragma unroll
;                 for (int m = 0; m < 4; ++m)
; #pragma unroll
;                     for (int bj = 0; bj < 2; ++bj) { const size_t o = o0 + (size_t)(m * 16) * 2048 + bj * HALF; f32x4 x0, x1; unpack8(*(const GAS u32x4*)(XB + o), x0, x1);
;                         const f32x4 v0 = x0 + gv[bj][0] * acc[ai][bj][m][0], v1 = x1 + gv[bj][1] * acc[ai][bj][m][1];
;                         if (OUTF != nullptr) { *(GAS f32x4*)(OUTF + o) = v0; *(GAS f32x4*)(OUTF + o + 4) = v1; } else *(GAS u32x4*)(XB + o) = pack8(v0, v1); }
.LBB0_1671:
	s_nop 0
	v_add_co_u32_e32 v148, vcc, 0x20000, v182
	s_nop 1
	v_addc_co_u32_e32 v149, vcc, 0, v183, vcc
	s_and_b64 vcc, exec, s[38:39]
	s_waitcnt vmcnt(7)
	s_nop 1
	v_mov_b32_e32 v148, v238
	v_mov_b32_e32 v149, v239
	v_mov_b32_e32 v150, v240
	v_mov_b32_e32 v151, v241
	v_lshlrev_b32_e32 v152, 16, v148
	v_and_b32_e32 v153, 0xffff0000, v148
	v_lshlrev_b32_e32 v148, 16, v149
	v_and_b32_e32 v149, 0xffff0000, v149
	v_lshlrev_b32_e32 v168, 16, v150
	v_and_b32_e32 v169, 0xffff0000, v150
	v_lshlrev_b32_e32 v150, 16, v151
	v_and_b32_e32 v151, 0xffff0000, v151
	v_pk_fma_f32 v[154:155], v[106:107], v[146:147], v[148:149]
	v_pk_fma_f32 v[152:153], v[104:105], v[144:145], v[152:153]
	v_pk_fma_f32 v[150:151], v[96:97], v[142:143], v[150:151]
	v_pk_fma_f32 v[148:149], v[94:95], v[140:141], v[168:169]
	s_cbranch_vccnz .LBB0_1721
	v_add_co_u32_e32 v172, vcc, 0x40000, v184
	s_nop 1
	v_addc_co_u32_e32 v173, vcc, 0, v185, vcc
	v_lshl_add_u64 v[168:169], v[184:185], 0, s[64:65]
	global_store_dwordx4 v[172:173], v[152:155], off
	global_store_dwordx4 v[168:169], v[148:151], off offset:16
	s_cbranch_execnz .LBB0_1674

; #define GAS __attribute__((address_space(1)))
; __device__ __forceinline__ u32x4 pack8(f32x4 v0, f32x4 v1) { u32x4 w; w.x = cvt_pk_bf16(v0[0], v0[1]); w.y = cvt_pk_bf16(v0[2], v0[3]); w.z = cvt_pk_bf16(v1[0], v1[1]); w.w = cvt_pk_bf16(v1[2], v1[3]); return w; }
; __device__ __forceinline__ void unpack8(u32x4 w, f32x4& v0, f32x4& v1) { v0 = (f32x4){bflo(w.x), bfhi(w.x), bflo(w.y), bfhi(w.y)}; v1 = (f32x4){bflo(w.z), bfhi(w.z), bflo(w.w), bfhi(w.w)}; }
; #define GAS __attribute__((address_space(1)))
;     __device__ __forceinline__ void operator()(const f32x4 (&acc)[2][2][4][2], const Unit& u, int wr, int wc, int fr, int fq) const {
;     ...
;             } else { const size_t o0 = (size_t)(rb + fr) * 2048 + col0;
; #pragma unroll
;                 for (int m = 0; m < 4; ++m)
; #pragma unroll
;                     for (int bj = 0; bj < 2; ++bj) { const size_t o = o0 + (size_t)(m * 16) * 2048 + bj * HALF; f32x4 x0, x1; unpack8(*(const GAS u32x4*)(XB + o), x0, x1);
;                         const f32x4 v0 = x0 + gv[bj][0] * acc[ai][bj][m][0], v1 = x1 + gv[bj][1] * acc[ai][bj][m][1];
;                         if (OUTF != nullptr) { *(GAS f32x4*)(OUTF + o) = v0; *(GAS f32x4*)(OUTF + o + 4) = v1; } else *(GAS u32x4*)(XB + o) = pack8(v0, v1); }
.LBB0_1674:
	s_nop 0
	v_add_co_u32_e32 v148, vcc, 0x20000, v182
	s_nop 1
	v_addc_co_u32_e32 v149, vcc, 0, v183, vcc
	s_and_b64 vcc, exec, s[38:39]
	s_waitcnt vmcnt(7)
	s_nop 1
	v_mov_b32_e32 v148, v242
	v_mov_b32_e32 v149, v243
	v_mov_b32_e32 v150, v244
	v_mov_b32_e32 v151, v245
	v_lshlrev_b32_e32 v152, 16, v148
	v_and_b32_e32 v153, 0xffff0000, v148
	v_lshlrev_b32_e32 v148, 16, v149
	v_and_b32_e32 v149, 0xffff0000, v149
	v_lshlrev_b32_e32 v168, 16, v150
	v_and_b32_e32 v169, 0xffff0000, v150
	v_lshlrev_b32_e32 v150, 16, v151
	v_and_b32_e32 v151, 0xffff0000, v151
	v_pk_fma_f32 v[154:155], v[84:85], v[138:139], v[148:149]
	v_pk_fma_f32 v[152:153], v[82:83], v[136:137], v[152:153]
	v_pk_fma_f32 v[150:151], v[76:77], v[134:135], v[150:151]
	v_pk_fma_f32 v[148:149], v[74:75], v[132:133], v[168:169]
	s_cbranch_vccnz .LBB0_1722
	v_add_co_u32_e32 v172, vcc, 0x40000, v184
	s_mov_b64 s[0:1], 0x40200
	s_nop 0
	v_addc_co_u32_e32 v173, vcc, 0, v185, vcc
	v_lshl_add_u64 v[168:169], v[184:185], 0, s[0:1]
	global_store_dwordx4 v[172:173], v[152:155], off offset:512
	global_store_dwordx4 v[168:169], v[148:151], off offset:16
	s_cbranch_execnz .LBB0_1677

; #define GAS __attribute__((address_space(1)))
; __device__ __forceinline__ u32x4 pack8(f32x4 v0, f32x4 v1) { u32x4 w; w.x = cvt_pk_bf16(v0[0], v0[1]); w.y = cvt_pk_bf16(v0[2], v0[3]); w.z = cvt_pk_bf16(v1[0], v1[1]); w.w = cvt_pk_bf16(v1[2], v1[3]); return w; }
; __device__ __forceinline__ void unpack8(u32x4 w, f32x4& v0, f32x4& v1) { v0 = (f32x4){bflo(w.x), bfhi(w.x), bflo(w.y), bfhi(w.y)}; v1 = (f32x4){bflo(w.z), bfhi(w.z), bflo(w.w), bfhi(w.w)}; }
; #define GAS __attribute__((address_space(1)))
;     __device__ __forceinline__ void operator()(const f32x4 (&acc)[2][2][4][2], const Unit& u, int wr, int wc, int fr, int fq) const {
;     ...
;             } else { const size_t o0 = (size_t)(rb + fr) * 2048 + col0;
; #pragma unroll
;                 for (int m = 0; m < 4; ++m)
; #pragma unroll
;                     for (int bj = 0; bj < 2; ++bj) { const size_t o = o0 + (size_t)(m * 16) * 2048 + bj * HALF; f32x4 x0, x1; unpack8(*(const GAS u32x4*)(XB + o), x0, x1);
;                         const f32x4 v0 = x0 + gv[bj][0] * acc[ai][bj][m][0], v1 = x1 + gv[bj][1] * acc[ai][bj][m][1];
;                         if (OUTF != nullptr) { *(GAS f32x4*)(OUTF + o) = v0; *(GAS f32x4*)(OUTF + o + 4) = v1; } else *(GAS u32x4*)(XB + o) = pack8(v0, v1); }
.LBB0_1677:
	s_nop 0
	v_add_co_u32_e32 v148, vcc, 0x30000, v182
	s_nop 1
	v_addc_co_u32_e32 v149, vcc, 0, v183, vcc
	s_and_b64 vcc, exec, s[38:39]
	s_waitcnt vmcnt(7)
	s_nop 1
	v_mov_b32_e32 v148, v190
	v_mov_b32_e32 v149, v191
	v_mov_b32_e32 v150, v192
	v_mov_b32_e32 v151, v193
	v_lshlrev_b32_e32 v152, 16, v148
	v_and_b32_e32 v153, 0xffff0000, v148
	v_lshlrev_b32_e32 v148, 16, v149
	v_and_b32_e32 v149, 0xffff0000, v149
	v_lshlrev_b32_e32 v168, 16, v150
	v_and_b32_e32 v169, 0xffff0000, v150
	v_lshlrev_b32_e32 v150, 16, v151
	v_and_b32_e32 v151, 0xffff0000, v151
	v_pk_fma_f32 v[154:155], v[88:89], v[146:147], v[148:149]
	v_pk_fma_f32 v[152:153], v[86:87], v[144:145], v[152:153]
	v_pk_fma_f32 v[150:151], v[80:81], v[142:143], v[150:151]
	v_pk_fma_f32 v[148:149], v[78:79], v[140:141], v[168:169]
	s_cbranch_vccnz .LBB0_1723
	v_add_co_u32_e32 v172, vcc, 0x60000, v184
	s_mov_b64 s[0:1], 0x60000
	s_nop 0
	v_addc_co_u32_e32 v173, vcc, 0, v185, vcc
	v_lshl_add_u64 v[168:169], v[184:185], 0, s[0:1]
	global_store_dwordx4 v[172:173], v[152:155], off
	global_store_dwordx4 v[168:169], v[148:151], off offset:16
	s_cbranch_execnz .LBB0_1680

; #define GAS __attribute__((address_space(1)))
; __device__ __forceinline__ u32x4 pack8(f32x4 v0, f32x4 v1) { u32x4 w; w.x = cvt_pk_bf16(v0[0], v0[1]); w.y = cvt_pk_bf16(v0[2], v0[3]); w.z = cvt_pk_bf16(v1[0], v1[1]); w.w = cvt_pk_bf16(v1[2], v1[3]); return w; }
; __device__ __forceinline__ void unpack8(u32x4 w, f32x4& v0, f32x4& v1) { v0 = (f32x4){bflo(w.x), bfhi(w.x), bflo(w.y), bfhi(w.y)}; v1 = (f32x4){bflo(w.z), bfhi(w.z), bflo(w.w), bfhi(w.w)}; }
; #define GAS __attribute__((address_space(1)))
;     __device__ __forceinline__ void operator()(const f32x4 (&acc)[2][2][4][2], const Unit& u, int wr, int wc, int fr, int fq) const {
;     ...
;             } else { const size_t o0 = (size_t)(rb + fr) * 2048 + col0;
; #pragma unroll
;                 for (int m = 0; m < 4; ++m)
; #pragma unroll
;                     for (int bj = 0; bj < 2; ++bj) { const size_t o = o0 + (size_t)(m * 16) * 2048 + bj * HALF; f32x4 x0, x1; unpack8(*(const GAS u32x4*)(XB + o), x0, x1);
;                         const f32x4 v0 = x0 + gv[bj][0] * acc[ai][bj][m][0], v1 = x1 + gv[bj][1] * acc[ai][bj][m][1];
;                         if (OUTF != nullptr) { *(GAS f32x4*)(OUTF + o) = v0; *(GAS f32x4*)(OUTF + o + 4) = v1; } else *(GAS u32x4*)(XB + o) = pack8(v0, v1); }
.LBB0_1680:
	s_nop 0
	v_add_co_u32_e32 v148, vcc, 0x30000, v182
	s_nop 1
	v_addc_co_u32_e32 v149, vcc, 0, v183, vcc
	s_and_b64 vcc, exec, s[38:39]
	s_waitcnt vmcnt(7)
	s_nop 1
	v_mov_b32_e32 v148, v194
	v_mov_b32_e32 v149, v195
	v_mov_b32_e32 v150, v196
	v_mov_b32_e32 v151, v197
	v_lshlrev_b32_e32 v152, 16, v148
	v_and_b32_e32 v153, 0xffff0000, v148
	v_lshlrev_b32_e32 v148, 16, v149
	v_and_b32_e32 v149, 0xffff0000, v149
	v_lshlrev_b32_e32 v168, 16, v150
	v_and_b32_e32 v169, 0xffff0000, v150
	v_lshlrev_b32_e32 v150, 16, v151
	v_and_b32_e32 v151, 0xffff0000, v151
	v_pk_fma_f32 v[154:155], v[72:73], v[138:139], v[148:149]
	v_pk_fma_f32 v[152:153], v[70:71], v[136:137], v[152:153]
	v_pk_fma_f32 v[150:151], v[68:69], v[134:135], v[150:151]
	v_pk_fma_f32 v[148:149], v[66:67], v[132:133], v[168:169]
	s_cbranch_vccnz .LBB0_1724
	v_add_co_u32_e32 v172, vcc, 0x60000, v184
	s_mov_b64 s[0:1], 0x60200
	s_nop 0
	v_addc_co_u32_e32 v173, vcc, 0, v185, vcc
	v_lshl_add_u64 v[168:169], v[184:185], 0, s[0:1]
	global_store_dwordx4 v[172:173], v[152:155], off offset:512
	global_store_dwordx4 v[168:169], v[148:151], off offset:16
	s_cbranch_execnz .LBB0_1683

; #define GAS __attribute__((address_space(1)))
; __device__ __forceinline__ u32x4 pack8(f32x4 v0, f32x4 v1) { u32x4 w; w.x = cvt_pk_bf16(v0[0], v0[1]); w.y = cvt_pk_bf16(v0[2], v0[3]); w.z = cvt_pk_bf16(v1[0], v1[1]); w.w = cvt_pk_bf16(v1[2], v1[3]); return w; }
; __device__ __forceinline__ void unpack8(u32x4 w, f32x4& v0, f32x4& v1) { v0 = (f32x4){bflo(w.x), bfhi(w.x), bflo(w.y), bfhi(w.y)}; v1 = (f32x4){bflo(w.z), bfhi(w.z), bflo(w.w), bfhi(w.w)}; }
; #define GAS __attribute__((address_space(1)))
;     __device__ __forceinline__ void operator()(const f32x4 (&acc)[2][2][4][2], const Unit& u, int wr, int wc, int fr, int fq) const {
;     ...
;             } else { const size_t o0 = (size_t)(rb + fr) * 2048 + col0;
; #pragma unroll
;                 for (int m = 0; m < 4; ++m)
; #pragma unroll
;                     for (int bj = 0; bj < 2; ++bj) { const size_t o = o0 + (size_t)(m * 16) * 2048 + bj * HALF; f32x4 x0, x1; unpack8(*(const GAS u32x4*)(XB + o), x0, x1);
;                         const f32x4 v0 = x0 + gv[bj][0] * acc[ai][bj][m][0], v1 = x1 + gv[bj][1] * acc[ai][bj][m][1];
;                         if (OUTF != nullptr) { *(GAS f32x4*)(OUTF + o) = v0; *(GAS f32x4*)(OUTF + o + 4) = v1; } else *(GAS u32x4*)(XB + o) = pack8(v0, v1); }
.LBB0_1689:
	v_or_b32_e32 v82, s0, v1
	v_ashrrev_i32_e32 v83, 31, v82
	v_lshlrev_b64 v[82:83], 11, v[82:83]
	v_lshl_add_u64 v[94:95], v[82:83], 0, v[180:181]
	v_lshl_add_u64 v[90:91], v[94:95], 1, s[10:11]
	global_load_dwordx4 v[222:225], v[90:91], off
	global_load_dwordx4 v[226:229], v[90:91], off offset:256
	v_add_co_u32_e32 v198, vcc, 0x10000, v90
	s_nop 1
	v_addc_co_u32_e32 v199, vcc, 0, v91, vcc
	global_load_dwordx4 v[230:233], v[198:199], off
	global_load_dwordx4 v[234:237], v[198:199], off offset:256
	v_add_co_u32_e32 v198, vcc, 0x20000, v90
	s_nop 1
	v_addc_co_u32_e32 v199, vcc, 0, v91, vcc
	global_load_dwordx4 v[238:241], v[198:199], off
	global_load_dwordx4 v[242:245], v[198:199], off offset:256
	v_add_co_u32_e32 v198, vcc, 0x30000, v90
	s_nop 1
	v_addc_co_u32_e32 v199, vcc, 0, v91, vcc
	global_load_dwordx4 v[190:193], v[198:199], off
	global_load_dwordx4 v[194:197], v[198:199], off offset:256
	s_and_b64 vcc, exec, s[38:39]
	s_waitcnt vmcnt(7)
	s_nop 1
	v_mov_b32_e32 v82, v222
	v_mov_b32_e32 v83, v223
	v_mov_b32_e32 v84, v224
	v_mov_b32_e32 v85, v225
	v_lshlrev_b32_e32 v86, 16, v82
	v_and_b32_e32 v87, 0xffff0000, v82
	v_lshlrev_b32_e32 v82, 16, v83
	v_and_b32_e32 v83, 0xffff0000, v83
	v_lshlrev_b32_e32 v92, 16, v84
	v_and_b32_e32 v93, 0xffff0000, v84
	v_lshlrev_b32_e32 v84, 16, v85
	v_and_b32_e32 v85, 0xffff0000, v85
	v_pk_fma_f32 v[88:89], v[64:65], v[80:81], v[82:83]
	v_pk_fma_f32 v[86:87], v[62:63], v[78:79], v[86:87]
	v_pk_fma_f32 v[84:85], v[60:61], v[76:77], v[84:85]
	v_pk_fma_f32 v[82:83], v[58:59], v[74:75], v[92:93]
	v_lshl_add_u64 v[92:93], v[94:95], 2, s[6:7]
	s_cbranch_vccnz .LBB0_1691
	s_mov_b64 s[34:35], 0
	global_store_dwordx4 v[92:93], v[86:89], off
	global_store_dwordx4 v[92:93], v[82:85], off offset:16

; #define GAS __attribute__((address_space(1)))
; __device__ __forceinline__ u32x4 pack8(f32x4 v0, f32x4 v1) { u32x4 w; w.x = cvt_pk_bf16(v0[0], v0[1]); w.y = cvt_pk_bf16(v0[2], v0[3]); w.z = cvt_pk_bf16(v1[0], v1[1]); w.w = cvt_pk_bf16(v1[2], v1[3]); return w; }
; __device__ __forceinline__ void unpack8(u32x4 w, f32x4& v0, f32x4& v1) { v0 = (f32x4){bflo(w.x), bfhi(w.x), bflo(w.y), bfhi(w.y)}; v1 = (f32x4){bflo(w.z), bfhi(w.z), bflo(w.w), bfhi(w.w)}; }
; #define GAS __attribute__((address_space(1)))
;     __device__ __forceinline__ void operator()(const f32x4 (&acc)[2][2][4][2], const Unit& u, int wr, int wc, int fr, int fq) const {
;     ...
;             } else { const size_t o0 = (size_t)(rb + fr) * 2048 + col0;
; #pragma unroll
;                 for (int m = 0; m < 4; ++m)
; #pragma unroll
;                     for (int bj = 0; bj < 2; ++bj) { const size_t o = o0 + (size_t)(m * 16) * 2048 + bj * HALF; f32x4 x0, x1; unpack8(*(const GAS u32x4*)(XB + o), x0, x1);
;                         const f32x4 v0 = x0 + gv[bj][0] * acc[ai][bj][m][0], v1 = x1 + gv[bj][1] * acc[ai][bj][m][1];
;                         if (OUTF != nullptr) { *(GAS f32x4*)(OUTF + o) = v0; *(GAS f32x4*)(OUTF + o + 4) = v1; } else *(GAS u32x4*)(XB + o) = pack8(v0, v1); }
.LBB0_1693:
	v_lshlrev_b64 v[82:83], 1, v[94:95]
	v_or_b32_e32 v82, 0x100, v82
	v_lshl_add_u64 v[94:95], s[10:11], 0, v[82:83]
	s_and_b64 vcc, exec, s[38:39]
	s_waitcnt vmcnt(7)
	s_nop 1
	v_mov_b32_e32 v82, v226
	v_mov_b32_e32 v83, v227
	v_mov_b32_e32 v84, v228
	v_mov_b32_e32 v85, v229
	v_lshlrev_b32_e32 v86, 16, v82
	v_and_b32_e32 v87, 0xffff0000, v82
	v_lshlrev_b32_e32 v82, 16, v83
	v_and_b32_e32 v83, 0xffff0000, v83
	v_lshlrev_b32_e32 v96, 16, v84
	v_and_b32_e32 v97, 0xffff0000, v84
	v_lshlrev_b32_e32 v84, 16, v85
	v_and_b32_e32 v85, 0xffff0000, v85
	v_pk_fma_f32 v[88:89], v[52:53], v[72:73], v[82:83]
	v_pk_fma_f32 v[86:87], v[50:51], v[70:71], v[86:87]
	v_pk_fma_f32 v[84:85], v[44:45], v[68:69], v[84:85]
	v_pk_fma_f32 v[82:83], v[42:43], v[66:67], v[96:97]
	s_cbranch_vccnz .LBB0_1725
	global_store_dwordx4 v[92:93], v[86:89], off offset:512
	global_store_dwordx4 v[92:93], v[82:85], off offset:528
	s_cbranch_execnz .LBB0_1696

; #define GAS __attribute__((address_space(1)))
; __device__ __forceinline__ u32x4 pack8(f32x4 v0, f32x4 v1) { u32x4 w; w.x = cvt_pk_bf16(v0[0], v0[1]); w.y = cvt_pk_bf16(v0[2], v0[3]); w.z = cvt_pk_bf16(v1[0], v1[1]); w.w = cvt_pk_bf16(v1[2], v1[3]); return w; }
; __device__ __forceinline__ void unpack8(u32x4 w, f32x4& v0, f32x4& v1) { v0 = (f32x4){bflo(w.x), bfhi(w.x), bflo(w.y), bfhi(w.y)}; v1 = (f32x4){bflo(w.z), bfhi(w.z), bflo(w.w), bfhi(w.w)}; }
; #define GAS __attribute__((address_space(1)))
;     __device__ __forceinline__ void operator()(const f32x4 (&acc)[2][2][4][2], const Unit& u, int wr, int wc, int fr, int fq) const {
;     ...
;             } else { const size_t o0 = (size_t)(rb + fr) * 2048 + col0;
; #pragma unroll
;                 for (int m = 0; m < 4; ++m)
; #pragma unroll
;                     for (int bj = 0; bj < 2; ++bj) { const size_t o = o0 + (size_t)(m * 16) * 2048 + bj * HALF; f32x4 x0, x1; unpack8(*(const GAS u32x4*)(XB + o), x0, x1);
;                         const f32x4 v0 = x0 + gv[bj][0] * acc[ai][bj][m][0], v1 = x1 + gv[bj][1] * acc[ai][bj][m][1];
;                         if (OUTF != nullptr) { *(GAS f32x4*)(OUTF + o) = v0; *(GAS f32x4*)(OUTF + o + 4) = v1; } else *(GAS u32x4*)(XB + o) = pack8(v0, v1); }
.LBB0_1696:
	s_nop 0
	v_add_co_u32_e32 v82, vcc, 0x10000, v90
	s_nop 1
	v_addc_co_u32_e32 v83, vcc, 0, v91, vcc
	s_and_b64 vcc, exec, s[38:39]
	s_waitcnt vmcnt(7)
	s_nop 1
	v_mov_b32_e32 v82, v230
	v_mov_b32_e32 v83, v231
	v_mov_b32_e32 v84, v232
	v_mov_b32_e32 v85, v233
	v_lshlrev_b32_e32 v86, 16, v82
	v_and_b32_e32 v87, 0xffff0000, v82
	v_lshlrev_b32_e32 v82, 16, v83
	v_and_b32_e32 v83, 0xffff0000, v83
	v_lshlrev_b32_e32 v94, 16, v84
	v_and_b32_e32 v95, 0xffff0000, v84
	v_lshlrev_b32_e32 v84, 16, v85
	v_and_b32_e32 v85, 0xffff0000, v85
	v_pk_fma_f32 v[88:89], v[56:57], v[80:81], v[82:83]
	v_pk_fma_f32 v[86:87], v[54:55], v[78:79], v[86:87]
	v_pk_fma_f32 v[84:85], v[48:49], v[76:77], v[84:85]
	v_pk_fma_f32 v[82:83], v[46:47], v[74:75], v[94:95]
	s_cbranch_vccnz .LBB0_1726
	v_add_co_u32_e32 v96, vcc, 0x20000, v92
	s_mov_b64 s[0:1], 0x20000
	s_nop 0
	v_addc_co_u32_e32 v97, vcc, 0, v93, vcc
	v_lshl_add_u64 v[94:95], v[92:93], 0, s[0:1]
	global_store_dwordx4 v[96:97], v[86:89], off
	global_store_dwordx4 v[94:95], v[82:85], off offset:16
	s_cbranch_execnz .LBB0_1699

; #define GAS __attribute__((address_space(1)))
; __device__ __forceinline__ u32x4 pack8(f32x4 v0, f32x4 v1) { u32x4 w; w.x = cvt_pk_bf16(v0[0], v0[1]); w.y = cvt_pk_bf16(v0[2], v0[3]); w.z = cvt_pk_bf16(v1[0], v1[1]); w.w = cvt_pk_bf16(v1[2], v1[3]); return w; }
; __device__ __forceinline__ void unpack8(u32x4 w, f32x4& v0, f32x4& v1) { v0 = (f32x4){bflo(w.x), bfhi(w.x), bflo(w.y), bfhi(w.y)}; v1 = (f32x4){bflo(w.z), bfhi(w.z), bflo(w.w), bfhi(w.w)}; }
; #define GAS __attribute__((address_space(1)))
;     __device__ __forceinline__ void operator()(const f32x4 (&acc)[2][2][4][2], const Unit& u, int wr, int wc, int fr, int fq) const {
;     ...
;             } else { const size_t o0 = (size_t)(rb + fr) * 2048 + col0;
; #pragma unroll
;                 for (int m = 0; m < 4; ++m)
; #pragma unroll
;                     for (int bj = 0; bj < 2; ++bj) { const size_t o = o0 + (size_t)(m * 16) * 2048 + bj * HALF; f32x4 x0, x1; unpack8(*(const GAS u32x4*)(XB + o), x0, x1);
;                         const f32x4 v0 = x0 + gv[bj][0] * acc[ai][bj][m][0], v1 = x1 + gv[bj][1] * acc[ai][bj][m][1];
;                         if (OUTF != nullptr) { *(GAS f32x4*)(OUTF + o) = v0; *(GAS f32x4*)(OUTF + o + 4) = v1; } else *(GAS u32x4*)(XB + o) = pack8(v0, v1); }
.LBB0_1699:
	s_nop 0
	v_add_co_u32_e32 v82, vcc, 0x10000, v90
	s_nop 1
	v_addc_co_u32_e32 v83, vcc, 0, v91, vcc
	s_and_b64 vcc, exec, s[38:39]
	s_waitcnt vmcnt(7)
	s_nop 1
	v_mov_b32_e32 v82, v234
	v_mov_b32_e32 v83, v235
	v_mov_b32_e32 v84, v236
	v_mov_b32_e32 v85, v237
	v_lshlrev_b32_e32 v86, 16, v82
	v_and_b32_e32 v87, 0xffff0000, v82
	v_lshlrev_b32_e32 v82, 16, v83
	v_and_b32_e32 v83, 0xffff0000, v83
	v_lshlrev_b32_e32 v94, 16, v84
	v_and_b32_e32 v95, 0xffff0000, v84
	v_lshlrev_b32_e32 v84, 16, v85
	v_and_b32_e32 v85, 0xffff0000, v85
	v_pk_fma_f32 v[88:89], v[36:37], v[72:73], v[82:83]
	v_pk_fma_f32 v[86:87], v[34:35], v[70:71], v[86:87]
	v_pk_fma_f32 v[84:85], v[28:29], v[68:69], v[84:85]
	v_pk_fma_f32 v[82:83], v[26:27], v[66:67], v[94:95]
	s_cbranch_vccnz .LBB0_1727
	v_add_co_u32_e32 v96, vcc, 0x20000, v92
	s_mov_b64 s[0:1], 0x20200
	s_nop 0
	v_addc_co_u32_e32 v97, vcc, 0, v93, vcc
	v_lshl_add_u64 v[94:95], v[92:93], 0, s[0:1]
	global_store_dwordx4 v[96:97], v[86:89], off offset:512
	global_store_dwordx4 v[94:95], v[82:85], off offset:16
	s_cbranch_execnz .LBB0_1702

; #define GAS __attribute__((address_space(1)))
; __device__ __forceinline__ u32x4 pack8(f32x4 v0, f32x4 v1) { u32x4 w; w.x = cvt_pk_bf16(v0[0], v0[1]); w.y = cvt_pk_bf16(v0[2], v0[3]); w.z = cvt_pk_bf16(v1[0], v1[1]); w.w = cvt_pk_bf16(v1[2], v1[3]); return w; }
; __device__ __forceinline__ void unpack8(u32x4 w, f32x4& v0, f32x4& v1) { v0 = (f32x4){bflo(w.x), bfhi(w.x), bflo(w.y), bfhi(w.y)}; v1 = (f32x4){bflo(w.z), bfhi(w.z), bflo(w.w), bfhi(w.w)}; }
; #define GAS __attribute__((address_space(1)))
;     __device__ __forceinline__ void operator()(const f32x4 (&acc)[2][2][4][2], const Unit& u, int wr, int wc, int fr, int fq) const {
;     ...
;             } else { const size_t o0 = (size_t)(rb + fr) * 2048 + col0;
; #pragma unroll
;                 for (int m = 0; m < 4; ++m)
; #pragma unroll
;                     for (int bj = 0; bj < 2; ++bj) { const size_t o = o0 + (size_t)(m * 16) * 2048 + bj * HALF; f32x4 x0, x1; unpack8(*(const GAS u32x4*)(XB + o), x0, x1);
;                         const f32x4 v0 = x0 + gv[bj][0] * acc[ai][bj][m][0], v1 = x1 + gv[bj][1] * acc[ai][bj][m][1];
;                         if (OUTF != nullptr) { *(GAS f32x4*)(OUTF + o) = v0; *(GAS f32x4*)(OUTF + o + 4) = v1; } else *(GAS u32x4*)(XB + o) = pack8(v0, v1); }
.LBB0_1702:
	s_nop 0
	v_add_co_u32_e32 v82, vcc, 0x20000, v90
	s_nop 1
	v_addc_co_u32_e32 v83, vcc, 0, v91, vcc
	s_and_b64 vcc, exec, s[38:39]
	s_waitcnt vmcnt(7)
	s_nop 1
	v_mov_b32_e32 v82, v238
	v_mov_b32_e32 v83, v239
	v_mov_b32_e32 v84, v240
	v_mov_b32_e32 v85, v241
	v_lshlrev_b32_e32 v86, 16, v82
	v_and_b32_e32 v87, 0xffff0000, v82
	v_lshlrev_b32_e32 v82, 16, v83
	v_and_b32_e32 v83, 0xffff0000, v83
	v_lshlrev_b32_e32 v94, 16, v84
	v_and_b32_e32 v95, 0xffff0000, v84
	v_lshlrev_b32_e32 v84, 16, v85
	v_and_b32_e32 v85, 0xffff0000, v85
	v_pk_fma_f32 v[88:89], v[40:41], v[80:81], v[82:83]
	v_pk_fma_f32 v[86:87], v[38:39], v[78:79], v[86:87]
	v_pk_fma_f32 v[84:85], v[32:33], v[76:77], v[84:85]
	v_pk_fma_f32 v[82:83], v[30:31], v[74:75], v[94:95]
	s_cbranch_vccnz .LBB0_1728
	v_add_co_u32_e32 v96, vcc, 0x40000, v92
	s_nop 1
	v_addc_co_u32_e32 v97, vcc, 0, v93, vcc
	v_lshl_add_u64 v[94:95], v[92:93], 0, s[64:65]
	global_store_dwordx4 v[96:97], v[86:89], off
	global_store_dwordx4 v[94:95], v[82:85], off offset:16
	s_cbranch_execnz .LBB0_1705

; #define GAS __attribute__((address_space(1)))
; __device__ __forceinline__ u32x4 pack8(f32x4 v0, f32x4 v1) { u32x4 w; w.x = cvt_pk_bf16(v0[0], v0[1]); w.y = cvt_pk_bf16(v0[2], v0[3]); w.z = cvt_pk_bf16(v1[0], v1[1]); w.w = cvt_pk_bf16(v1[2], v1[3]); return w; }
; __device__ __forceinline__ void unpack8(u32x4 w, f32x4& v0, f32x4& v1) { v0 = (f32x4){bflo(w.x), bfhi(w.x), bflo(w.y), bfhi(w.y)}; v1 = (f32x4){bflo(w.z), bfhi(w.z), bflo(w.w), bfhi(w.w)}; }
; #define GAS __attribute__((address_space(1)))
;     __device__ __forceinline__ void operator()(const f32x4 (&acc)[2][2][4][2], const Unit& u, int wr, int wc, int fr, int fq) const {
;     ...
;             } else { const size_t o0 = (size_t)(rb + fr) * 2048 + col0;
; #pragma unroll
;                 for (int m = 0; m < 4; ++m)
; #pragma unroll
;                     for (int bj = 0; bj < 2; ++bj) { const size_t o = o0 + (size_t)(m * 16) * 2048 + bj * HALF; f32x4 x0, x1; unpack8(*(const GAS u32x4*)(XB + o), x0, x1);
;                         const f32x4 v0 = x0 + gv[bj][0] * acc[ai][bj][m][0], v1 = x1 + gv[bj][1] * acc[ai][bj][m][1];
;                         if (OUTF != nullptr) { *(GAS f32x4*)(OUTF + o) = v0; *(GAS f32x4*)(OUTF + o + 4) = v1; } else *(GAS u32x4*)(XB + o) = pack8(v0, v1); }
.LBB0_1705:
	s_nop 0
	v_add_co_u32_e32 v82, vcc, 0x20000, v90
	s_nop 1
	v_addc_co_u32_e32 v83, vcc, 0, v91, vcc
	s_and_b64 vcc, exec, s[38:39]
	s_waitcnt vmcnt(7)
	s_nop 1
	v_mov_b32_e32 v82, v242
	v_mov_b32_e32 v83, v243
	v_mov_b32_e32 v84, v244
	v_mov_b32_e32 v85, v245
	v_lshlrev_b32_e32 v86, 16, v82
	v_and_b32_e32 v87, 0xffff0000, v82
	v_lshlrev_b32_e32 v82, 16, v83
	v_and_b32_e32 v83, 0xffff0000, v83
	v_lshlrev_b32_e32 v94, 16, v84
	v_and_b32_e32 v95, 0xffff0000, v84
	v_lshlrev_b32_e32 v84, 16, v85
	v_and_b32_e32 v85, 0xffff0000, v85
	v_pk_fma_f32 v[88:89], v[20:21], v[72:73], v[82:83]
	v_pk_fma_f32 v[86:87], v[18:19], v[70:71], v[86:87]
	v_pk_fma_f32 v[84:85], v[12:13], v[68:69], v[84:85]
	v_pk_fma_f32 v[82:83], v[10:11], v[66:67], v[94:95]
	s_cbranch_vccnz .LBB0_1729
	v_add_co_u32_e32 v96, vcc, 0x40000, v92
	s_mov_b64 s[0:1], 0x40200
	s_nop 0
	v_addc_co_u32_e32 v97, vcc, 0, v93, vcc
	v_lshl_add_u64 v[94:95], v[92:93], 0, s[0:1]
	global_store_dwordx4 v[96:97], v[86:89], off offset:512
	global_store_dwordx4 v[94:95], v[82:85], off offset:16
	s_cbranch_execnz .LBB0_1708

; #define GAS __attribute__((address_space(1)))
; __device__ __forceinline__ u32x4 pack8(f32x4 v0, f32x4 v1) { u32x4 w; w.x = cvt_pk_bf16(v0[0], v0[1]); w.y = cvt_pk_bf16(v0[2], v0[3]); w.z = cvt_pk_bf16(v1[0], v1[1]); w.w = cvt_pk_bf16(v1[2], v1[3]); return w; }
; __device__ __forceinline__ void unpack8(u32x4 w, f32x4& v0, f32x4& v1) { v0 = (f32x4){bflo(w.x), bfhi(w.x), bflo(w.y), bfhi(w.y)}; v1 = (f32x4){bflo(w.z), bfhi(w.z), bflo(w.w), bfhi(w.w)}; }
; #define GAS __attribute__((address_space(1)))
;     __device__ __forceinline__ void operator()(const f32x4 (&acc)[2][2][4][2], const Unit& u, int wr, int wc, int fr, int fq) const {
;     ...
;             } else { const size_t o0 = (size_t)(rb + fr) * 2048 + col0;
; #pragma unroll
;                 for (int m = 0; m < 4; ++m)
; #pragma unroll
;                     for (int bj = 0; bj < 2; ++bj) { const size_t o = o0 + (size_t)(m * 16) * 2048 + bj * HALF; f32x4 x0, x1; unpack8(*(const GAS u32x4*)(XB + o), x0, x1);
;                         const f32x4 v0 = x0 + gv[bj][0] * acc[ai][bj][m][0], v1 = x1 + gv[bj][1] * acc[ai][bj][m][1];
;                         if (OUTF != nullptr) { *(GAS f32x4*)(OUTF + o) = v0; *(GAS f32x4*)(OUTF + o + 4) = v1; } else *(GAS u32x4*)(XB + o) = pack8(v0, v1); }
.LBB0_1708:
	s_nop 0
	v_add_co_u32_e32 v82, vcc, 0x30000, v90
	s_nop 1
	v_addc_co_u32_e32 v83, vcc, 0, v91, vcc
	s_and_b64 vcc, exec, s[38:39]
	s_waitcnt vmcnt(7)
	s_nop 1
	v_mov_b32_e32 v82, v190
	v_mov_b32_e32 v83, v191
	v_mov_b32_e32 v84, v192
	v_mov_b32_e32 v85, v193
	v_lshlrev_b32_e32 v86, 16, v82
	v_and_b32_e32 v87, 0xffff0000, v82
	v_lshlrev_b32_e32 v82, 16, v83
	v_and_b32_e32 v83, 0xffff0000, v83
	v_lshlrev_b32_e32 v94, 16, v84
	v_and_b32_e32 v95, 0xffff0000, v84
	v_lshlrev_b32_e32 v84, 16, v85
	v_and_b32_e32 v85, 0xffff0000, v85
	v_pk_fma_f32 v[88:89], v[24:25], v[80:81], v[82:83]
	v_pk_fma_f32 v[86:87], v[22:23], v[78:79], v[86:87]
	v_pk_fma_f32 v[84:85], v[16:17], v[76:77], v[84:85]
	v_pk_fma_f32 v[82:83], v[14:15], v[74:75], v[94:95]
	s_cbranch_vccnz .LBB0_1730
	v_add_co_u32_e32 v96, vcc, 0x60000, v92
	s_mov_b64 s[0:1], 0x60000
	s_nop 0
	v_addc_co_u32_e32 v97, vcc, 0, v93, vcc
	v_lshl_add_u64 v[94:95], v[92:93], 0, s[0:1]
	global_store_dwordx4 v[96:97], v[86:89], off
	global_store_dwordx4 v[94:95], v[82:85], off offset:16
	s_cbranch_execnz .LBB0_1711

; #define GAS __attribute__((address_space(1)))
; __device__ __forceinline__ u32x4 pack8(f32x4 v0, f32x4 v1) { u32x4 w; w.x = cvt_pk_bf16(v0[0], v0[1]); w.y = cvt_pk_bf16(v0[2], v0[3]); w.z = cvt_pk_bf16(v1[0], v1[1]); w.w = cvt_pk_bf16(v1[2], v1[3]); return w; }
; __device__ __forceinline__ void unpack8(u32x4 w, f32x4& v0, f32x4& v1) { v0 = (f32x4){bflo(w.x), bfhi(w.x), bflo(w.y), bfhi(w.y)}; v1 = (f32x4){bflo(w.z), bfhi(w.z), bflo(w.w), bfhi(w.w)}; }
; #define GAS __attribute__((address_space(1)))
;     __device__ __forceinline__ void operator()(const f32x4 (&acc)[2][2][4][2], const Unit& u, int wr, int wc, int fr, int fq) const {
;     ...
;             } else { const size_t o0 = (size_t)(rb + fr) * 2048 + col0;
; #pragma unroll
;                 for (int m = 0; m < 4; ++m)
; #pragma unroll
;                     for (int bj = 0; bj < 2; ++bj) { const size_t o = o0 + (size_t)(m * 16) * 2048 + bj * HALF; f32x4 x0, x1; unpack8(*(const GAS u32x4*)(XB + o), x0, x1);
;                         const f32x4 v0 = x0 + gv[bj][0] * acc[ai][bj][m][0], v1 = x1 + gv[bj][1] * acc[ai][bj][m][1];
;                         if (OUTF != nullptr) { *(GAS f32x4*)(OUTF + o) = v0; *(GAS f32x4*)(OUTF + o + 4) = v1; } else *(GAS u32x4*)(XB + o) = pack8(v0, v1); }
.LBB0_1711:
	s_nop 0
	v_add_co_u32_e32 v82, vcc, 0x30000, v90
	s_nop 1
	v_addc_co_u32_e32 v83, vcc, 0, v91, vcc
	s_and_b64 vcc, exec, s[38:39]
	s_waitcnt vmcnt(7)
	s_nop 1
	v_mov_b32_e32 v82, v194
	v_mov_b32_e32 v83, v195
	v_mov_b32_e32 v84, v196
	v_mov_b32_e32 v85, v197
	v_lshlrev_b32_e32 v86, 16, v82
	v_and_b32_e32 v87, 0xffff0000, v82
	v_lshlrev_b32_e32 v82, 16, v83
	v_and_b32_e32 v83, 0xffff0000, v83
	v_lshlrev_b32_e32 v94, 16, v84
	v_and_b32_e32 v95, 0xffff0000, v84
	v_lshlrev_b32_e32 v84, 16, v85
	v_and_b32_e32 v85, 0xffff0000, v85
	v_pk_fma_f32 v[88:89], v[8:9], v[72:73], v[82:83]
	v_pk_fma_f32 v[86:87], v[6:7], v[70:71], v[86:87]
	v_pk_fma_f32 v[84:85], v[4:5], v[68:69], v[84:85]
	v_pk_fma_f32 v[82:83], v[2:3], v[66:67], v[94:95]
	s_cbranch_vccnz .LBB0_1731
	s_mov_b64 s[0:1], 0x60200
	v_lshl_add_u64 v[94:95], v[92:93], 0, s[0:1]
	v_add_co_u32_e32 v92, vcc, 0x60000, v92
	s_nop 1
	v_addc_co_u32_e32 v93, vcc, 0, v93, vcc
	global_store_dwordx4 v[92:93], v[86:89], off offset:512
	global_store_dwordx4 v[94:95], v[82:85], off offset:16
	s_cbranch_execnz .LBB0_1714
